# LDS-DMA pieces with scalar base + 32-bit lane offset (80 of 176), dropping their v_lshl_add_u64; on top of static wave priority
# speedup vs baseline: 1.0097x; 1.0097x over previous
; #define PG8_STAGE(bufoff, gbase, voff) do { _Pragma("unroll") for (int _i = 0; _i < 2; ++_i) \
;         __builtin_amdgcn_global_load_lds((const unsigned*)((const char*)(gbase) + (voff)[_i]), (PG8_LAS unsigned*)(lds + (bufoff) + ldsw + _i * 8192), 16, 0, 0); } while (0)
; #define PG8_WAIT_V(n) asm volatile("s_waitcnt vmcnt(" #n ")" ::: "memory")
; #define PG8_BAR __builtin_amdgcn_s_barrier()
; template <class Epi, class Sched, bool ALIGN_EPI = false, bool SP2 = false>
; __device__ __forceinline__ void gemm_phase(PG8_LAS unsigned char* lds, const Gemm g, const Sched& S, const Epi& E) {
;     ...
;     for (int i = 0; i < 2; ++i) { int R, C; stage_rc(tid * 16 + i * 8192, R, C); const int Rb = Epi::PERM ? ((R & ~31) + perm32(R & 31)) : R;
;         voffA[i] = (unsigned)(R * K + C) * 2u; voffB[i] = (unsigned)(Rb * K + C) * 2u; }
;     const size_t kstep = (size_t)(BK * 2);
;     const size_t hstep = (size_t)HALF * K * 2;
;     const size_t tstep = 2 * hstep;
;     const unsigned ldsw = (unsigned)wid * 1024u;
;     const int aoff = lds_byte(wr * 64 + fr, fq * 8), boff = lds_byte(wc * 32 + fr, fq * 8);
;     ...
;         PG8_STAGE(PG8_SB(1, 0), cB + kstep, voffB); PG8_STAGE(PG8_SA(1, 0), cA + kstep, voffA); PG8_STAGE(PG8_SB(1, 1), cB + hstep + kstep, voffB);
;         PG8_WAIT_V(6); PG8_BAR;
.LBB0_283:
	s_lshl_b32 s2, s2, 5
	s_and_b32 s14, s2, 0x60
	s_mov_b64 s[2:3], 0x80
	s_add_i32 m0, s21, 0x18000
	v_lshl_add_u64 v[6:7], v[6:7], 0, s[2:3]
	s_lshl_b32 s7, s6, 13
	s_lshl_b32 s15, s14, 7
	s_waitcnt vmcnt(2)
	s_barrier
	global_load_lds_dwordx4 v[6:7], off
	v_lshl_add_u64 v[4:5], v[4:5], 0, s[2:3]
	s_add_i32 m0, s21, 0x1a000
	s_add_i32 s36, s21, 0x8000
	s_add_i32 s37, s21, 0xa000
	global_load_lds_dwordx4 v[4:5], off
	v_lshl_add_u64 v[0:1], v[0:1], 0, s[2:3]
	s_mov_b32 m0, s36
	s_add_u32 s12, s24, 0x80080
	global_load_lds_dwordx4 v[0:1], off
	v_lshl_add_u64 v[0:1], v[2:3], 0, s[2:3]
	s_mov_b32 m0, s37
	s_addc_u32 s13, s25, 0
	global_load_lds_dwordx4 v[0:1], off
	s_add_i32 m0, s21, 0x1c000
	s_nop 0
	global_load_lds_dwordx4 v134, s[12:13]
	s_add_i32 m0, s21, 0x1e000
	s_cmpk_lt_u32 s5, 0x100
	global_load_lds_dwordx4 v130, s[12:13]
	v_and_b32_e32 v0, 15, v10
	v_lshrrev_b32_e32 v1, 1, v10
	s_sext_i32_i16 s45, s4
	v_lshl_or_b32 v152, s6, 6, v0
	v_and_b32_e32 v1, 24, v1
	s_cselect_b64 s[4:5], -1, 0
	s_lshl_b32 s6, s6, 8
	v_lshlrev_b32_e32 v2, 1, v1
	s_add_i32 s6, s6, 0
	v_lshl_or_b32 v2, v0, 6, v2
	v_lshlrev_b32_e32 v0, 2, v0
	s_add_i32 s6, s6, 0x20000
	v_and_b32_e32 v3, 32, v0
	v_add_u32_e32 v154, s6, v0
	v_lshlrev_b32_e32 v0, 15, v13
	v_and_b32_e32 v0, 0xffff0000, v0
	v_or_b32_e32 v155, s14, v1
	v_lshl_add_u32 v0, v12, 12, v0
	v_and_b32_e32 v1, 1, v13
	v_lshl_or_b32 v0, v1, 6, v0
	v_lshl_add_u32 v138, v14, 1, v0
	v_lshlrev_b32_e32 v0, 15, v8
	v_and_b32_e32 v0, 0xffff0000, v0
	s_waitcnt vmcnt(6)
	v_lshl_add_u32 v0, v9, 12, v0
	v_and_b32_e32 v1, 1, v8
	v_bitop3_b32 v4, v2, s7, v3 bitop3:0xde
	v_bitop3_b32 v153, v2, s15, v3 bitop3:0xde
	v_lshl_or_b32 v0, v1, 6, v0
	s_add_i32 s40, 0, 0x10000
	s_add_i32 s41, 0, 0x14000
	v_mov_b32_e32 v139, v135
	v_lshl_add_u32 v140, v11, 1, v0
	v_mov_b32_e32 v141, v135
	v_mov_b64_e32 v[142:143], 0x300
	v_mov_b64_e32 v[144:145], 0x2ff
	v_add_u32_e32 v156, s40, v153
	v_add_u32_e32 v157, s41, v153
	v_add_u32_e32 v158, 0, v4
	s_movk_i32 s42, 0x3000
	s_barrier
	s_waitcnt vmcnt(0)
	s_branch .LBB0_286

; #define PG8_STAGE(bufoff, gbase, voff) do { _Pragma("unroll") for (int _i = 0; _i < 2; ++_i) \
;         __builtin_amdgcn_global_load_lds((const unsigned*)((const char*)(gbase) + (voff)[_i]), (PG8_LAS unsigned*)(lds + (bufoff) + ldsw + _i * 8192), 16, 0, 0); } while (0)
; #define PG8_LDA(dst, b, h) do { _Pragma("unroll") for (int m = 0; m < 4; ++m) _Pragma("unroll") for (int k = 0; k < 2; ++k) dst[m][k] = *(const PG8_LAS bf16x8*)(lds + PG8_SA(b, h) + aoff + m * 2048 + k * 1024); } while (0)
; #define PG8_LDB(dst, b, h) do { _Pragma("unroll") for (int n = 0; n < 2; ++n) _Pragma("unroll") for (int k = 0; k < 2; ++k) dst[n][k] = *(const PG8_LAS bf16x8*)(lds + PG8_SB(b, h) + boff + n * 2048 + k * 1024); } while (0)
; #define PG8_MMA(ai, bj, At, Bt) do { __builtin_amdgcn_s_setprio(1); _Pragma("unroll") for (int m = 0; m < 4; ++m) _Pragma("unroll") for (int n = 0; n < 2; ++n) _Pragma("unroll") for (int k = 0; k < 2; ++k) \
;         acc[ai][bj][m][n] = __builtin_amdgcn_mfma_f32_16x16x32_bf16(Bt[n][k], At[m][k], acc[ai][bj][m][n], 0, 0, 0); __builtin_amdgcn_s_setprio(0); } while (0)
; #define PG8_WAIT_V(n) asm volatile("s_waitcnt vmcnt(" #n ")" ::: "memory")
; #define PG8_WAIT_L(n) asm volatile("s_waitcnt lgkmcnt(" #n ")" ::: "memory")
; #define PG8_BAR __builtin_amdgcn_s_barrier()
; #define PG8_SCHED __builtin_amdgcn_sched_barrier(0)
; template <class Epi, class Sched, bool ALIGN_EPI = false, bool SP2 = false>
; __device__ __forceinline__ void gemm_phase(PG8_LAS unsigned char* lds, const Gemm g, const Sched& S, const Epi& E) {
;     ...
;             PG8_LDB(B0, 0, 0); PG8_LDB(B1, 0, 1); PG8_SCHED; PG8_LDA(At, 0, 0); PG8_STAGE(PG8_SA(1, 1), a1 + hstep, voffA);
;             PG8_WAIT_V(8); PG8_WAIT_L(0); PG8_BAR; PG8_MMA(0, 0, At, B0); PG8_MMA(0, 1, At, B1); PG8_BAR; PG8_SCHED;
;             PG8_LDA(At, 0, 1); PG8_STAGE(PG8_SB(0, 0), b2, voffB); PG8_STAGE(PG8_SB(0, 1), b2 + hstep, voffB); PG8_STAGE(PG8_SA(0, 0), a2, voffA);
;             PG8_WAIT_V(8); PG8_WAIT_L(0); PG8_BAR; PG8_MMA(1, 0, At, B0); PG8_MMA(1, 1, At, B1); PG8_BAR; PG8_SCHED;
.LBB0_289:
	ds_read_b128 v[146:149], v156
	ds_read_b128 v[160:163], v156 offset:1024
	ds_read_b128 v[164:167], v156 offset:2048
	ds_read_b128 v[168:171], v156 offset:3072
	ds_read_b128 v[180:183], v157
	ds_read_b128 v[184:187], v157 offset:1024
	ds_read_b128 v[188:191], v157 offset:2048
	ds_read_b128 v[192:195], v157 offset:3072
	s_add_u32 s24, s22, 0xfff80080
	s_addc_u32 s25, s23, -1
	s_cmp_eq_u32 s50, 28
	s_cselect_b32 s27, s15, s25
	s_cselect_b32 s26, s46, s24
	s_cselect_b32 s25, s13, s49
	s_cselect_b32 s24, s47, s48
	s_add_i32 m0, s21, 0xc000
	ds_read_b128 v[196:199], v158
	ds_read_b128 v[200:203], v158 offset:1024
	ds_read_b128 v[204:207], v158 offset:2048
	ds_read_b128 v[208:211], v158 offset:3072
	ds_read_b128 v[212:215], v158 offset:4096
	ds_read_b128 v[216:219], v158 offset:5120
	ds_read_b128 v[220:223], v158 offset:6144
	ds_read_b128 v[224:227], v158 offset:7168
	global_load_lds_dwordx4 v138, s[22:23]
	s_add_i32 m0, s21, 0xe000
	s_nop 0
	global_load_lds_dwordx4 v140, s[22:23]
	s_waitcnt vmcnt(8)
	s_waitcnt lgkmcnt(0)
	s_barrier
	s_setprio 1
	s_waitcnt lgkmcnt(0)
	v_mfma_f32_16x16x32_bf16 v[124:127], v[146:149], v[196:199], v[124:127]
	v_mfma_f32_16x16x32_bf16 v[120:123], v[164:167], v[196:199], v[120:123]
	v_mfma_f32_16x16x32_bf16 v[116:119], v[146:149], v[204:207], v[116:119]
	v_mfma_f32_16x16x32_bf16 v[108:111], v[164:167], v[204:207], v[108:111]
	v_mfma_f32_16x16x32_bf16 v[100:103], v[146:149], v[212:215], v[100:103]
	v_mfma_f32_16x16x32_bf16 v[92:95], v[164:167], v[212:215], v[92:95]
	v_mfma_f32_16x16x32_bf16 v[84:87], v[146:149], v[220:223], v[84:87]
	v_mfma_f32_16x16x32_bf16 v[76:79], v[164:167], v[220:223], v[76:79]
	v_mfma_f32_16x16x32_bf16 v[124:127], v[160:163], v[200:203], v[124:127]
	v_mfma_f32_16x16x32_bf16 v[120:123], v[168:171], v[200:203], v[120:123]
	v_mfma_f32_16x16x32_bf16 v[116:119], v[160:163], v[208:211], v[116:119]
	v_mfma_f32_16x16x32_bf16 v[108:111], v[168:171], v[208:211], v[108:111]
	v_mfma_f32_16x16x32_bf16 v[100:103], v[160:163], v[216:219], v[100:103]
	v_mfma_f32_16x16x32_bf16 v[92:95], v[168:171], v[216:219], v[92:95]
	v_mfma_f32_16x16x32_bf16 v[84:87], v[160:163], v[224:227], v[84:87]
	v_mfma_f32_16x16x32_bf16 v[76:79], v[168:171], v[224:227], v[76:79]
	s_setprio 0
	s_setprio 1
	v_mfma_f32_16x16x32_bf16 v[112:115], v[180:183], v[196:199], v[112:115]
	v_mfma_f32_16x16x32_bf16 v[104:107], v[188:191], v[196:199], v[104:107]
	v_mfma_f32_16x16x32_bf16 v[96:99], v[180:183], v[204:207], v[96:99]
	v_mfma_f32_16x16x32_bf16 v[88:91], v[188:191], v[204:207], v[88:91]
	v_mfma_f32_16x16x32_bf16 v[80:83], v[180:183], v[212:215], v[80:83]
	v_mfma_f32_16x16x32_bf16 v[72:75], v[188:191], v[212:215], v[72:75]
	v_mfma_f32_16x16x32_bf16 v[68:71], v[180:183], v[220:223], v[68:71]
	v_mfma_f32_16x16x32_bf16 v[64:67], v[188:191], v[220:223], v[64:67]
	v_mfma_f32_16x16x32_bf16 v[112:115], v[184:187], v[200:203], v[112:115]
	v_mfma_f32_16x16x32_bf16 v[104:107], v[192:195], v[200:203], v[104:107]
	v_mfma_f32_16x16x32_bf16 v[96:99], v[184:187], v[208:211], v[96:99]
	v_mfma_f32_16x16x32_bf16 v[88:91], v[192:195], v[208:211], v[88:91]
	v_mfma_f32_16x16x32_bf16 v[80:83], v[184:187], v[216:219], v[80:83]
	v_mfma_f32_16x16x32_bf16 v[72:75], v[192:195], v[216:219], v[72:75]
	v_mfma_f32_16x16x32_bf16 v[68:71], v[184:187], v[224:227], v[68:71]
	v_mfma_f32_16x16x32_bf16 v[64:67], v[192:195], v[224:227], v[64:67]
	s_setprio 0
	s_barrier
	s_add_i32 s51, s40, s30
	v_lshl_add_u64 v[150:151], s[24:25], 0, v[134:135]
	s_mov_b32 m0, s51
	ds_read_b128 v[196:199], v158 offset:16384
	ds_read_b128 v[200:203], v158 offset:17408
	ds_read_b128 v[204:207], v158 offset:18432
	ds_read_b128 v[208:211], v158 offset:19456
	ds_read_b128 v[212:215], v158 offset:20480
	ds_read_b128 v[216:219], v158 offset:21504
	ds_read_b128 v[220:223], v158 offset:22528
	ds_read_b128 v[224:227], v158 offset:23552
	global_load_lds_dwordx4 v[150:151], off
	s_add_i32 m0, s51, 0x2000
	s_add_u32 s52, s24, 0x80000
	v_lshl_add_u64 v[228:229], s[24:25], 0, v[130:131]
	s_addc_u32 s53, s25, 0
	s_add_i32 s51, s41, s30
	global_load_lds_dwordx4 v[228:229], off
	s_mov_b32 m0, s51
	v_lshl_add_u64 v[232:233], s[26:27], 0, v[132:133]
	global_load_lds_dwordx4 v134, s[52:53]
	s_add_i32 m0, s51, 0x2000
	s_nop 0
	global_load_lds_dwordx4 v130, s[52:53]
	v_lshl_add_u64 v[230:231], s[26:27], 0, v[136:137]
	s_mov_b32 m0, s21
	s_nop 0
	global_load_lds_dwordx4 v[230:231], off
	s_mov_b32 m0, s33
	s_nop 0
	global_load_lds_dwordx4 v[232:233], off
	s_waitcnt vmcnt(8)
	s_waitcnt lgkmcnt(0)
	s_barrier
; #define PG8_STAGE(bufoff, gbase, voff) do { _Pragma("unroll") for (int _i = 0; _i < 2; ++_i) \
;         __builtin_amdgcn_global_load_lds((const unsigned*)((const char*)(gbase) + (voff)[_i]), (PG8_LAS unsigned*)(lds + (bufoff) + ldsw + _i * 8192), 16, 0, 0); } while (0)
; #define PG8_LDA(dst, b, h) do { _Pragma("unroll") for (int m = 0; m < 4; ++m) _Pragma("unroll") for (int k = 0; k < 2; ++k) dst[m][k] = *(const PG8_LAS bf16x8*)(lds + PG8_SA(b, h) + aoff + m * 2048 + k * 1024); } while (0)
; #define PG8_LDB(dst, b, h) do { _Pragma("unroll") for (int n = 0; n < 2; ++n) _Pragma("unroll") for (int k = 0; k < 2; ++k) dst[n][k] = *(const PG8_LAS bf16x8*)(lds + PG8_SB(b, h) + boff + n * 2048 + k * 1024); } while (0)
; #define PG8_MMA(ai, bj, At, Bt) do { __builtin_amdgcn_s_setprio(1); _Pragma("unroll") for (int m = 0; m < 4; ++m) _Pragma("unroll") for (int n = 0; n < 2; ++n) _Pragma("unroll") for (int k = 0; k < 2; ++k) \
;         acc[ai][bj][m][n] = __builtin_amdgcn_mfma_f32_16x16x32_bf16(Bt[n][k], At[m][k], acc[ai][bj][m][n], 0, 0, 0); __builtin_amdgcn_s_setprio(0); } while (0)
; #define PG8_WAIT_V(n) asm volatile("s_waitcnt vmcnt(" #n ")" ::: "memory")
; #define PG8_WAIT_L(n) asm volatile("s_waitcnt lgkmcnt(" #n ")" ::: "memory")
; #define PG8_BAR __builtin_amdgcn_s_barrier()
; #define PG8_SCHED __builtin_amdgcn_sched_barrier(0)
; template <class Epi, class Sched, bool ALIGN_EPI = false, bool SP2 = false>
; __device__ __forceinline__ void gemm_phase(PG8_LAS unsigned char* lds, const Gemm g, const Sched& S, const Epi& E) {
;     ...
;             PG8_WAIT_V(8); PG8_WAIT_L(0); PG8_BAR; PG8_MMA(1, 0, At, B0); PG8_MMA(1, 1, At, B1); PG8_BAR; PG8_SCHED;
;             PG8_LDB(B0, 1, 0); PG8_LDB(B1, 1, 1); PG8_SCHED; PG8_LDA(At, 1, 0); PG8_STAGE(PG8_SA(0, 1), a2 + hstep, voffA);
;             PG8_WAIT_V(8); PG8_WAIT_L(0); PG8_BAR; PG8_MMA(0, 0, At, B0); PG8_MMA(0, 1, At, B1); PG8_BAR; PG8_SCHED;
	s_setprio 1
	s_waitcnt lgkmcnt(0)
	v_mfma_f32_16x16x32_bf16 v[60:63], v[146:149], v[196:199], v[60:63]
	v_mfma_f32_16x16x32_bf16 v[56:59], v[164:167], v[196:199], v[56:59]
	v_mfma_f32_16x16x32_bf16 v[52:55], v[146:149], v[204:207], v[52:55]
	v_mfma_f32_16x16x32_bf16 v[44:47], v[164:167], v[204:207], v[44:47]
	v_mfma_f32_16x16x32_bf16 v[36:39], v[146:149], v[212:215], v[36:39]
	v_mfma_f32_16x16x32_bf16 v[28:31], v[164:167], v[212:215], v[28:31]
	v_mfma_f32_16x16x32_bf16 v[20:23], v[146:149], v[220:223], v[20:23]
	v_mfma_f32_16x16x32_bf16 v[12:15], v[164:167], v[220:223], v[12:15]
	v_mfma_f32_16x16x32_bf16 v[60:63], v[160:163], v[200:203], v[60:63]
	v_mfma_f32_16x16x32_bf16 v[56:59], v[168:171], v[200:203], v[56:59]
	v_mfma_f32_16x16x32_bf16 v[52:55], v[160:163], v[208:211], v[52:55]
	v_mfma_f32_16x16x32_bf16 v[44:47], v[168:171], v[208:211], v[44:47]
	v_mfma_f32_16x16x32_bf16 v[36:39], v[160:163], v[216:219], v[36:39]
	v_mfma_f32_16x16x32_bf16 v[28:31], v[168:171], v[216:219], v[28:31]
	v_mfma_f32_16x16x32_bf16 v[20:23], v[160:163], v[224:227], v[20:23]
	v_mfma_f32_16x16x32_bf16 v[12:15], v[168:171], v[224:227], v[12:15]
	s_setprio 0
	s_setprio 1
	v_mfma_f32_16x16x32_bf16 v[48:51], v[180:183], v[196:199], v[48:51]
	v_mfma_f32_16x16x32_bf16 v[40:43], v[188:191], v[196:199], v[40:43]
	v_mfma_f32_16x16x32_bf16 v[32:35], v[180:183], v[204:207], v[32:35]
	v_mfma_f32_16x16x32_bf16 v[24:27], v[188:191], v[204:207], v[24:27]
	v_mfma_f32_16x16x32_bf16 v[16:19], v[180:183], v[212:215], v[16:19]
	v_mfma_f32_16x16x32_bf16 v[8:11], v[188:191], v[212:215], v[8:11]
	v_mfma_f32_16x16x32_bf16 v[4:7], v[180:183], v[220:223], v[4:7]
	v_mfma_f32_16x16x32_bf16 v[0:3], v[188:191], v[220:223], v[0:3]
	v_mfma_f32_16x16x32_bf16 v[48:51], v[184:187], v[200:203], v[48:51]
	v_mfma_f32_16x16x32_bf16 v[40:43], v[192:195], v[200:203], v[40:43]
	v_mfma_f32_16x16x32_bf16 v[32:35], v[184:187], v[208:211], v[32:35]
	v_mfma_f32_16x16x32_bf16 v[24:27], v[192:195], v[208:211], v[24:27]
	v_mfma_f32_16x16x32_bf16 v[16:19], v[184:187], v[216:219], v[16:19]
	v_mfma_f32_16x16x32_bf16 v[8:11], v[192:195], v[216:219], v[8:11]
	v_mfma_f32_16x16x32_bf16 v[4:7], v[184:187], v[224:227], v[4:7]
	v_mfma_f32_16x16x32_bf16 v[0:3], v[192:195], v[224:227], v[0:3]
	s_setprio 0
	s_barrier
	s_add_i32 s51, 0, 0x18000
	v_add_u32_e32 v159, s51, v153
	s_add_i32 s52, 0, 0x1c000
	ds_read_b128 v[146:149], v159
	ds_read_b128 v[160:163], v159 offset:1024
	ds_read_b128 v[164:167], v159 offset:2048
	ds_read_b128 v[168:171], v159 offset:3072
	v_add_u32_e32 v159, s52, v153
	ds_read_b128 v[180:183], v159
	ds_read_b128 v[184:187], v159 offset:1024
	ds_read_b128 v[188:191], v159 offset:2048
	ds_read_b128 v[192:195], v159 offset:3072
	s_add_u32 s26, s26, 0x80000
	s_addc_u32 s27, s27, 0
	s_mov_b32 m0, s34
	ds_read_b128 v[196:199], v158 offset:32768
	ds_read_b128 v[200:203], v158 offset:33792
	ds_read_b128 v[204:207], v158 offset:34816
	ds_read_b128 v[208:211], v158 offset:35840
	ds_read_b128 v[212:215], v158 offset:36864
	ds_read_b128 v[216:219], v158 offset:37888
	ds_read_b128 v[220:223], v158 offset:38912
	ds_read_b128 v[224:227], v158 offset:39936
	global_load_lds_dwordx4 v136, s[26:27]
	s_mov_b32 m0, s35
	s_nop 0
	global_load_lds_dwordx4 v132, s[26:27]
	s_waitcnt vmcnt(8)
	s_waitcnt lgkmcnt(0)
	s_barrier
	s_setprio 1
	s_waitcnt lgkmcnt(0)
	v_mfma_f32_16x16x32_bf16 v[124:127], v[146:149], v[196:199], v[124:127]
	v_mfma_f32_16x16x32_bf16 v[120:123], v[164:167], v[196:199], v[120:123]
	v_mfma_f32_16x16x32_bf16 v[116:119], v[146:149], v[204:207], v[116:119]
	v_mfma_f32_16x16x32_bf16 v[108:111], v[164:167], v[204:207], v[108:111]
	v_mfma_f32_16x16x32_bf16 v[100:103], v[146:149], v[212:215], v[100:103]
	v_mfma_f32_16x16x32_bf16 v[92:95], v[164:167], v[212:215], v[92:95]
	v_mfma_f32_16x16x32_bf16 v[84:87], v[146:149], v[220:223], v[84:87]
	v_mfma_f32_16x16x32_bf16 v[76:79], v[164:167], v[220:223], v[76:79]
	v_mfma_f32_16x16x32_bf16 v[124:127], v[160:163], v[200:203], v[124:127]
	v_mfma_f32_16x16x32_bf16 v[120:123], v[168:171], v[200:203], v[120:123]
	v_mfma_f32_16x16x32_bf16 v[116:119], v[160:163], v[208:211], v[116:119]
	v_mfma_f32_16x16x32_bf16 v[108:111], v[168:171], v[208:211], v[108:111]
	v_mfma_f32_16x16x32_bf16 v[100:103], v[160:163], v[216:219], v[100:103]
	v_mfma_f32_16x16x32_bf16 v[92:95], v[168:171], v[216:219], v[92:95]
	v_mfma_f32_16x16x32_bf16 v[84:87], v[160:163], v[224:227], v[84:87]
	v_mfma_f32_16x16x32_bf16 v[76:79], v[168:171], v[224:227], v[76:79]
	s_setprio 0
	s_setprio 1
	v_mfma_f32_16x16x32_bf16 v[112:115], v[180:183], v[196:199], v[112:115]
	v_mfma_f32_16x16x32_bf16 v[104:107], v[188:191], v[196:199], v[104:107]
	v_mfma_f32_16x16x32_bf16 v[96:99], v[180:183], v[204:207], v[96:99]
	v_mfma_f32_16x16x32_bf16 v[88:91], v[188:191], v[204:207], v[88:91]
	v_mfma_f32_16x16x32_bf16 v[80:83], v[180:183], v[212:215], v[80:83]
	v_mfma_f32_16x16x32_bf16 v[72:75], v[188:191], v[212:215], v[72:75]
	v_mfma_f32_16x16x32_bf16 v[68:71], v[180:183], v[220:223], v[68:71]
	v_mfma_f32_16x16x32_bf16 v[64:67], v[188:191], v[220:223], v[64:67]
	v_mfma_f32_16x16x32_bf16 v[112:115], v[184:187], v[200:203], v[112:115]
	v_mfma_f32_16x16x32_bf16 v[104:107], v[192:195], v[200:203], v[104:107]
	v_mfma_f32_16x16x32_bf16 v[96:99], v[184:187], v[208:211], v[96:99]
	v_mfma_f32_16x16x32_bf16 v[88:91], v[192:195], v[208:211], v[88:91]
	v_mfma_f32_16x16x32_bf16 v[80:83], v[184:187], v[216:219], v[80:83]
	v_mfma_f32_16x16x32_bf16 v[72:75], v[192:195], v[216:219], v[72:75]
	v_mfma_f32_16x16x32_bf16 v[68:71], v[184:187], v[224:227], v[68:71]
	v_mfma_f32_16x16x32_bf16 v[64:67], v[192:195], v[224:227], v[64:67]
	s_setprio 0
	s_barrier
; #define PG8_STAGE(bufoff, gbase, voff) do { _Pragma("unroll") for (int _i = 0; _i < 2; ++_i) \
;         __builtin_amdgcn_global_load_lds((const unsigned*)((const char*)(gbase) + (voff)[_i]), (PG8_LAS unsigned*)(lds + (bufoff) + ldsw + _i * 8192), 16, 0, 0); } while (0)
; #define PG8_LDA(dst, b, h) do { _Pragma("unroll") for (int m = 0; m < 4; ++m) _Pragma("unroll") for (int k = 0; k < 2; ++k) dst[m][k] = *(const PG8_LAS bf16x8*)(lds + PG8_SA(b, h) + aoff + m * 2048 + k * 1024); } while (0)
; #define PG8_MMA(ai, bj, At, Bt) do { __builtin_amdgcn_s_setprio(1); _Pragma("unroll") for (int m = 0; m < 4; ++m) _Pragma("unroll") for (int n = 0; n < 2; ++n) _Pragma("unroll") for (int k = 0; k < 2; ++k) \
;         acc[ai][bj][m][n] = __builtin_amdgcn_mfma_f32_16x16x32_bf16(Bt[n][k], At[m][k], acc[ai][bj][m][n], 0, 0, 0); __builtin_amdgcn_s_setprio(0); } while (0)
; #define PG8_WAIT_V(n) asm volatile("s_waitcnt vmcnt(" #n ")" ::: "memory")
; #define PG8_WAIT_L(n) asm volatile("s_waitcnt lgkmcnt(" #n ")" ::: "memory")
; #define PG8_BAR __builtin_amdgcn_s_barrier()
; #define PG8_SCHED __builtin_amdgcn_sched_barrier(0)
; template <class Epi, class Sched, bool ALIGN_EPI = false, bool SP2 = false>
; __device__ __forceinline__ void gemm_phase(PG8_LAS unsigned char* lds, const Gemm g, const Sched& S, const Epi& E) {
;     ...
;         for (int t = 0; t < nt; t += 2) {
;     ...
;             PG8_LDA(At, 1, 1); PG8_STAGE(PG8_SB(1, 0), b3, voffB); PG8_STAGE(PG8_SB(1, 1), b3 + hstep, voffB); PG8_STAGE(PG8_SA(1, 0), a3, voffA);
;             PG8_WAIT_V(8); PG8_WAIT_L(0); PG8_BAR; PG8_MMA(1, 0, At, B0); PG8_MMA(1, 1, At, B1); PG8_BAR; PG8_SCHED;
	s_add_i32 s26, s51, s30
	v_lshl_add_u64 v[150:151], v[150:151], 0, s[2:3]
	s_mov_b32 m0, s26
	ds_read_b128 v[196:199], v158 offset:49152
	ds_read_b128 v[200:203], v158 offset:50176
	ds_read_b128 v[204:207], v158 offset:51200
	ds_read_b128 v[208:211], v158 offset:52224
	ds_read_b128 v[212:215], v158 offset:53248
	ds_read_b128 v[216:219], v158 offset:54272
	ds_read_b128 v[220:223], v158 offset:55296
	ds_read_b128 v[224:227], v158 offset:56320
	global_load_lds_dwordx4 v[150:151], off
	s_add_i32 m0, s26, 0x2000
	s_add_u32 s24, s24, 0x80080
	v_lshl_add_u64 v[150:151], v[228:229], 0, s[2:3]
	s_addc_u32 s25, s25, 0
	s_add_i32 s26, s52, s30
	global_load_lds_dwordx4 v[150:151], off
	s_mov_b32 m0, s26
	s_nop 0
	global_load_lds_dwordx4 v134, s[24:25]
	s_add_i32 m0, s26, 0x2000
	s_nop 0
	global_load_lds_dwordx4 v130, s[24:25]
	v_lshl_add_u64 v[150:151], v[230:231], 0, s[2:3]
	s_mov_b32 m0, s36
	s_nop 0
	global_load_lds_dwordx4 v[150:151], off
	v_lshl_add_u64 v[150:151], v[232:233], 0, s[2:3]
	s_mov_b32 m0, s37
	s_nop 0
	global_load_lds_dwordx4 v[150:151], off
	s_waitcnt vmcnt(8)
	s_waitcnt lgkmcnt(0)
	s_barrier
	s_setprio 1
	s_waitcnt lgkmcnt(0)
	v_mfma_f32_16x16x32_bf16 v[60:63], v[146:149], v[196:199], v[60:63]
	v_mfma_f32_16x16x32_bf16 v[56:59], v[164:167], v[196:199], v[56:59]
	v_mfma_f32_16x16x32_bf16 v[52:55], v[146:149], v[204:207], v[52:55]
	v_mfma_f32_16x16x32_bf16 v[44:47], v[164:167], v[204:207], v[44:47]
	v_mfma_f32_16x16x32_bf16 v[36:39], v[146:149], v[212:215], v[36:39]
	v_mfma_f32_16x16x32_bf16 v[28:31], v[164:167], v[212:215], v[28:31]
	v_mfma_f32_16x16x32_bf16 v[20:23], v[146:149], v[220:223], v[20:23]
	v_mfma_f32_16x16x32_bf16 v[12:15], v[164:167], v[220:223], v[12:15]
	v_mfma_f32_16x16x32_bf16 v[60:63], v[160:163], v[200:203], v[60:63]
	v_mfma_f32_16x16x32_bf16 v[56:59], v[168:171], v[200:203], v[56:59]
	v_mfma_f32_16x16x32_bf16 v[52:55], v[160:163], v[208:211], v[52:55]
	v_mfma_f32_16x16x32_bf16 v[44:47], v[168:171], v[208:211], v[44:47]
	v_mfma_f32_16x16x32_bf16 v[36:39], v[160:163], v[216:219], v[36:39]
	v_mfma_f32_16x16x32_bf16 v[28:31], v[168:171], v[216:219], v[28:31]
	v_mfma_f32_16x16x32_bf16 v[20:23], v[160:163], v[224:227], v[20:23]
	v_mfma_f32_16x16x32_bf16 v[12:15], v[168:171], v[224:227], v[12:15]
	s_setprio 0
	s_setprio 1
	v_mfma_f32_16x16x32_bf16 v[48:51], v[180:183], v[196:199], v[48:51]
	v_mfma_f32_16x16x32_bf16 v[40:43], v[188:191], v[196:199], v[40:43]
	v_mfma_f32_16x16x32_bf16 v[32:35], v[180:183], v[204:207], v[32:35]
	v_mfma_f32_16x16x32_bf16 v[24:27], v[188:191], v[204:207], v[24:27]
	v_mfma_f32_16x16x32_bf16 v[16:19], v[180:183], v[212:215], v[16:19]
	v_mfma_f32_16x16x32_bf16 v[8:11], v[188:191], v[212:215], v[8:11]
	v_mfma_f32_16x16x32_bf16 v[4:7], v[180:183], v[220:223], v[4:7]
	v_mfma_f32_16x16x32_bf16 v[0:3], v[188:191], v[220:223], v[0:3]
	v_mfma_f32_16x16x32_bf16 v[48:51], v[184:187], v[200:203], v[48:51]
	v_mfma_f32_16x16x32_bf16 v[40:43], v[192:195], v[200:203], v[40:43]
	v_mfma_f32_16x16x32_bf16 v[32:35], v[184:187], v[208:211], v[32:35]
	v_mfma_f32_16x16x32_bf16 v[24:27], v[192:195], v[208:211], v[24:27]
	v_mfma_f32_16x16x32_bf16 v[16:19], v[184:187], v[216:219], v[16:19]
	v_mfma_f32_16x16x32_bf16 v[8:11], v[192:195], v[216:219], v[8:11]
	v_mfma_f32_16x16x32_bf16 v[4:7], v[184:187], v[224:227], v[4:7]
	v_mfma_f32_16x16x32_bf16 v[0:3], v[192:195], v[224:227], v[0:3]
	s_setprio 0
	s_barrier
	s_add_i32 s50, s50, 2
	s_add_u32 s22, s22, 0x100
	s_addc_u32 s23, s23, 0
	s_add_u32 s48, s48, 0x100
	s_addc_u32 s49, s49, 0
	s_cmp_gt_u32 s50, 29
	s_cbranch_scc0 .LBB0_289
	s_nop 0
	v_readfirstlane_b32 s15, v172
	s_nop 3
	s_lshr_b32 s15, s15, 6
	s_cmp_lt_u32 s15, 4
	s_cbranch_scc0 .Lprio_k0
	s_setprio 1

; #define PG8_STAGE(bufoff, gbase, voff) do { _Pragma("unroll") for (int _i = 0; _i < 2; ++_i) \
;         __builtin_amdgcn_global_load_lds((const unsigned*)((const char*)(gbase) + (voff)[_i]), (PG8_LAS unsigned*)(lds + (bufoff) + ldsw + _i * 8192), 16, 0, 0); } while (0)
; #define PG8_WAIT_V(n) asm volatile("s_waitcnt vmcnt(" #n ")" ::: "memory")
; #define PG8_BAR __builtin_amdgcn_s_barrier()
; template <class Epi, class Sched, bool ALIGN_EPI = false, bool SP2 = false>
; __device__ __forceinline__ void gemm_phase(PG8_LAS unsigned char* lds, const Gemm g, const Sched& S, const Epi& E) {
;     ...
;     for (int i = 0; i < 2; ++i) { int R, C; stage_rc(tid * 16 + i * 8192, R, C); const int Rb = Epi::PERM ? ((R & ~31) + perm32(R & 31)) : R;
;         voffA[i] = (unsigned)(R * K + C) * 2u; voffB[i] = (unsigned)(Rb * K + C) * 2u; }
;     const size_t kstep = (size_t)(BK * 2);
;     const size_t hstep = (size_t)HALF * K * 2;
;     const size_t tstep = 2 * hstep;
;     const unsigned ldsw = (unsigned)wid * 1024u;
;     const int aoff = lds_byte(wr * 64 + fr, fq * 8), boff = lds_byte(wc * 32 + fr, fq * 8);
;     ...
;         PG8_STAGE(PG8_SB(1, 0), cB + kstep, voffB); PG8_STAGE(PG8_SA(1, 0), cA + kstep, voffA); PG8_STAGE(PG8_SB(1, 1), cB + hstep + kstep, voffB);
;         PG8_WAIT_V(6); PG8_BAR;
.LBB0_575:
	v_bfe_u32 v16, v12, 4, 2
	v_and_b32_e32 v15, 15, v12
	v_lshlrev_b32_e32 v17, 4, v16
	v_lshlrev_b32_e32 v12, 2, v12
	s_and_b32 s40, s4, 3
	v_lshl_or_b32 v146, s5, 6, v15
	v_lshl_or_b32 v15, v15, 6, v17
	s_lshl_b32 s4, s5, 13
	v_and_b32_e32 v12, 32, v12
	v_bitop3_b32 v17, v15, s4, v12 bitop3:0xde
	s_lshl_b32 s4, s40, 12
	v_bitop3_b32 v147, v15, s4, v12 bitop3:0xde
	s_mov_b64 s[4:5], 0x80
	s_add_i32 m0, s34, 0x18000
	v_lshl_add_u64 v[6:7], v[6:7], 0, s[4:5]
	s_waitcnt vmcnt(2)
	s_barrier
	global_load_lds_dwordx4 v[6:7], off
	v_lshl_add_u64 v[4:5], v[4:5], 0, s[4:5]
	s_add_i32 m0, s34, 0x1a000
	s_add_i32 s41, s34, 0x8000
	s_add_i32 s44, s34, 0xa000
	global_load_lds_dwordx4 v[4:5], off
	v_lshl_add_u64 v[0:1], v[0:1], 0, s[4:5]
	s_mov_b32 m0, s41
	s_add_u32 s8, s26, 0x80080
	global_load_lds_dwordx4 v[0:1], off
	v_lshl_add_u64 v[0:1], v[2:3], 0, s[4:5]
	s_mov_b32 m0, s44
	s_addc_u32 s9, s27, 0
	global_load_lds_dwordx4 v[0:1], off
	s_add_i32 m0, s34, 0x1c000
	s_nop 0
	global_load_lds_dwordx4 v130, s[8:9]
	s_add_i32 m0, s34, 0x1e000
	s_cmpk_lt_u32 s6, 0x100
	global_load_lds_dwordx4 v132, s[8:9]
	v_lshlrev_b32_e32 v0, 2, v16
	v_lshl_or_b32 v148, s40, 5, v0
	v_lshlrev_b32_e32 v0, 15, v8
	v_and_b32_e32 v0, 0xffff0000, v0
	v_lshl_add_u32 v0, v9, 12, v0
	v_and_b32_e32 v1, 1, v8
	v_lshl_or_b32 v0, v1, 6, v0
	v_lshl_add_u32 v134, v10, 1, v0
	v_lshlrev_b32_e32 v0, 15, v11
	v_and_b32_e32 v0, 0xffff0000, v0
	s_waitcnt vmcnt(6)
	v_lshl_add_u32 v0, v13, 12, v0
	v_and_b32_e32 v1, 1, v11
	s_cselect_b64 s[6:7], -1, 0
	v_lshl_or_b32 v0, v1, 6, v0
	s_add_i32 s45, 0, 0x10000
	s_add_i32 s46, 0, 0x14000
	v_cmp_eq_u32_e64 s[8:9], 0, v16
	v_mov_b32_e32 v135, v131
	v_lshl_add_u32 v136, v14, 1, v0
	v_mov_b32_e32 v137, v131
	v_mov_b64_e32 v[138:139], 0x100
	v_mov_b64_e32 v[140:141], 0xff
	v_add_u32_e32 v149, s45, v147
	v_add_u32_e32 v150, s46, v147
	v_add_u32_e32 v151, 0, v17
	s_mov_b32 s47, 0
	s_barrier
	s_branch .LBB0_578

; #define PG8_STAGE(bufoff, gbase, voff) do { _Pragma("unroll") for (int _i = 0; _i < 2; ++_i) \
;         __builtin_amdgcn_global_load_lds((const unsigned*)((const char*)(gbase) + (voff)[_i]), (PG8_LAS unsigned*)(lds + (bufoff) + ldsw + _i * 8192), 16, 0, 0); } while (0)
; #define PG8_LDA(dst, b, h) do { _Pragma("unroll") for (int m = 0; m < 4; ++m) _Pragma("unroll") for (int k = 0; k < 2; ++k) dst[m][k] = *(const PG8_LAS bf16x8*)(lds + PG8_SA(b, h) + aoff + m * 2048 + k * 1024); } while (0)
; #define PG8_LDB(dst, b, h) do { _Pragma("unroll") for (int n = 0; n < 2; ++n) _Pragma("unroll") for (int k = 0; k < 2; ++k) dst[n][k] = *(const PG8_LAS bf16x8*)(lds + PG8_SB(b, h) + boff + n * 2048 + k * 1024); } while (0)
; #define PG8_MMA(ai, bj, At, Bt) do { __builtin_amdgcn_s_setprio(1); _Pragma("unroll") for (int m = 0; m < 4; ++m) _Pragma("unroll") for (int n = 0; n < 2; ++n) _Pragma("unroll") for (int k = 0; k < 2; ++k) \
;         acc[ai][bj][m][n] = __builtin_amdgcn_mfma_f32_16x16x32_bf16(Bt[n][k], At[m][k], acc[ai][bj][m][n], 0, 0, 0); __builtin_amdgcn_s_setprio(0); } while (0)
; #define PG8_WAIT_V(n) asm volatile("s_waitcnt vmcnt(" #n ")" ::: "memory")
; #define PG8_WAIT_L(n) asm volatile("s_waitcnt lgkmcnt(" #n ")" ::: "memory")
; #define PG8_BAR __builtin_amdgcn_s_barrier()
; #define PG8_SCHED __builtin_amdgcn_sched_barrier(0)
; template <class Epi, class Sched, bool ALIGN_EPI = false, bool SP2 = false>
; __device__ __forceinline__ void gemm_phase(PG8_LAS unsigned char* lds, const Gemm g, const Sched& S, const Epi& E) {
;     ...
;             PG8_LDB(B0, 0, 0); PG8_LDB(B1, 0, 1); PG8_SCHED; PG8_LDA(At, 0, 0); PG8_STAGE(PG8_SA(1, 1), a1 + hstep, voffA);
;             PG8_WAIT_V(8); PG8_WAIT_L(0); PG8_BAR; PG8_MMA(0, 0, At, B0); PG8_MMA(0, 1, At, B1); PG8_BAR; PG8_SCHED;
;             PG8_LDA(At, 0, 1); PG8_STAGE(PG8_SB(0, 0), b2, voffB); PG8_STAGE(PG8_SB(0, 1), b2 + hstep, voffB); PG8_STAGE(PG8_SA(0, 0), a2, voffA);
;             PG8_WAIT_V(8); PG8_WAIT_L(0); PG8_BAR; PG8_MMA(1, 0, At, B0); PG8_MMA(1, 1, At, B1); PG8_BAR; PG8_SCHED;
.LBB0_585:
	ds_read_b128 v[142:145], v149
	ds_read_b128 v[152:155], v149 offset:1024
	ds_read_b128 v[156:159], v149 offset:2048
	ds_read_b128 v[160:163], v149 offset:3072
	ds_read_b128 v[164:167], v150
	ds_read_b128 v[168:171], v150 offset:1024
	ds_read_b128 v[180:183], v150 offset:2048
	ds_read_b128 v[184:187], v150 offset:3072
	s_add_u32 s26, s24, 0xfff80080
	s_addc_u32 s27, s25, -1
	s_cmp_eq_u32 s51, 28
	s_cselect_b32 s29, s17, s27
	s_cselect_b32 s28, s23, s26
	s_cselect_b32 s27, s13, s50
	s_cselect_b32 s26, s48, s49
	s_add_i32 m0, s34, 0xc000
	ds_read_b128 v[188:191], v151
	ds_read_b128 v[192:195], v151 offset:1024
	ds_read_b128 v[196:199], v151 offset:2048
	ds_read_b128 v[200:203], v151 offset:3072
	ds_read_b128 v[204:207], v151 offset:4096
	ds_read_b128 v[208:211], v151 offset:5120
	ds_read_b128 v[212:215], v151 offset:6144
	ds_read_b128 v[216:219], v151 offset:7168
	global_load_lds_dwordx4 v134, s[24:25]
	s_add_i32 m0, s34, 0xe000
	s_nop 0
	global_load_lds_dwordx4 v136, s[24:25]
	s_waitcnt vmcnt(8)
	s_waitcnt lgkmcnt(0)
	s_barrier
	s_setprio 1
	s_waitcnt lgkmcnt(0)
	v_mfma_f32_16x16x32_bf16 v[124:127], v[142:145], v[188:191], v[124:127]
	v_mfma_f32_16x16x32_bf16 v[120:123], v[156:159], v[188:191], v[120:123]
	v_mfma_f32_16x16x32_bf16 v[108:111], v[142:145], v[196:199], v[108:111]
	v_mfma_f32_16x16x32_bf16 v[104:107], v[156:159], v[196:199], v[104:107]
	v_mfma_f32_16x16x32_bf16 v[92:95], v[142:145], v[204:207], v[92:95]
	v_mfma_f32_16x16x32_bf16 v[88:91], v[156:159], v[204:207], v[88:91]
	v_mfma_f32_16x16x32_bf16 v[76:79], v[142:145], v[212:215], v[76:79]
	v_mfma_f32_16x16x32_bf16 v[72:75], v[156:159], v[212:215], v[72:75]
	v_mfma_f32_16x16x32_bf16 v[124:127], v[152:155], v[192:195], v[124:127]
	v_mfma_f32_16x16x32_bf16 v[120:123], v[160:163], v[192:195], v[120:123]
	v_mfma_f32_16x16x32_bf16 v[108:111], v[152:155], v[200:203], v[108:111]
	v_mfma_f32_16x16x32_bf16 v[104:107], v[160:163], v[200:203], v[104:107]
	v_mfma_f32_16x16x32_bf16 v[92:95], v[152:155], v[208:211], v[92:95]
	v_mfma_f32_16x16x32_bf16 v[88:91], v[160:163], v[208:211], v[88:91]
	v_mfma_f32_16x16x32_bf16 v[76:79], v[152:155], v[216:219], v[76:79]
	v_mfma_f32_16x16x32_bf16 v[72:75], v[160:163], v[216:219], v[72:75]
	s_setprio 0
	s_setprio 1
	v_mfma_f32_16x16x32_bf16 v[116:119], v[164:167], v[188:191], v[116:119]
	v_mfma_f32_16x16x32_bf16 v[112:115], v[180:183], v[188:191], v[112:115]
	v_mfma_f32_16x16x32_bf16 v[100:103], v[164:167], v[196:199], v[100:103]
	v_mfma_f32_16x16x32_bf16 v[96:99], v[180:183], v[196:199], v[96:99]
	v_mfma_f32_16x16x32_bf16 v[84:87], v[164:167], v[204:207], v[84:87]
	v_mfma_f32_16x16x32_bf16 v[80:83], v[180:183], v[204:207], v[80:83]
	v_mfma_f32_16x16x32_bf16 v[68:71], v[164:167], v[212:215], v[68:71]
	v_mfma_f32_16x16x32_bf16 v[64:67], v[180:183], v[212:215], v[64:67]
	v_mfma_f32_16x16x32_bf16 v[116:119], v[168:171], v[192:195], v[116:119]
	v_mfma_f32_16x16x32_bf16 v[112:115], v[184:187], v[192:195], v[112:115]
	v_mfma_f32_16x16x32_bf16 v[100:103], v[168:171], v[200:203], v[100:103]
	v_mfma_f32_16x16x32_bf16 v[96:99], v[184:187], v[200:203], v[96:99]
	v_mfma_f32_16x16x32_bf16 v[84:87], v[168:171], v[208:211], v[84:87]
	v_mfma_f32_16x16x32_bf16 v[80:83], v[184:187], v[208:211], v[80:83]
	v_mfma_f32_16x16x32_bf16 v[68:71], v[168:171], v[216:219], v[68:71]
	v_mfma_f32_16x16x32_bf16 v[64:67], v[184:187], v[216:219], v[64:67]
	s_setprio 0
	s_barrier
	s_add_i32 s52, s45, s33
	v_lshl_add_u64 v[220:221], s[26:27], 0, v[130:131]
	s_mov_b32 m0, s52
	ds_read_b128 v[188:191], v151 offset:16384
	ds_read_b128 v[192:195], v151 offset:17408
	ds_read_b128 v[196:199], v151 offset:18432
	ds_read_b128 v[200:203], v151 offset:19456
	ds_read_b128 v[204:207], v151 offset:20480
	ds_read_b128 v[208:211], v151 offset:21504
	ds_read_b128 v[212:215], v151 offset:22528
	ds_read_b128 v[216:219], v151 offset:23552
	global_load_lds_dwordx4 v[220:221], off
	s_add_i32 m0, s52, 0x2000
	s_add_u32 s52, s26, 0x80000
	v_lshl_add_u64 v[222:223], s[26:27], 0, v[132:133]
	s_addc_u32 s53, s27, 0
	s_add_i32 s54, s46, s33
	global_load_lds_dwordx4 v[222:223], off
	s_mov_b32 m0, s54
	v_lshl_add_u64 v[226:227], s[28:29], 0, v[132:133]
	global_load_lds_dwordx4 v130, s[52:53]
	s_add_i32 m0, s54, 0x2000
	s_nop 0
	global_load_lds_dwordx4 v132, s[52:53]
	v_lshl_add_u64 v[224:225], s[28:29], 0, v[130:131]
	s_mov_b32 m0, s34
	s_nop 0
	global_load_lds_dwordx4 v[224:225], off
	s_mov_b32 m0, s35
	s_nop 0
	global_load_lds_dwordx4 v[226:227], off
	s_waitcnt vmcnt(8)
	s_waitcnt lgkmcnt(0)
	s_barrier
; #define PG8_STAGE(bufoff, gbase, voff) do { _Pragma("unroll") for (int _i = 0; _i < 2; ++_i) \
;         __builtin_amdgcn_global_load_lds((const unsigned*)((const char*)(gbase) + (voff)[_i]), (PG8_LAS unsigned*)(lds + (bufoff) + ldsw + _i * 8192), 16, 0, 0); } while (0)
; #define PG8_LDA(dst, b, h) do { _Pragma("unroll") for (int m = 0; m < 4; ++m) _Pragma("unroll") for (int k = 0; k < 2; ++k) dst[m][k] = *(const PG8_LAS bf16x8*)(lds + PG8_SA(b, h) + aoff + m * 2048 + k * 1024); } while (0)
; #define PG8_LDB(dst, b, h) do { _Pragma("unroll") for (int n = 0; n < 2; ++n) _Pragma("unroll") for (int k = 0; k < 2; ++k) dst[n][k] = *(const PG8_LAS bf16x8*)(lds + PG8_SB(b, h) + boff + n * 2048 + k * 1024); } while (0)
; #define PG8_MMA(ai, bj, At, Bt) do { __builtin_amdgcn_s_setprio(1); _Pragma("unroll") for (int m = 0; m < 4; ++m) _Pragma("unroll") for (int n = 0; n < 2; ++n) _Pragma("unroll") for (int k = 0; k < 2; ++k) \
;         acc[ai][bj][m][n] = __builtin_amdgcn_mfma_f32_16x16x32_bf16(Bt[n][k], At[m][k], acc[ai][bj][m][n], 0, 0, 0); __builtin_amdgcn_s_setprio(0); } while (0)
; #define PG8_WAIT_V(n) asm volatile("s_waitcnt vmcnt(" #n ")" ::: "memory")
; #define PG8_WAIT_L(n) asm volatile("s_waitcnt lgkmcnt(" #n ")" ::: "memory")
; #define PG8_BAR __builtin_amdgcn_s_barrier()
; #define PG8_SCHED __builtin_amdgcn_sched_barrier(0)
; template <class Epi, class Sched, bool ALIGN_EPI = false, bool SP2 = false>
; __device__ __forceinline__ void gemm_phase(PG8_LAS unsigned char* lds, const Gemm g, const Sched& S, const Epi& E) {
;     ...
;             PG8_WAIT_V(8); PG8_WAIT_L(0); PG8_BAR; PG8_MMA(1, 0, At, B0); PG8_MMA(1, 1, At, B1); PG8_BAR; PG8_SCHED;
;             PG8_LDB(B0, 1, 0); PG8_LDB(B1, 1, 1); PG8_SCHED; PG8_LDA(At, 1, 0); PG8_STAGE(PG8_SA(0, 1), a2 + hstep, voffA);
;             PG8_WAIT_V(8); PG8_WAIT_L(0); PG8_BAR; PG8_MMA(0, 0, At, B0); PG8_MMA(0, 1, At, B1); PG8_BAR; PG8_SCHED;
	s_setprio 1
	s_waitcnt lgkmcnt(0)
	v_mfma_f32_16x16x32_bf16 v[60:63], v[142:145], v[188:191], v[60:63]
	v_mfma_f32_16x16x32_bf16 v[56:59], v[156:159], v[188:191], v[56:59]
	v_mfma_f32_16x16x32_bf16 v[44:47], v[142:145], v[196:199], v[44:47]
	v_mfma_f32_16x16x32_bf16 v[40:43], v[156:159], v[196:199], v[40:43]
	v_mfma_f32_16x16x32_bf16 v[28:31], v[142:145], v[204:207], v[28:31]
	v_mfma_f32_16x16x32_bf16 v[24:27], v[156:159], v[204:207], v[24:27]
	v_mfma_f32_16x16x32_bf16 v[12:15], v[142:145], v[212:215], v[12:15]
	v_mfma_f32_16x16x32_bf16 v[8:11], v[156:159], v[212:215], v[8:11]
	v_mfma_f32_16x16x32_bf16 v[60:63], v[152:155], v[192:195], v[60:63]
	v_mfma_f32_16x16x32_bf16 v[56:59], v[160:163], v[192:195], v[56:59]
	v_mfma_f32_16x16x32_bf16 v[44:47], v[152:155], v[200:203], v[44:47]
	v_mfma_f32_16x16x32_bf16 v[40:43], v[160:163], v[200:203], v[40:43]
	v_mfma_f32_16x16x32_bf16 v[28:31], v[152:155], v[208:211], v[28:31]
	v_mfma_f32_16x16x32_bf16 v[24:27], v[160:163], v[208:211], v[24:27]
	v_mfma_f32_16x16x32_bf16 v[12:15], v[152:155], v[216:219], v[12:15]
	v_mfma_f32_16x16x32_bf16 v[8:11], v[160:163], v[216:219], v[8:11]
	s_setprio 0
	s_setprio 1
	v_mfma_f32_16x16x32_bf16 v[52:55], v[164:167], v[188:191], v[52:55]
	v_mfma_f32_16x16x32_bf16 v[48:51], v[180:183], v[188:191], v[48:51]
	v_mfma_f32_16x16x32_bf16 v[36:39], v[164:167], v[196:199], v[36:39]
	v_mfma_f32_16x16x32_bf16 v[32:35], v[180:183], v[196:199], v[32:35]
	v_mfma_f32_16x16x32_bf16 v[20:23], v[164:167], v[204:207], v[20:23]
	v_mfma_f32_16x16x32_bf16 v[16:19], v[180:183], v[204:207], v[16:19]
	v_mfma_f32_16x16x32_bf16 v[4:7], v[164:167], v[212:215], v[4:7]
	v_mfma_f32_16x16x32_bf16 v[0:3], v[180:183], v[212:215], v[0:3]
	v_mfma_f32_16x16x32_bf16 v[52:55], v[168:171], v[192:195], v[52:55]
	v_mfma_f32_16x16x32_bf16 v[48:51], v[184:187], v[192:195], v[48:51]
	v_mfma_f32_16x16x32_bf16 v[36:39], v[168:171], v[200:203], v[36:39]
	v_mfma_f32_16x16x32_bf16 v[32:35], v[184:187], v[200:203], v[32:35]
	v_mfma_f32_16x16x32_bf16 v[20:23], v[168:171], v[208:211], v[20:23]
	v_mfma_f32_16x16x32_bf16 v[16:19], v[184:187], v[208:211], v[16:19]
	v_mfma_f32_16x16x32_bf16 v[4:7], v[168:171], v[216:219], v[4:7]
	v_mfma_f32_16x16x32_bf16 v[0:3], v[184:187], v[216:219], v[0:3]
	s_setprio 0
	s_barrier
	s_add_i32 s52, 0, 0x18000
	s_add_i32 s53, 0, 0x1c000
	v_add_u32_e32 v160, s52, v147
	v_add_u32_e32 v179, s53, v147
	ds_read_b128 v[142:145], v160
	ds_read_b128 v[152:155], v160 offset:1024
	ds_read_b128 v[156:159], v160 offset:2048
	ds_read_b128 v[160:163], v160 offset:3072
	ds_read_b128 v[164:167], v179
	ds_read_b128 v[168:171], v179 offset:1024
	ds_read_b128 v[180:183], v179 offset:2048
	ds_read_b128 v[184:187], v179 offset:3072
	s_add_u32 s28, s28, 0x80000
	s_addc_u32 s29, s29, 0
	s_mov_b32 m0, s36
	ds_read_b128 v[188:191], v151 offset:32768
	ds_read_b128 v[192:195], v151 offset:33792
	ds_read_b128 v[196:199], v151 offset:34816
	ds_read_b128 v[200:203], v151 offset:35840
	ds_read_b128 v[204:207], v151 offset:36864
	ds_read_b128 v[208:211], v151 offset:37888
	ds_read_b128 v[212:215], v151 offset:38912
	ds_read_b128 v[216:219], v151 offset:39936
	global_load_lds_dwordx4 v130, s[28:29]
	s_mov_b32 m0, s37
	s_nop 0
	global_load_lds_dwordx4 v132, s[28:29]
	s_waitcnt vmcnt(8)
	s_waitcnt lgkmcnt(0)
	s_barrier
	s_setprio 1
	s_waitcnt lgkmcnt(0)
	v_mfma_f32_16x16x32_bf16 v[124:127], v[142:145], v[188:191], v[124:127]
	v_mfma_f32_16x16x32_bf16 v[120:123], v[156:159], v[188:191], v[120:123]
	v_mfma_f32_16x16x32_bf16 v[108:111], v[142:145], v[196:199], v[108:111]
	v_mfma_f32_16x16x32_bf16 v[104:107], v[156:159], v[196:199], v[104:107]
	v_mfma_f32_16x16x32_bf16 v[92:95], v[142:145], v[204:207], v[92:95]
	v_mfma_f32_16x16x32_bf16 v[88:91], v[156:159], v[204:207], v[88:91]
	v_mfma_f32_16x16x32_bf16 v[76:79], v[142:145], v[212:215], v[76:79]
	v_mfma_f32_16x16x32_bf16 v[72:75], v[156:159], v[212:215], v[72:75]
	v_mfma_f32_16x16x32_bf16 v[124:127], v[152:155], v[192:195], v[124:127]
	v_mfma_f32_16x16x32_bf16 v[120:123], v[160:163], v[192:195], v[120:123]
	v_mfma_f32_16x16x32_bf16 v[108:111], v[152:155], v[200:203], v[108:111]
	v_mfma_f32_16x16x32_bf16 v[104:107], v[160:163], v[200:203], v[104:107]
	v_mfma_f32_16x16x32_bf16 v[92:95], v[152:155], v[208:211], v[92:95]
	v_mfma_f32_16x16x32_bf16 v[88:91], v[160:163], v[208:211], v[88:91]
	v_mfma_f32_16x16x32_bf16 v[76:79], v[152:155], v[216:219], v[76:79]
	v_mfma_f32_16x16x32_bf16 v[72:75], v[160:163], v[216:219], v[72:75]
	s_setprio 0
	s_setprio 1
	v_mfma_f32_16x16x32_bf16 v[116:119], v[164:167], v[188:191], v[116:119]
	v_mfma_f32_16x16x32_bf16 v[112:115], v[180:183], v[188:191], v[112:115]
	v_mfma_f32_16x16x32_bf16 v[100:103], v[164:167], v[196:199], v[100:103]
	v_mfma_f32_16x16x32_bf16 v[96:99], v[180:183], v[196:199], v[96:99]
	v_mfma_f32_16x16x32_bf16 v[84:87], v[164:167], v[204:207], v[84:87]
	v_mfma_f32_16x16x32_bf16 v[80:83], v[180:183], v[204:207], v[80:83]
	v_mfma_f32_16x16x32_bf16 v[68:71], v[164:167], v[212:215], v[68:71]
	v_mfma_f32_16x16x32_bf16 v[64:67], v[180:183], v[212:215], v[64:67]
	v_mfma_f32_16x16x32_bf16 v[116:119], v[168:171], v[192:195], v[116:119]
	v_mfma_f32_16x16x32_bf16 v[112:115], v[184:187], v[192:195], v[112:115]
	v_mfma_f32_16x16x32_bf16 v[100:103], v[168:171], v[200:203], v[100:103]
	v_mfma_f32_16x16x32_bf16 v[96:99], v[184:187], v[200:203], v[96:99]
	v_mfma_f32_16x16x32_bf16 v[84:87], v[168:171], v[208:211], v[84:87]
	v_mfma_f32_16x16x32_bf16 v[80:83], v[184:187], v[208:211], v[80:83]
	v_mfma_f32_16x16x32_bf16 v[68:71], v[168:171], v[216:219], v[68:71]
	v_mfma_f32_16x16x32_bf16 v[64:67], v[184:187], v[216:219], v[64:67]
	s_setprio 0
	s_barrier
; #define PG8_STAGE(bufoff, gbase, voff) do { _Pragma("unroll") for (int _i = 0; _i < 2; ++_i) \
;         __builtin_amdgcn_global_load_lds((const unsigned*)((const char*)(gbase) + (voff)[_i]), (PG8_LAS unsigned*)(lds + (bufoff) + ldsw + _i * 8192), 16, 0, 0); } while (0)
; #define PG8_LDA(dst, b, h) do { _Pragma("unroll") for (int m = 0; m < 4; ++m) _Pragma("unroll") for (int k = 0; k < 2; ++k) dst[m][k] = *(const PG8_LAS bf16x8*)(lds + PG8_SA(b, h) + aoff + m * 2048 + k * 1024); } while (0)
; #define PG8_MMA(ai, bj, At, Bt) do { __builtin_amdgcn_s_setprio(1); _Pragma("unroll") for (int m = 0; m < 4; ++m) _Pragma("unroll") for (int n = 0; n < 2; ++n) _Pragma("unroll") for (int k = 0; k < 2; ++k) \
;         acc[ai][bj][m][n] = __builtin_amdgcn_mfma_f32_16x16x32_bf16(Bt[n][k], At[m][k], acc[ai][bj][m][n], 0, 0, 0); __builtin_amdgcn_s_setprio(0); } while (0)
; #define PG8_WAIT_V(n) asm volatile("s_waitcnt vmcnt(" #n ")" ::: "memory")
; #define PG8_WAIT_L(n) asm volatile("s_waitcnt lgkmcnt(" #n ")" ::: "memory")
; #define PG8_BAR __builtin_amdgcn_s_barrier()
; #define PG8_SCHED __builtin_amdgcn_sched_barrier(0)
; template <class Epi, class Sched, bool ALIGN_EPI = false, bool SP2 = false>
; __device__ __forceinline__ void gemm_phase(PG8_LAS unsigned char* lds, const Gemm g, const Sched& S, const Epi& E) {
;     ...
;         for (int t = 0; t < nt; t += 2) {
;     ...
;             PG8_LDA(At, 1, 1); PG8_STAGE(PG8_SB(1, 0), b3, voffB); PG8_STAGE(PG8_SB(1, 1), b3 + hstep, voffB); PG8_STAGE(PG8_SA(1, 0), a3, voffA);
;             PG8_WAIT_V(8); PG8_WAIT_L(0); PG8_BAR; PG8_MMA(1, 0, At, B0); PG8_MMA(1, 1, At, B1); PG8_BAR; PG8_SCHED;
	s_add_i32 s28, s52, s33
	v_lshl_add_u64 v[220:221], v[220:221], 0, s[4:5]
	s_mov_b32 m0, s28
	ds_read_b128 v[188:191], v151 offset:49152
	ds_read_b128 v[192:195], v151 offset:50176
	ds_read_b128 v[196:199], v151 offset:51200
	ds_read_b128 v[200:203], v151 offset:52224
	ds_read_b128 v[204:207], v151 offset:53248
	ds_read_b128 v[208:211], v151 offset:54272
	ds_read_b128 v[212:215], v151 offset:55296
	ds_read_b128 v[216:219], v151 offset:56320
	global_load_lds_dwordx4 v[220:221], off
	s_add_i32 m0, s28, 0x2000
	s_add_u32 s26, s26, 0x80080
	v_lshl_add_u64 v[220:221], v[222:223], 0, s[4:5]
	s_addc_u32 s27, s27, 0
	s_add_i32 s28, s53, s33
	global_load_lds_dwordx4 v[220:221], off
	s_mov_b32 m0, s28
	s_nop 0
	global_load_lds_dwordx4 v130, s[26:27]
	s_add_i32 m0, s28, 0x2000
	s_nop 0
	global_load_lds_dwordx4 v132, s[26:27]
	v_lshl_add_u64 v[220:221], v[224:225], 0, s[4:5]
	s_mov_b32 m0, s41
	s_nop 0
	global_load_lds_dwordx4 v[220:221], off
	v_lshl_add_u64 v[220:221], v[226:227], 0, s[4:5]
	s_mov_b32 m0, s44
	s_nop 0
	global_load_lds_dwordx4 v[220:221], off
	s_waitcnt vmcnt(8)
	s_waitcnt lgkmcnt(0)
	s_barrier
	s_setprio 1
	s_waitcnt lgkmcnt(0)
	v_mfma_f32_16x16x32_bf16 v[60:63], v[142:145], v[188:191], v[60:63]
	v_mfma_f32_16x16x32_bf16 v[56:59], v[156:159], v[188:191], v[56:59]
	v_mfma_f32_16x16x32_bf16 v[44:47], v[142:145], v[196:199], v[44:47]
	v_mfma_f32_16x16x32_bf16 v[40:43], v[156:159], v[196:199], v[40:43]
	v_mfma_f32_16x16x32_bf16 v[28:31], v[142:145], v[204:207], v[28:31]
	v_mfma_f32_16x16x32_bf16 v[24:27], v[156:159], v[204:207], v[24:27]
	v_mfma_f32_16x16x32_bf16 v[12:15], v[142:145], v[212:215], v[12:15]
	v_mfma_f32_16x16x32_bf16 v[8:11], v[156:159], v[212:215], v[8:11]
	v_mfma_f32_16x16x32_bf16 v[60:63], v[152:155], v[192:195], v[60:63]
	v_mfma_f32_16x16x32_bf16 v[56:59], v[160:163], v[192:195], v[56:59]
	v_mfma_f32_16x16x32_bf16 v[44:47], v[152:155], v[200:203], v[44:47]
	v_mfma_f32_16x16x32_bf16 v[40:43], v[160:163], v[200:203], v[40:43]
	v_mfma_f32_16x16x32_bf16 v[28:31], v[152:155], v[208:211], v[28:31]
	v_mfma_f32_16x16x32_bf16 v[24:27], v[160:163], v[208:211], v[24:27]
	v_mfma_f32_16x16x32_bf16 v[12:15], v[152:155], v[216:219], v[12:15]
	v_mfma_f32_16x16x32_bf16 v[8:11], v[160:163], v[216:219], v[8:11]
	s_setprio 0
	s_setprio 1
	v_mfma_f32_16x16x32_bf16 v[52:55], v[164:167], v[188:191], v[52:55]
	v_mfma_f32_16x16x32_bf16 v[48:51], v[180:183], v[188:191], v[48:51]
	v_mfma_f32_16x16x32_bf16 v[36:39], v[164:167], v[196:199], v[36:39]
	v_mfma_f32_16x16x32_bf16 v[32:35], v[180:183], v[196:199], v[32:35]
	v_mfma_f32_16x16x32_bf16 v[20:23], v[164:167], v[204:207], v[20:23]
	v_mfma_f32_16x16x32_bf16 v[16:19], v[180:183], v[204:207], v[16:19]
	v_mfma_f32_16x16x32_bf16 v[4:7], v[164:167], v[212:215], v[4:7]
	v_mfma_f32_16x16x32_bf16 v[0:3], v[180:183], v[212:215], v[0:3]
	v_mfma_f32_16x16x32_bf16 v[52:55], v[168:171], v[192:195], v[52:55]
	v_mfma_f32_16x16x32_bf16 v[48:51], v[184:187], v[192:195], v[48:51]
	v_mfma_f32_16x16x32_bf16 v[36:39], v[168:171], v[200:203], v[36:39]
	v_mfma_f32_16x16x32_bf16 v[32:35], v[184:187], v[200:203], v[32:35]
	v_mfma_f32_16x16x32_bf16 v[20:23], v[168:171], v[208:211], v[20:23]
	v_mfma_f32_16x16x32_bf16 v[16:19], v[184:187], v[208:211], v[16:19]
	v_mfma_f32_16x16x32_bf16 v[4:7], v[168:171], v[216:219], v[4:7]
	v_mfma_f32_16x16x32_bf16 v[0:3], v[184:187], v[216:219], v[0:3]
	s_setprio 0
	s_barrier
	s_add_i32 s51, s51, 2
	s_add_u32 s24, s24, 0x100
	s_addc_u32 s25, s25, 0
	s_add_u32 s49, s49, 0x100
	s_addc_u32 s50, s50, 0
	s_cmp_gt_u32 s51, 29
	s_cbranch_scc0 .LBB0_585
	s_nop 0
	v_readfirstlane_b32 s23, v172
	s_nop 3
	s_lshr_b32 s23, s23, 6
	s_cmp_lt_u32 s23, 4
	s_cbranch_scc0 .Lprio_k1
	s_setprio 1

; #define PG8_STAGE(bufoff, gbase, voff) do { _Pragma("unroll") for (int _i = 0; _i < 2; ++_i) \
;         __builtin_amdgcn_global_load_lds((const unsigned*)((const char*)(gbase) + (voff)[_i]), (PG8_LAS unsigned*)(lds + (bufoff) + ldsw + _i * 8192), 16, 0, 0); } while (0)
; #define PG8_WAIT_V(n) asm volatile("s_waitcnt vmcnt(" #n ")" ::: "memory")
; #define PG8_BAR __builtin_amdgcn_s_barrier()
; template <class Epi, class Sched, bool ALIGN_EPI = false, bool SP2 = false>
; __device__ __forceinline__ void gemm_phase(PG8_LAS unsigned char* lds, const Gemm g, const Sched& S, const Epi& E) {
;     ...
;     for (int i = 0; i < 2; ++i) { int R, C; stage_rc(tid * 16 + i * 8192, R, C); const int Rb = Epi::PERM ? ((R & ~31) + perm32(R & 31)) : R;
;         voffA[i] = (unsigned)(R * K + C) * 2u; voffB[i] = (unsigned)(Rb * K + C) * 2u; }
;     const size_t kstep = (size_t)(BK * 2);
;     const size_t hstep = (size_t)HALF * K * 2;
;     const size_t tstep = 2 * hstep;
;     const unsigned ldsw = (unsigned)wid * 1024u;
;     const int aoff = lds_byte(wr * 64 + fr, fq * 8), boff = lds_byte(wc * 32 + fr, fq * 8);
;     ...
;         PG8_STAGE(PG8_SB(1, 0), cB + kstep, voffB); PG8_STAGE(PG8_SA(1, 0), cA + kstep, voffA); PG8_STAGE(PG8_SB(1, 1), cB + hstep + kstep, voffB);
;         PG8_WAIT_V(6); PG8_BAR;
.LBB0_831:
	v_and_b32_e32 v15, 15, v14
	v_lshrrev_b32_e32 v14, 1, v14
	v_and_b32_e32 v14, 24, v14
	s_waitcnt vmcnt(0)
	v_lshlrev_b32_e32 v16, 1, v14
	v_lshl_or_b32 v154, s6, 6, v15
	v_lshl_or_b32 v16, v15, 6, v16
	v_lshlrev_b32_e32 v15, 2, v15
	s_sext_i32_i16 s45, s2
	s_lshl_b32 s2, s6, 13
	v_and_b32_e32 v17, 32, v15
	v_bitop3_b32 v18, v16, s2, v17 bitop3:0xde
	s_lshl_b32 s2, s3, 5
	s_and_b32 s7, s2, 0x60
	s_lshl_b32 s2, s7, 7
	v_bitop3_b32 v155, v16, s2, v17 bitop3:0xde
	s_mov_b64 s[2:3], 0x80
	s_add_i32 m0, s30, 0x18000
	v_lshl_add_u64 v[6:7], v[6:7], 0, s[2:3]
	s_waitcnt vmcnt(2)
	s_barrier
	global_load_lds_dwordx4 v[6:7], off
	v_lshl_add_u64 v[4:5], v[4:5], 0, s[2:3]
	s_add_i32 m0, s30, 0x1a000
	s_add_i32 s35, s30, 0x8000
	s_add_i32 s36, s30, 0xa000
	global_load_lds_dwordx4 v[4:5], off
	v_lshl_add_u64 v[0:1], v[0:1], 0, s[2:3]
	s_mov_b32 m0, s35
	s_add_u32 s8, s22, 0x80080
	global_load_lds_dwordx4 v[0:1], off
	v_lshl_add_u64 v[0:1], v[2:3], 0, s[2:3]
	s_mov_b32 m0, s36
	s_addc_u32 s9, s23, 0
	global_load_lds_dwordx4 v[0:1], off
	s_add_i32 m0, s30, 0x1c000
	s_nop 0
	global_load_lds_dwordx4 v134, s[8:9]
	s_add_i32 m0, s30, 0x1e000
	s_cmpk_lt_u32 s4, 0x100
	global_load_lds_dwordx4 v130, s[8:9]
	v_lshlrev_b32_e32 v0, 15, v12
	v_and_b32_e32 v0, 0xffff0000, v0
	v_lshl_add_u32 v0, v11, 12, v0
	v_and_b32_e32 v1, 1, v12
	v_lshl_or_b32 v0, v1, 6, v0
	v_lshl_add_u32 v138, v13, 1, v0
	v_lshlrev_b32_e32 v0, 15, v8
	s_cselect_b64 s[4:5], -1, 0
	s_lshl_b32 s6, s6, 8
	v_and_b32_e32 v0, 0xffff0000, v0
	s_waitcnt vmcnt(6)
	s_add_i32 s6, s6, 0
	v_lshl_add_u32 v0, v9, 12, v0
	v_and_b32_e32 v1, 1, v8
	s_add_i32 s6, s6, 0x20000
	v_lshl_or_b32 v0, v1, 6, v0
	s_add_i32 s37, 0, 0x10000
	s_add_i32 s40, 0, 0x14000
	v_add_u32_e32 v156, s6, v15
	v_or_b32_e32 v157, s7, v14
	v_mov_b32_e32 v139, v135
	v_lshl_add_u32 v140, v10, 1, v0
	v_mov_b32_e32 v141, v135
	v_mov_b64_e32 v[142:143], 0x580
	v_mov_b64_e32 v[144:145], 0x57f
	v_add_u32_e32 v158, s37, v155
	v_add_u32_e32 v159, s40, v155
	v_add_u32_e32 v160, 0, v18
	s_movk_i32 s41, 0x2c00
	s_barrier
	s_branch .LBB0_834

; #define PG8_STAGE(bufoff, gbase, voff) do { _Pragma("unroll") for (int _i = 0; _i < 2; ++_i) \
;         __builtin_amdgcn_global_load_lds((const unsigned*)((const char*)(gbase) + (voff)[_i]), (PG8_LAS unsigned*)(lds + (bufoff) + ldsw + _i * 8192), 16, 0, 0); } while (0)
; #define PG8_LDA(dst, b, h) do { _Pragma("unroll") for (int m = 0; m < 4; ++m) _Pragma("unroll") for (int k = 0; k < 2; ++k) dst[m][k] = *(const PG8_LAS bf16x8*)(lds + PG8_SA(b, h) + aoff + m * 2048 + k * 1024); } while (0)
; #define PG8_LDB(dst, b, h) do { _Pragma("unroll") for (int n = 0; n < 2; ++n) _Pragma("unroll") for (int k = 0; k < 2; ++k) dst[n][k] = *(const PG8_LAS bf16x8*)(lds + PG8_SB(b, h) + boff + n * 2048 + k * 1024); } while (0)
; #define PG8_MMA(ai, bj, At, Bt) do { __builtin_amdgcn_s_setprio(1); _Pragma("unroll") for (int m = 0; m < 4; ++m) _Pragma("unroll") for (int n = 0; n < 2; ++n) _Pragma("unroll") for (int k = 0; k < 2; ++k) \
;         acc[ai][bj][m][n] = __builtin_amdgcn_mfma_f32_16x16x32_bf16(Bt[n][k], At[m][k], acc[ai][bj][m][n], 0, 0, 0); __builtin_amdgcn_s_setprio(0); } while (0)
; #define PG8_WAIT_V(n) asm volatile("s_waitcnt vmcnt(" #n ")" ::: "memory")
; #define PG8_WAIT_L(n) asm volatile("s_waitcnt lgkmcnt(" #n ")" ::: "memory")
; #define PG8_BAR __builtin_amdgcn_s_barrier()
; #define PG8_SCHED __builtin_amdgcn_sched_barrier(0)
; template <class Epi, class Sched, bool ALIGN_EPI = false, bool SP2 = false>
; __device__ __forceinline__ void gemm_phase(PG8_LAS unsigned char* lds, const Gemm g, const Sched& S, const Epi& E) {
;     ...
;             PG8_LDB(B0, 0, 0); PG8_LDB(B1, 0, 1); PG8_SCHED; PG8_LDA(At, 0, 0); PG8_STAGE(PG8_SA(1, 1), a1 + hstep, voffA);
;             PG8_WAIT_V(8); PG8_WAIT_L(0); PG8_BAR; PG8_MMA(0, 0, At, B0); PG8_MMA(0, 1, At, B1); PG8_BAR; PG8_SCHED;
;             PG8_LDA(At, 0, 1); PG8_STAGE(PG8_SB(0, 0), b2, voffB); PG8_STAGE(PG8_SB(0, 1), b2 + hstep, voffB); PG8_STAGE(PG8_SA(0, 0), a2, voffA);
;             PG8_WAIT_V(8); PG8_WAIT_L(0); PG8_BAR; PG8_MMA(1, 0, At, B0); PG8_MMA(1, 1, At, B1); PG8_BAR; PG8_SCHED;
.LBB0_837:
	ds_read_b128 v[146:149], v158
	ds_read_b128 v[150:153], v158 offset:1024
	ds_read_b128 v[162:165], v158 offset:2048
	ds_read_b128 v[166:169], v158 offset:3072
	ds_read_b128 v[180:183], v159
	ds_read_b128 v[184:187], v159 offset:1024
	ds_read_b128 v[188:191], v159 offset:2048
	ds_read_b128 v[192:195], v159 offset:3072
	s_add_u32 s22, s20, 0xfff80080
	s_addc_u32 s23, s21, -1
	s_cmp_eq_u32 s50, 28
	s_cselect_b32 s25, s11, s23
	s_cselect_b32 s24, s46, s22
	s_cselect_b32 s23, s7, s49
	s_cselect_b32 s22, s47, s48
	s_add_i32 m0, s30, 0xc000
	ds_read_b128 v[196:199], v160
	ds_read_b128 v[200:203], v160 offset:1024
	ds_read_b128 v[204:207], v160 offset:2048
	ds_read_b128 v[208:211], v160 offset:3072
	ds_read_b128 v[212:215], v160 offset:4096
	ds_read_b128 v[216:219], v160 offset:5120
	ds_read_b128 v[220:223], v160 offset:6144
	ds_read_b128 v[224:227], v160 offset:7168
	global_load_lds_dwordx4 v138, s[20:21]
	s_add_i32 m0, s30, 0xe000
	s_nop 0
	global_load_lds_dwordx4 v140, s[20:21]
	s_waitcnt vmcnt(8)
	s_waitcnt lgkmcnt(0)
	s_barrier
	s_setprio 1
	s_waitcnt lgkmcnt(0)
	v_mfma_f32_16x16x32_bf16 v[124:127], v[146:149], v[196:199], v[124:127]
	v_mfma_f32_16x16x32_bf16 v[116:119], v[162:165], v[196:199], v[116:119]
	v_mfma_f32_16x16x32_bf16 v[108:111], v[146:149], v[204:207], v[108:111]
	v_mfma_f32_16x16x32_bf16 v[100:103], v[162:165], v[204:207], v[100:103]
	v_mfma_f32_16x16x32_bf16 v[92:95], v[146:149], v[212:215], v[92:95]
	v_mfma_f32_16x16x32_bf16 v[84:87], v[162:165], v[212:215], v[84:87]
	v_mfma_f32_16x16x32_bf16 v[76:79], v[146:149], v[220:223], v[76:79]
	v_mfma_f32_16x16x32_bf16 v[68:71], v[162:165], v[220:223], v[68:71]
	v_mfma_f32_16x16x32_bf16 v[124:127], v[150:153], v[200:203], v[124:127]
	v_mfma_f32_16x16x32_bf16 v[116:119], v[166:169], v[200:203], v[116:119]
	v_mfma_f32_16x16x32_bf16 v[108:111], v[150:153], v[208:211], v[108:111]
	v_mfma_f32_16x16x32_bf16 v[100:103], v[166:169], v[208:211], v[100:103]
	v_mfma_f32_16x16x32_bf16 v[92:95], v[150:153], v[216:219], v[92:95]
	v_mfma_f32_16x16x32_bf16 v[84:87], v[166:169], v[216:219], v[84:87]
	v_mfma_f32_16x16x32_bf16 v[76:79], v[150:153], v[224:227], v[76:79]
	v_mfma_f32_16x16x32_bf16 v[68:71], v[166:169], v[224:227], v[68:71]
	s_setprio 0
	s_setprio 1
	v_mfma_f32_16x16x32_bf16 v[120:123], v[180:183], v[196:199], v[120:123]
	v_mfma_f32_16x16x32_bf16 v[112:115], v[188:191], v[196:199], v[112:115]
	v_mfma_f32_16x16x32_bf16 v[104:107], v[180:183], v[204:207], v[104:107]
	v_mfma_f32_16x16x32_bf16 v[96:99], v[188:191], v[204:207], v[96:99]
	v_mfma_f32_16x16x32_bf16 v[88:91], v[180:183], v[212:215], v[88:91]
	v_mfma_f32_16x16x32_bf16 v[80:83], v[188:191], v[212:215], v[80:83]
	v_mfma_f32_16x16x32_bf16 v[72:75], v[180:183], v[220:223], v[72:75]
	v_mfma_f32_16x16x32_bf16 v[64:67], v[188:191], v[220:223], v[64:67]
	v_mfma_f32_16x16x32_bf16 v[120:123], v[184:187], v[200:203], v[120:123]
	v_mfma_f32_16x16x32_bf16 v[112:115], v[192:195], v[200:203], v[112:115]
	v_mfma_f32_16x16x32_bf16 v[104:107], v[184:187], v[208:211], v[104:107]
	v_mfma_f32_16x16x32_bf16 v[96:99], v[192:195], v[208:211], v[96:99]
	v_mfma_f32_16x16x32_bf16 v[88:91], v[184:187], v[216:219], v[88:91]
	v_mfma_f32_16x16x32_bf16 v[80:83], v[192:195], v[216:219], v[80:83]
	v_mfma_f32_16x16x32_bf16 v[72:75], v[184:187], v[224:227], v[72:75]
	v_mfma_f32_16x16x32_bf16 v[64:67], v[192:195], v[224:227], v[64:67]
	s_setprio 0
	s_barrier
	s_add_i32 s51, s37, s26
	v_lshl_add_u64 v[170:171], s[22:23], 0, v[134:135]
	s_mov_b32 m0, s51
	ds_read_b128 v[196:199], v160 offset:16384
	ds_read_b128 v[200:203], v160 offset:17408
	ds_read_b128 v[204:207], v160 offset:18432
	ds_read_b128 v[208:211], v160 offset:19456
	ds_read_b128 v[212:215], v160 offset:20480
	ds_read_b128 v[216:219], v160 offset:21504
	ds_read_b128 v[220:223], v160 offset:22528
	ds_read_b128 v[224:227], v160 offset:23552
	global_load_lds_dwordx4 v[170:171], off
	s_add_i32 m0, s51, 0x2000
	s_add_u32 s52, s22, 0x80000
	v_lshl_add_u64 v[228:229], s[22:23], 0, v[130:131]
	s_addc_u32 s53, s23, 0
	s_add_i32 s51, s40, s26
	global_load_lds_dwordx4 v[228:229], off
	s_mov_b32 m0, s51
	v_lshl_add_u64 v[232:233], s[24:25], 0, v[132:133]
	global_load_lds_dwordx4 v134, s[52:53]
	s_add_i32 m0, s51, 0x2000
	s_nop 0
	global_load_lds_dwordx4 v130, s[52:53]
	v_lshl_add_u64 v[230:231], s[24:25], 0, v[136:137]
	s_mov_b32 m0, s30
	s_nop 0
	global_load_lds_dwordx4 v[230:231], off
	s_mov_b32 m0, s31
	s_nop 0
	global_load_lds_dwordx4 v[232:233], off
	s_waitcnt vmcnt(8)
	s_waitcnt lgkmcnt(0)
	s_barrier
; #define PG8_STAGE(bufoff, gbase, voff) do { _Pragma("unroll") for (int _i = 0; _i < 2; ++_i) \
;         __builtin_amdgcn_global_load_lds((const unsigned*)((const char*)(gbase) + (voff)[_i]), (PG8_LAS unsigned*)(lds + (bufoff) + ldsw + _i * 8192), 16, 0, 0); } while (0)
; #define PG8_LDA(dst, b, h) do { _Pragma("unroll") for (int m = 0; m < 4; ++m) _Pragma("unroll") for (int k = 0; k < 2; ++k) dst[m][k] = *(const PG8_LAS bf16x8*)(lds + PG8_SA(b, h) + aoff + m * 2048 + k * 1024); } while (0)
; #define PG8_LDB(dst, b, h) do { _Pragma("unroll") for (int n = 0; n < 2; ++n) _Pragma("unroll") for (int k = 0; k < 2; ++k) dst[n][k] = *(const PG8_LAS bf16x8*)(lds + PG8_SB(b, h) + boff + n * 2048 + k * 1024); } while (0)
; #define PG8_MMA(ai, bj, At, Bt) do { __builtin_amdgcn_s_setprio(1); _Pragma("unroll") for (int m = 0; m < 4; ++m) _Pragma("unroll") for (int n = 0; n < 2; ++n) _Pragma("unroll") for (int k = 0; k < 2; ++k) \
;         acc[ai][bj][m][n] = __builtin_amdgcn_mfma_f32_16x16x32_bf16(Bt[n][k], At[m][k], acc[ai][bj][m][n], 0, 0, 0); __builtin_amdgcn_s_setprio(0); } while (0)
; #define PG8_WAIT_V(n) asm volatile("s_waitcnt vmcnt(" #n ")" ::: "memory")
; #define PG8_WAIT_L(n) asm volatile("s_waitcnt lgkmcnt(" #n ")" ::: "memory")
; #define PG8_BAR __builtin_amdgcn_s_barrier()
; #define PG8_SCHED __builtin_amdgcn_sched_barrier(0)
; template <class Epi, class Sched, bool ALIGN_EPI = false, bool SP2 = false>
; __device__ __forceinline__ void gemm_phase(PG8_LAS unsigned char* lds, const Gemm g, const Sched& S, const Epi& E) {
;     ...
;             PG8_WAIT_V(8); PG8_WAIT_L(0); PG8_BAR; PG8_MMA(1, 0, At, B0); PG8_MMA(1, 1, At, B1); PG8_BAR; PG8_SCHED;
;             PG8_LDB(B0, 1, 0); PG8_LDB(B1, 1, 1); PG8_SCHED; PG8_LDA(At, 1, 0); PG8_STAGE(PG8_SA(0, 1), a2 + hstep, voffA);
;             PG8_WAIT_V(8); PG8_WAIT_L(0); PG8_BAR; PG8_MMA(0, 0, At, B0); PG8_MMA(0, 1, At, B1); PG8_BAR; PG8_SCHED;
	s_setprio 1
	s_waitcnt lgkmcnt(0)
	v_mfma_f32_16x16x32_bf16 v[60:63], v[146:149], v[196:199], v[60:63]
	v_mfma_f32_16x16x32_bf16 v[52:55], v[162:165], v[196:199], v[52:55]
	v_mfma_f32_16x16x32_bf16 v[44:47], v[146:149], v[204:207], v[44:47]
	v_mfma_f32_16x16x32_bf16 v[36:39], v[162:165], v[204:207], v[36:39]
	v_mfma_f32_16x16x32_bf16 v[28:31], v[146:149], v[212:215], v[28:31]
	v_mfma_f32_16x16x32_bf16 v[20:23], v[162:165], v[212:215], v[20:23]
	v_mfma_f32_16x16x32_bf16 v[12:15], v[146:149], v[220:223], v[12:15]
	v_mfma_f32_16x16x32_bf16 v[4:7], v[162:165], v[220:223], v[4:7]
	v_mfma_f32_16x16x32_bf16 v[60:63], v[150:153], v[200:203], v[60:63]
	v_mfma_f32_16x16x32_bf16 v[52:55], v[166:169], v[200:203], v[52:55]
	v_mfma_f32_16x16x32_bf16 v[44:47], v[150:153], v[208:211], v[44:47]
	v_mfma_f32_16x16x32_bf16 v[36:39], v[166:169], v[208:211], v[36:39]
	v_mfma_f32_16x16x32_bf16 v[28:31], v[150:153], v[216:219], v[28:31]
	v_mfma_f32_16x16x32_bf16 v[20:23], v[166:169], v[216:219], v[20:23]
	v_mfma_f32_16x16x32_bf16 v[12:15], v[150:153], v[224:227], v[12:15]
	v_mfma_f32_16x16x32_bf16 v[4:7], v[166:169], v[224:227], v[4:7]
	s_setprio 0
	s_setprio 1
	v_mfma_f32_16x16x32_bf16 v[56:59], v[180:183], v[196:199], v[56:59]
	v_mfma_f32_16x16x32_bf16 v[48:51], v[188:191], v[196:199], v[48:51]
	v_mfma_f32_16x16x32_bf16 v[40:43], v[180:183], v[204:207], v[40:43]
	v_mfma_f32_16x16x32_bf16 v[32:35], v[188:191], v[204:207], v[32:35]
	v_mfma_f32_16x16x32_bf16 v[24:27], v[180:183], v[212:215], v[24:27]
	v_mfma_f32_16x16x32_bf16 v[16:19], v[188:191], v[212:215], v[16:19]
	v_mfma_f32_16x16x32_bf16 v[8:11], v[180:183], v[220:223], v[8:11]
	v_mfma_f32_16x16x32_bf16 v[0:3], v[188:191], v[220:223], v[0:3]
	v_mfma_f32_16x16x32_bf16 v[56:59], v[184:187], v[200:203], v[56:59]
	v_mfma_f32_16x16x32_bf16 v[48:51], v[192:195], v[200:203], v[48:51]
	v_mfma_f32_16x16x32_bf16 v[40:43], v[184:187], v[208:211], v[40:43]
	v_mfma_f32_16x16x32_bf16 v[32:35], v[192:195], v[208:211], v[32:35]
	v_mfma_f32_16x16x32_bf16 v[24:27], v[184:187], v[216:219], v[24:27]
	v_mfma_f32_16x16x32_bf16 v[16:19], v[192:195], v[216:219], v[16:19]
	v_mfma_f32_16x16x32_bf16 v[8:11], v[184:187], v[224:227], v[8:11]
	v_mfma_f32_16x16x32_bf16 v[0:3], v[192:195], v[224:227], v[0:3]
	s_setprio 0
	s_barrier
	s_add_i32 s51, 0, 0x18000
	v_add_u32_e32 v161, s51, v155
	s_add_i32 s52, 0, 0x1c000
	ds_read_b128 v[146:149], v161
	ds_read_b128 v[150:153], v161 offset:1024
	ds_read_b128 v[162:165], v161 offset:2048
	ds_read_b128 v[166:169], v161 offset:3072
	v_add_u32_e32 v161, s52, v155
	ds_read_b128 v[180:183], v161
	ds_read_b128 v[184:187], v161 offset:1024
	ds_read_b128 v[188:191], v161 offset:2048
	ds_read_b128 v[192:195], v161 offset:3072
	s_add_u32 s24, s24, 0x80000
	s_addc_u32 s25, s25, 0
	s_mov_b32 m0, s33
	ds_read_b128 v[196:199], v160 offset:32768
	ds_read_b128 v[200:203], v160 offset:33792
	ds_read_b128 v[204:207], v160 offset:34816
	ds_read_b128 v[208:211], v160 offset:35840
	ds_read_b128 v[212:215], v160 offset:36864
	ds_read_b128 v[216:219], v160 offset:37888
	ds_read_b128 v[220:223], v160 offset:38912
	ds_read_b128 v[224:227], v160 offset:39936
	global_load_lds_dwordx4 v136, s[24:25]
	s_mov_b32 m0, s34
	s_nop 0
	global_load_lds_dwordx4 v132, s[24:25]
	s_waitcnt vmcnt(8)
	s_waitcnt lgkmcnt(0)
	s_barrier
	s_setprio 1
	s_waitcnt lgkmcnt(0)
	v_mfma_f32_16x16x32_bf16 v[124:127], v[146:149], v[196:199], v[124:127]
	v_mfma_f32_16x16x32_bf16 v[116:119], v[162:165], v[196:199], v[116:119]
	v_mfma_f32_16x16x32_bf16 v[108:111], v[146:149], v[204:207], v[108:111]
	v_mfma_f32_16x16x32_bf16 v[100:103], v[162:165], v[204:207], v[100:103]
	v_mfma_f32_16x16x32_bf16 v[92:95], v[146:149], v[212:215], v[92:95]
	v_mfma_f32_16x16x32_bf16 v[84:87], v[162:165], v[212:215], v[84:87]
	v_mfma_f32_16x16x32_bf16 v[76:79], v[146:149], v[220:223], v[76:79]
	v_mfma_f32_16x16x32_bf16 v[68:71], v[162:165], v[220:223], v[68:71]
	v_mfma_f32_16x16x32_bf16 v[124:127], v[150:153], v[200:203], v[124:127]
	v_mfma_f32_16x16x32_bf16 v[116:119], v[166:169], v[200:203], v[116:119]
	v_mfma_f32_16x16x32_bf16 v[108:111], v[150:153], v[208:211], v[108:111]
	v_mfma_f32_16x16x32_bf16 v[100:103], v[166:169], v[208:211], v[100:103]
	v_mfma_f32_16x16x32_bf16 v[92:95], v[150:153], v[216:219], v[92:95]
	v_mfma_f32_16x16x32_bf16 v[84:87], v[166:169], v[216:219], v[84:87]
	v_mfma_f32_16x16x32_bf16 v[76:79], v[150:153], v[224:227], v[76:79]
	v_mfma_f32_16x16x32_bf16 v[68:71], v[166:169], v[224:227], v[68:71]
	s_setprio 0
	s_setprio 1
	v_mfma_f32_16x16x32_bf16 v[120:123], v[180:183], v[196:199], v[120:123]
	v_mfma_f32_16x16x32_bf16 v[112:115], v[188:191], v[196:199], v[112:115]
	v_mfma_f32_16x16x32_bf16 v[104:107], v[180:183], v[204:207], v[104:107]
	v_mfma_f32_16x16x32_bf16 v[96:99], v[188:191], v[204:207], v[96:99]
	v_mfma_f32_16x16x32_bf16 v[88:91], v[180:183], v[212:215], v[88:91]
	v_mfma_f32_16x16x32_bf16 v[80:83], v[188:191], v[212:215], v[80:83]
	v_mfma_f32_16x16x32_bf16 v[72:75], v[180:183], v[220:223], v[72:75]
	v_mfma_f32_16x16x32_bf16 v[64:67], v[188:191], v[220:223], v[64:67]
	v_mfma_f32_16x16x32_bf16 v[120:123], v[184:187], v[200:203], v[120:123]
	v_mfma_f32_16x16x32_bf16 v[112:115], v[192:195], v[200:203], v[112:115]
	v_mfma_f32_16x16x32_bf16 v[104:107], v[184:187], v[208:211], v[104:107]
	v_mfma_f32_16x16x32_bf16 v[96:99], v[192:195], v[208:211], v[96:99]
	v_mfma_f32_16x16x32_bf16 v[88:91], v[184:187], v[216:219], v[88:91]
	v_mfma_f32_16x16x32_bf16 v[80:83], v[192:195], v[216:219], v[80:83]
	v_mfma_f32_16x16x32_bf16 v[72:75], v[184:187], v[224:227], v[72:75]
	v_mfma_f32_16x16x32_bf16 v[64:67], v[192:195], v[224:227], v[64:67]
	s_setprio 0
	s_barrier
; #define PG8_STAGE(bufoff, gbase, voff) do { _Pragma("unroll") for (int _i = 0; _i < 2; ++_i) \
;         __builtin_amdgcn_global_load_lds((const unsigned*)((const char*)(gbase) + (voff)[_i]), (PG8_LAS unsigned*)(lds + (bufoff) + ldsw + _i * 8192), 16, 0, 0); } while (0)
; #define PG8_LDA(dst, b, h) do { _Pragma("unroll") for (int m = 0; m < 4; ++m) _Pragma("unroll") for (int k = 0; k < 2; ++k) dst[m][k] = *(const PG8_LAS bf16x8*)(lds + PG8_SA(b, h) + aoff + m * 2048 + k * 1024); } while (0)
; #define PG8_MMA(ai, bj, At, Bt) do { __builtin_amdgcn_s_setprio(1); _Pragma("unroll") for (int m = 0; m < 4; ++m) _Pragma("unroll") for (int n = 0; n < 2; ++n) _Pragma("unroll") for (int k = 0; k < 2; ++k) \
;         acc[ai][bj][m][n] = __builtin_amdgcn_mfma_f32_16x16x32_bf16(Bt[n][k], At[m][k], acc[ai][bj][m][n], 0, 0, 0); __builtin_amdgcn_s_setprio(0); } while (0)
; #define PG8_WAIT_V(n) asm volatile("s_waitcnt vmcnt(" #n ")" ::: "memory")
; #define PG8_WAIT_L(n) asm volatile("s_waitcnt lgkmcnt(" #n ")" ::: "memory")
; #define PG8_BAR __builtin_amdgcn_s_barrier()
; #define PG8_SCHED __builtin_amdgcn_sched_barrier(0)
; template <class Epi, class Sched, bool ALIGN_EPI = false, bool SP2 = false>
; __device__ __forceinline__ void gemm_phase(PG8_LAS unsigned char* lds, const Gemm g, const Sched& S, const Epi& E) {
;     ...
;         for (int t = 0; t < nt; t += 2) {
;     ...
;             PG8_LDA(At, 1, 1); PG8_STAGE(PG8_SB(1, 0), b3, voffB); PG8_STAGE(PG8_SB(1, 1), b3 + hstep, voffB); PG8_STAGE(PG8_SA(1, 0), a3, voffA);
;             PG8_WAIT_V(8); PG8_WAIT_L(0); PG8_BAR; PG8_MMA(1, 0, At, B0); PG8_MMA(1, 1, At, B1); PG8_BAR; PG8_SCHED;
	s_add_i32 s24, s51, s26
	v_lshl_add_u64 v[170:171], v[170:171], 0, s[2:3]
	s_mov_b32 m0, s24
	ds_read_b128 v[196:199], v160 offset:49152
	ds_read_b128 v[200:203], v160 offset:50176
	ds_read_b128 v[204:207], v160 offset:51200
	ds_read_b128 v[208:211], v160 offset:52224
	ds_read_b128 v[212:215], v160 offset:53248
	ds_read_b128 v[216:219], v160 offset:54272
	ds_read_b128 v[220:223], v160 offset:55296
	ds_read_b128 v[224:227], v160 offset:56320
	global_load_lds_dwordx4 v[170:171], off
	s_add_i32 m0, s24, 0x2000
	s_add_u32 s22, s22, 0x80080
	v_lshl_add_u64 v[170:171], v[228:229], 0, s[2:3]
	s_addc_u32 s23, s23, 0
	s_add_i32 s24, s52, s26
	global_load_lds_dwordx4 v[170:171], off
	s_mov_b32 m0, s24
	s_nop 0
	global_load_lds_dwordx4 v134, s[22:23]
	s_add_i32 m0, s24, 0x2000
	s_nop 0
	global_load_lds_dwordx4 v130, s[22:23]
	v_lshl_add_u64 v[170:171], v[230:231], 0, s[2:3]
	s_mov_b32 m0, s35
	s_nop 0
	global_load_lds_dwordx4 v[170:171], off
	v_lshl_add_u64 v[170:171], v[232:233], 0, s[2:3]
	s_mov_b32 m0, s36
	s_nop 0
	global_load_lds_dwordx4 v[170:171], off
	s_waitcnt vmcnt(8)
	s_waitcnt lgkmcnt(0)
	s_barrier
	s_setprio 1
	s_waitcnt lgkmcnt(0)
	v_mfma_f32_16x16x32_bf16 v[60:63], v[146:149], v[196:199], v[60:63]
	v_mfma_f32_16x16x32_bf16 v[52:55], v[162:165], v[196:199], v[52:55]
	v_mfma_f32_16x16x32_bf16 v[44:47], v[146:149], v[204:207], v[44:47]
	v_mfma_f32_16x16x32_bf16 v[36:39], v[162:165], v[204:207], v[36:39]
	v_mfma_f32_16x16x32_bf16 v[28:31], v[146:149], v[212:215], v[28:31]
	v_mfma_f32_16x16x32_bf16 v[20:23], v[162:165], v[212:215], v[20:23]
	v_mfma_f32_16x16x32_bf16 v[12:15], v[146:149], v[220:223], v[12:15]
	v_mfma_f32_16x16x32_bf16 v[4:7], v[162:165], v[220:223], v[4:7]
	v_mfma_f32_16x16x32_bf16 v[60:63], v[150:153], v[200:203], v[60:63]
	v_mfma_f32_16x16x32_bf16 v[52:55], v[166:169], v[200:203], v[52:55]
	v_mfma_f32_16x16x32_bf16 v[44:47], v[150:153], v[208:211], v[44:47]
	v_mfma_f32_16x16x32_bf16 v[36:39], v[166:169], v[208:211], v[36:39]
	v_mfma_f32_16x16x32_bf16 v[28:31], v[150:153], v[216:219], v[28:31]
	v_mfma_f32_16x16x32_bf16 v[20:23], v[166:169], v[216:219], v[20:23]
	v_mfma_f32_16x16x32_bf16 v[12:15], v[150:153], v[224:227], v[12:15]
	v_mfma_f32_16x16x32_bf16 v[4:7], v[166:169], v[224:227], v[4:7]
	s_setprio 0
	s_setprio 1
	v_mfma_f32_16x16x32_bf16 v[56:59], v[180:183], v[196:199], v[56:59]
	v_mfma_f32_16x16x32_bf16 v[48:51], v[188:191], v[196:199], v[48:51]
	v_mfma_f32_16x16x32_bf16 v[40:43], v[180:183], v[204:207], v[40:43]
	v_mfma_f32_16x16x32_bf16 v[32:35], v[188:191], v[204:207], v[32:35]
	v_mfma_f32_16x16x32_bf16 v[24:27], v[180:183], v[212:215], v[24:27]
	v_mfma_f32_16x16x32_bf16 v[16:19], v[188:191], v[212:215], v[16:19]
	v_mfma_f32_16x16x32_bf16 v[8:11], v[180:183], v[220:223], v[8:11]
	v_mfma_f32_16x16x32_bf16 v[0:3], v[188:191], v[220:223], v[0:3]
	v_mfma_f32_16x16x32_bf16 v[56:59], v[184:187], v[200:203], v[56:59]
	v_mfma_f32_16x16x32_bf16 v[48:51], v[192:195], v[200:203], v[48:51]
	v_mfma_f32_16x16x32_bf16 v[40:43], v[184:187], v[208:211], v[40:43]
	v_mfma_f32_16x16x32_bf16 v[32:35], v[192:195], v[208:211], v[32:35]
	v_mfma_f32_16x16x32_bf16 v[24:27], v[184:187], v[216:219], v[24:27]
	v_mfma_f32_16x16x32_bf16 v[16:19], v[192:195], v[216:219], v[16:19]
	v_mfma_f32_16x16x32_bf16 v[8:11], v[184:187], v[224:227], v[8:11]
	v_mfma_f32_16x16x32_bf16 v[0:3], v[192:195], v[224:227], v[0:3]
	s_setprio 0
	s_barrier
	s_add_i32 s50, s50, 2
	s_add_u32 s20, s20, 0x100
	s_addc_u32 s21, s21, 0
	s_add_u32 s48, s48, 0x100
	s_addc_u32 s49, s49, 0
	s_cmp_gt_u32 s50, 29
	s_cbranch_scc0 .LBB0_837
	s_nop 0
	v_readfirstlane_b32 s11, v172
	s_nop 3
	s_lshr_b32 s11, s11, 6
	s_cmp_lt_u32 s11, 4
	s_cbranch_scc0 .Lprio_k2
	s_setprio 1

; #define PG8_STAGE(bufoff, gbase, voff) do { _Pragma("unroll") for (int _i = 0; _i < 2; ++_i) \
;         __builtin_amdgcn_global_load_lds((const unsigned*)((const char*)(gbase) + (voff)[_i]), (PG8_LAS unsigned*)(lds + (bufoff) + ldsw + _i * 8192), 16, 0, 0); } while (0)
; #define PG8_WAIT_V(n) asm volatile("s_waitcnt vmcnt(" #n ")" ::: "memory")
; #define PG8_BAR __builtin_amdgcn_s_barrier()
; template <class Epi, class Sched, bool ALIGN_EPI = false, bool SP2 = false>
; __device__ __forceinline__ void gemm_phase(PG8_LAS unsigned char* lds, const Gemm g, const Sched& S, const Epi& E) {
;     ...
;     for (int i = 0; i < 2; ++i) { int R, C; stage_rc(tid * 16 + i * 8192, R, C); const int Rb = Epi::PERM ? ((R & ~31) + perm32(R & 31)) : R;
;         voffA[i] = (unsigned)(R * K + C) * 2u; voffB[i] = (unsigned)(Rb * K + C) * 2u; }
;     const size_t kstep = (size_t)(BK * 2);
;     const size_t hstep = (size_t)HALF * K * 2;
;     const size_t tstep = 2 * hstep;
;     const unsigned ldsw = (unsigned)wid * 1024u;
;     const int aoff = lds_byte(wr * 64 + fr, fq * 8), boff = lds_byte(wc * 32 + fr, fq * 8);
;     ...
;         PG8_STAGE(PG8_SB(1, 0), cB + kstep, voffB); PG8_STAGE(PG8_SA(1, 0), cA + kstep, voffA); PG8_STAGE(PG8_SB(1, 1), cB + hstep + kstep, voffB);
;         PG8_WAIT_V(6); PG8_BAR;
.LBB0_1066:
	v_bfe_u32 v17, v9, 4, 2
	v_and_b32_e32 v18, 15, v9
	v_lshlrev_b32_e32 v19, 4, v17
	v_lshlrev_b32_e32 v9, 2, v9
	s_and_b32 s34, s4, 3
	v_lshl_or_b32 v148, s5, 6, v18
	v_lshl_or_b32 v18, v18, 6, v19
	s_lshl_b32 s4, s5, 13
	v_and_b32_e32 v9, 32, v9
	v_bitop3_b32 v19, v18, s4, v9 bitop3:0xde
	s_lshl_b32 s4, s34, 12
	v_bitop3_b32 v149, v18, s4, v9 bitop3:0xde
	s_mov_b64 s[4:5], 0x80
	s_add_i32 m0, s29, 0x18000
	v_lshl_add_u64 v[6:7], v[6:7], 0, s[4:5]
	s_waitcnt vmcnt(2)
	s_barrier
	global_load_lds_dwordx4 v[6:7], off
	v_lshl_add_u64 v[4:5], v[4:5], 0, s[4:5]
	s_add_i32 m0, s29, 0x1a000
	s_add_i32 s35, s29, 0x8000
	s_add_i32 s36, s29, 0xa000
	global_load_lds_dwordx4 v[4:5], off
	v_lshl_add_u64 v[0:1], v[0:1], 0, s[4:5]
	s_mov_b32 m0, s35
	s_add_u32 s8, s20, 0x160080
	global_load_lds_dwordx4 v[0:1], off
	v_lshl_add_u64 v[0:1], v[2:3], 0, s[4:5]
	s_mov_b32 m0, s36
	s_addc_u32 s9, s21, 0
	global_load_lds_dwordx4 v[0:1], off
	s_add_i32 m0, s29, 0x1c000
	s_nop 0
	global_load_lds_dwordx4 v130, s[8:9]
	s_add_i32 m0, s29, 0x1e000
	s_mov_b64 s[12:13], 0x160080
	global_load_lds_dwordx4 v132, s[8:9]
	v_lshlrev_b32_e32 v0, 2, v17
	v_lshl_or_b32 v150, s34, 5, v0
	v_lshrrev_b32_e32 v1, 1, v8
	v_mul_lo_u32 v0, v10, s10
	v_mad_u64_u32 v[0:1], s[16:17], v1, s11, v[0:1]
	v_or_b32_e32 v0, v0, v11
	v_add_lshl_u32 v0, v0, v12, 1
	v_mov_b32_e32 v1, v131
	v_lshl_add_u64 v[134:135], v[0:1], 0, s[12:13]
	v_lshrrev_b32_e32 v1, 1, v13
	v_mul_lo_u32 v0, v14, s10
	v_mad_u64_u32 v[0:1], s[10:11], v1, s11, v[0:1]
	s_waitcnt vmcnt(6)
	s_cmpk_lt_u32 s6, 0x100
	v_or_b32_e32 v0, v0, v15
	s_cselect_b64 s[6:7], -1, 0
	v_add_lshl_u32 v0, v0, v16, 1
	v_mov_b32_e32 v1, v131
	s_add_i32 s37, 0, 0x10000
	s_add_i32 s40, 0, 0x14000
	v_cmp_eq_u32_e64 s[8:9], 0, v17
	v_lshl_add_u64 v[136:137], v[0:1], 0, s[12:13]
	v_mov_b64_e32 v[138:139], 0x100
	v_mov_b64_e32 v[140:141], 0xff
	v_add_u32_e32 v151, s37, v149
	v_add_u32_e32 v152, s40, v149
	v_add_u32_e32 v153, 0, v19
	s_mov_b32 s41, 0
	s_barrier
	s_branch .LBB0_1069

; #define PG8_STAGE(bufoff, gbase, voff) do { _Pragma("unroll") for (int _i = 0; _i < 2; ++_i) \
;         __builtin_amdgcn_global_load_lds((const unsigned*)((const char*)(gbase) + (voff)[_i]), (PG8_LAS unsigned*)(lds + (bufoff) + ldsw + _i * 8192), 16, 0, 0); } while (0)
; #define PG8_LDA(dst, b, h) do { _Pragma("unroll") for (int m = 0; m < 4; ++m) _Pragma("unroll") for (int k = 0; k < 2; ++k) dst[m][k] = *(const PG8_LAS bf16x8*)(lds + PG8_SA(b, h) + aoff + m * 2048 + k * 1024); } while (0)
; #define PG8_LDB(dst, b, h) do { _Pragma("unroll") for (int n = 0; n < 2; ++n) _Pragma("unroll") for (int k = 0; k < 2; ++k) dst[n][k] = *(const PG8_LAS bf16x8*)(lds + PG8_SB(b, h) + boff + n * 2048 + k * 1024); } while (0)
; #define PG8_MMA(ai, bj, At, Bt) do { __builtin_amdgcn_s_setprio(1); _Pragma("unroll") for (int m = 0; m < 4; ++m) _Pragma("unroll") for (int n = 0; n < 2; ++n) _Pragma("unroll") for (int k = 0; k < 2; ++k) \
;         acc[ai][bj][m][n] = __builtin_amdgcn_mfma_f32_16x16x32_bf16(Bt[n][k], At[m][k], acc[ai][bj][m][n], 0, 0, 0); __builtin_amdgcn_s_setprio(0); } while (0)
; #define PG8_WAIT_V(n) asm volatile("s_waitcnt vmcnt(" #n ")" ::: "memory")
; #define PG8_WAIT_L(n) asm volatile("s_waitcnt lgkmcnt(" #n ")" ::: "memory")
; #define PG8_BAR __builtin_amdgcn_s_barrier()
; #define PG8_SCHED __builtin_amdgcn_sched_barrier(0)
; template <class Epi, class Sched, bool ALIGN_EPI = false, bool SP2 = false>
; __device__ __forceinline__ void gemm_phase(PG8_LAS unsigned char* lds, const Gemm g, const Sched& S, const Epi& E) {
;     ...
;             PG8_LDB(B0, 0, 0); PG8_LDB(B1, 0, 1); PG8_SCHED; PG8_LDA(At, 0, 0); PG8_STAGE(PG8_SA(1, 1), a1 + hstep, voffA);
;             PG8_WAIT_V(8); PG8_WAIT_L(0); PG8_BAR; PG8_MMA(0, 0, At, B0); PG8_MMA(0, 1, At, B1); PG8_BAR; PG8_SCHED;
;             PG8_LDA(At, 0, 1); PG8_STAGE(PG8_SB(0, 0), b2, voffB); PG8_STAGE(PG8_SB(0, 1), b2 + hstep, voffB); PG8_STAGE(PG8_SA(0, 0), a2, voffA);
;             PG8_WAIT_V(8); PG8_WAIT_L(0); PG8_BAR; PG8_MMA(1, 0, At, B0); PG8_MMA(1, 1, At, B1); PG8_BAR; PG8_SCHED;
.LBB0_1080:
	ds_read_b128 v[142:145], v151
	ds_read_b128 v[154:157], v151 offset:1024
	ds_read_b128 v[158:161], v151 offset:2048
	ds_read_b128 v[162:165], v151 offset:3072
	ds_read_b128 v[166:169], v152
	ds_read_b128 v[180:183], v152 offset:1024
	ds_read_b128 v[184:187], v152 offset:2048
	ds_read_b128 v[188:191], v152 offset:3072
	s_add_u32 s20, s18, 0x100
	s_addc_u32 s21, s19, 0
	s_cmpk_eq_i32 s49, 0x54
	s_cselect_b32 s25, s13, s21
	s_cselect_b32 s24, s12, s20
	s_cselect_b32 s23, s17, s48
	s_cselect_b32 s22, s16, s47
	s_add_i32 m0, s29, 0xc000
	ds_read_b128 v[192:195], v153
	ds_read_b128 v[196:199], v153 offset:1024
	ds_read_b128 v[200:203], v153 offset:2048
	ds_read_b128 v[204:207], v153 offset:3072
	ds_read_b128 v[208:211], v153 offset:4096
	ds_read_b128 v[212:215], v153 offset:5120
	ds_read_b128 v[216:219], v153 offset:6144
	ds_read_b128 v[220:223], v153 offset:7168
	global_load_lds_dwordx4 v134, s[18:19]
	s_add_i32 m0, s29, 0xe000
	s_nop 0
	global_load_lds_dwordx4 v136, s[18:19]
	s_waitcnt vmcnt(8)
	s_waitcnt lgkmcnt(0)
	s_barrier
	s_setprio 1
	s_waitcnt lgkmcnt(0)
	v_mfma_f32_16x16x32_bf16 v[124:127], v[142:145], v[192:195], v[124:127]
	v_mfma_f32_16x16x32_bf16 v[120:123], v[158:161], v[192:195], v[120:123]
	v_mfma_f32_16x16x32_bf16 v[108:111], v[142:145], v[200:203], v[108:111]
	v_mfma_f32_16x16x32_bf16 v[104:107], v[158:161], v[200:203], v[104:107]
	v_mfma_f32_16x16x32_bf16 v[92:95], v[142:145], v[208:211], v[92:95]
	v_mfma_f32_16x16x32_bf16 v[88:91], v[158:161], v[208:211], v[88:91]
	v_mfma_f32_16x16x32_bf16 v[76:79], v[142:145], v[216:219], v[76:79]
	v_mfma_f32_16x16x32_bf16 v[72:75], v[158:161], v[216:219], v[72:75]
	v_mfma_f32_16x16x32_bf16 v[124:127], v[154:157], v[196:199], v[124:127]
	v_mfma_f32_16x16x32_bf16 v[120:123], v[162:165], v[196:199], v[120:123]
	v_mfma_f32_16x16x32_bf16 v[108:111], v[154:157], v[204:207], v[108:111]
	v_mfma_f32_16x16x32_bf16 v[104:107], v[162:165], v[204:207], v[104:107]
	v_mfma_f32_16x16x32_bf16 v[92:95], v[154:157], v[212:215], v[92:95]
	v_mfma_f32_16x16x32_bf16 v[88:91], v[162:165], v[212:215], v[88:91]
	v_mfma_f32_16x16x32_bf16 v[76:79], v[154:157], v[220:223], v[76:79]
	v_mfma_f32_16x16x32_bf16 v[72:75], v[162:165], v[220:223], v[72:75]
	s_setprio 0
	s_setprio 1
	v_mfma_f32_16x16x32_bf16 v[116:119], v[166:169], v[192:195], v[116:119]
	v_mfma_f32_16x16x32_bf16 v[112:115], v[184:187], v[192:195], v[112:115]
	v_mfma_f32_16x16x32_bf16 v[100:103], v[166:169], v[200:203], v[100:103]
	v_mfma_f32_16x16x32_bf16 v[96:99], v[184:187], v[200:203], v[96:99]
	v_mfma_f32_16x16x32_bf16 v[84:87], v[166:169], v[208:211], v[84:87]
	v_mfma_f32_16x16x32_bf16 v[80:83], v[184:187], v[208:211], v[80:83]
	v_mfma_f32_16x16x32_bf16 v[68:71], v[166:169], v[216:219], v[68:71]
	v_mfma_f32_16x16x32_bf16 v[64:67], v[184:187], v[216:219], v[64:67]
	v_mfma_f32_16x16x32_bf16 v[116:119], v[180:183], v[196:199], v[116:119]
	v_mfma_f32_16x16x32_bf16 v[112:115], v[188:191], v[196:199], v[112:115]
	v_mfma_f32_16x16x32_bf16 v[100:103], v[180:183], v[204:207], v[100:103]
	v_mfma_f32_16x16x32_bf16 v[96:99], v[188:191], v[204:207], v[96:99]
	v_mfma_f32_16x16x32_bf16 v[84:87], v[180:183], v[212:215], v[84:87]
	v_mfma_f32_16x16x32_bf16 v[80:83], v[188:191], v[212:215], v[80:83]
	v_mfma_f32_16x16x32_bf16 v[68:71], v[180:183], v[220:223], v[68:71]
	v_mfma_f32_16x16x32_bf16 v[64:67], v[188:191], v[220:223], v[64:67]
	s_setprio 0
	s_barrier
	s_add_i32 s18, s37, s28
	v_lshl_add_u64 v[146:147], s[22:23], 0, v[130:131]
	s_mov_b32 m0, s18
	ds_read_b128 v[192:195], v153 offset:16384
	ds_read_b128 v[196:199], v153 offset:17408
	ds_read_b128 v[200:203], v153 offset:18432
	ds_read_b128 v[204:207], v153 offset:19456
	ds_read_b128 v[208:211], v153 offset:20480
	ds_read_b128 v[212:215], v153 offset:21504
	ds_read_b128 v[216:219], v153 offset:22528
	ds_read_b128 v[220:223], v153 offset:23552
	global_load_lds_dwordx4 v[146:147], off
	s_add_i32 m0, s18, 0x2000
	s_add_u32 s18, s22, 0x160000
	v_lshl_add_u64 v[170:171], s[22:23], 0, v[132:133]
	s_addc_u32 s19, s23, 0
	s_add_i32 s50, s40, s28
	global_load_lds_dwordx4 v[170:171], off
	s_mov_b32 m0, s50
	v_lshl_add_u64 v[226:227], s[24:25], 0, v[132:133]
	global_load_lds_dwordx4 v130, s[18:19]
	s_add_i32 m0, s50, 0x2000
	s_nop 0
	global_load_lds_dwordx4 v132, s[18:19]
	v_lshl_add_u64 v[224:225], s[24:25], 0, v[130:131]
	s_mov_b32 m0, s29
	s_nop 0
	global_load_lds_dwordx4 v[224:225], off
	s_mov_b32 m0, s30
	s_nop 0
	global_load_lds_dwordx4 v[226:227], off
	s_waitcnt vmcnt(8)
	s_waitcnt lgkmcnt(0)
	s_barrier
; #define PG8_STAGE(bufoff, gbase, voff) do { _Pragma("unroll") for (int _i = 0; _i < 2; ++_i) \
;         __builtin_amdgcn_global_load_lds((const unsigned*)((const char*)(gbase) + (voff)[_i]), (PG8_LAS unsigned*)(lds + (bufoff) + ldsw + _i * 8192), 16, 0, 0); } while (0)
; #define PG8_LDA(dst, b, h) do { _Pragma("unroll") for (int m = 0; m < 4; ++m) _Pragma("unroll") for (int k = 0; k < 2; ++k) dst[m][k] = *(const PG8_LAS bf16x8*)(lds + PG8_SA(b, h) + aoff + m * 2048 + k * 1024); } while (0)
; #define PG8_LDB(dst, b, h) do { _Pragma("unroll") for (int n = 0; n < 2; ++n) _Pragma("unroll") for (int k = 0; k < 2; ++k) dst[n][k] = *(const PG8_LAS bf16x8*)(lds + PG8_SB(b, h) + boff + n * 2048 + k * 1024); } while (0)
; #define PG8_MMA(ai, bj, At, Bt) do { __builtin_amdgcn_s_setprio(1); _Pragma("unroll") for (int m = 0; m < 4; ++m) _Pragma("unroll") for (int n = 0; n < 2; ++n) _Pragma("unroll") for (int k = 0; k < 2; ++k) \
;         acc[ai][bj][m][n] = __builtin_amdgcn_mfma_f32_16x16x32_bf16(Bt[n][k], At[m][k], acc[ai][bj][m][n], 0, 0, 0); __builtin_amdgcn_s_setprio(0); } while (0)
; #define PG8_WAIT_V(n) asm volatile("s_waitcnt vmcnt(" #n ")" ::: "memory")
; #define PG8_WAIT_L(n) asm volatile("s_waitcnt lgkmcnt(" #n ")" ::: "memory")
; #define PG8_BAR __builtin_amdgcn_s_barrier()
; #define PG8_SCHED __builtin_amdgcn_sched_barrier(0)
; template <class Epi, class Sched, bool ALIGN_EPI = false, bool SP2 = false>
; __device__ __forceinline__ void gemm_phase(PG8_LAS unsigned char* lds, const Gemm g, const Sched& S, const Epi& E) {
;     ...
;             PG8_WAIT_V(8); PG8_WAIT_L(0); PG8_BAR; PG8_MMA(1, 0, At, B0); PG8_MMA(1, 1, At, B1); PG8_BAR; PG8_SCHED;
;             PG8_LDB(B0, 1, 0); PG8_LDB(B1, 1, 1); PG8_SCHED; PG8_LDA(At, 1, 0); PG8_STAGE(PG8_SA(0, 1), a2 + hstep, voffA);
;             PG8_WAIT_V(8); PG8_WAIT_L(0); PG8_BAR; PG8_MMA(0, 0, At, B0); PG8_MMA(0, 1, At, B1); PG8_BAR; PG8_SCHED;
	s_setprio 1
	s_waitcnt lgkmcnt(0)
	v_mfma_f32_16x16x32_bf16 v[60:63], v[142:145], v[192:195], v[60:63]
	v_mfma_f32_16x16x32_bf16 v[56:59], v[158:161], v[192:195], v[56:59]
	v_mfma_f32_16x16x32_bf16 v[44:47], v[142:145], v[200:203], v[44:47]
	v_mfma_f32_16x16x32_bf16 v[40:43], v[158:161], v[200:203], v[40:43]
	v_mfma_f32_16x16x32_bf16 v[28:31], v[142:145], v[208:211], v[28:31]
	v_mfma_f32_16x16x32_bf16 v[24:27], v[158:161], v[208:211], v[24:27]
	v_mfma_f32_16x16x32_bf16 v[12:15], v[142:145], v[216:219], v[12:15]
	v_mfma_f32_16x16x32_bf16 v[8:11], v[158:161], v[216:219], v[8:11]
	v_mfma_f32_16x16x32_bf16 v[60:63], v[154:157], v[196:199], v[60:63]
	v_mfma_f32_16x16x32_bf16 v[56:59], v[162:165], v[196:199], v[56:59]
	v_mfma_f32_16x16x32_bf16 v[44:47], v[154:157], v[204:207], v[44:47]
	v_mfma_f32_16x16x32_bf16 v[40:43], v[162:165], v[204:207], v[40:43]
	v_mfma_f32_16x16x32_bf16 v[28:31], v[154:157], v[212:215], v[28:31]
	v_mfma_f32_16x16x32_bf16 v[24:27], v[162:165], v[212:215], v[24:27]
	v_mfma_f32_16x16x32_bf16 v[12:15], v[154:157], v[220:223], v[12:15]
	v_mfma_f32_16x16x32_bf16 v[8:11], v[162:165], v[220:223], v[8:11]
	s_setprio 0
	s_setprio 1
	v_mfma_f32_16x16x32_bf16 v[52:55], v[166:169], v[192:195], v[52:55]
	v_mfma_f32_16x16x32_bf16 v[48:51], v[184:187], v[192:195], v[48:51]
	v_mfma_f32_16x16x32_bf16 v[36:39], v[166:169], v[200:203], v[36:39]
	v_mfma_f32_16x16x32_bf16 v[32:35], v[184:187], v[200:203], v[32:35]
	v_mfma_f32_16x16x32_bf16 v[20:23], v[166:169], v[208:211], v[20:23]
	v_mfma_f32_16x16x32_bf16 v[16:19], v[184:187], v[208:211], v[16:19]
	v_mfma_f32_16x16x32_bf16 v[4:7], v[166:169], v[216:219], v[4:7]
	v_mfma_f32_16x16x32_bf16 v[0:3], v[184:187], v[216:219], v[0:3]
	v_mfma_f32_16x16x32_bf16 v[52:55], v[180:183], v[196:199], v[52:55]
	v_mfma_f32_16x16x32_bf16 v[48:51], v[188:191], v[196:199], v[48:51]
	v_mfma_f32_16x16x32_bf16 v[36:39], v[180:183], v[204:207], v[36:39]
	v_mfma_f32_16x16x32_bf16 v[32:35], v[188:191], v[204:207], v[32:35]
	v_mfma_f32_16x16x32_bf16 v[20:23], v[180:183], v[212:215], v[20:23]
	v_mfma_f32_16x16x32_bf16 v[16:19], v[188:191], v[212:215], v[16:19]
	v_mfma_f32_16x16x32_bf16 v[4:7], v[180:183], v[220:223], v[4:7]
	v_mfma_f32_16x16x32_bf16 v[0:3], v[188:191], v[220:223], v[0:3]
	s_setprio 0
	s_barrier
	s_add_i32 s50, 0, 0x18000
	s_add_i32 s51, 0, 0x1c000
	v_add_u32_e32 v162, s50, v149
	v_add_u32_e32 v179, s51, v149
	ds_read_b128 v[142:145], v162
	ds_read_b128 v[154:157], v162 offset:1024
	ds_read_b128 v[158:161], v162 offset:2048
	ds_read_b128 v[162:165], v162 offset:3072
	ds_read_b128 v[166:169], v179
	ds_read_b128 v[180:183], v179 offset:1024
	ds_read_b128 v[184:187], v179 offset:2048
	ds_read_b128 v[188:191], v179 offset:3072
	s_add_u32 s18, s24, 0x160000
	s_addc_u32 s19, s25, 0
	s_mov_b32 m0, s31
	ds_read_b128 v[192:195], v153 offset:32768
	ds_read_b128 v[196:199], v153 offset:33792
	ds_read_b128 v[200:203], v153 offset:34816
	ds_read_b128 v[204:207], v153 offset:35840
	ds_read_b128 v[208:211], v153 offset:36864
	ds_read_b128 v[212:215], v153 offset:37888
	ds_read_b128 v[216:219], v153 offset:38912
	ds_read_b128 v[220:223], v153 offset:39936
	global_load_lds_dwordx4 v130, s[18:19]
	s_mov_b32 m0, s33
	s_nop 0
	global_load_lds_dwordx4 v132, s[18:19]
	s_waitcnt vmcnt(8)
	s_waitcnt lgkmcnt(0)
	s_barrier
	s_setprio 1
	s_waitcnt lgkmcnt(0)
	v_mfma_f32_16x16x32_bf16 v[124:127], v[142:145], v[192:195], v[124:127]
	v_mfma_f32_16x16x32_bf16 v[120:123], v[158:161], v[192:195], v[120:123]
	v_mfma_f32_16x16x32_bf16 v[108:111], v[142:145], v[200:203], v[108:111]
	v_mfma_f32_16x16x32_bf16 v[104:107], v[158:161], v[200:203], v[104:107]
	v_mfma_f32_16x16x32_bf16 v[92:95], v[142:145], v[208:211], v[92:95]
	v_mfma_f32_16x16x32_bf16 v[88:91], v[158:161], v[208:211], v[88:91]
	v_mfma_f32_16x16x32_bf16 v[76:79], v[142:145], v[216:219], v[76:79]
	v_mfma_f32_16x16x32_bf16 v[72:75], v[158:161], v[216:219], v[72:75]
	v_mfma_f32_16x16x32_bf16 v[124:127], v[154:157], v[196:199], v[124:127]
	v_mfma_f32_16x16x32_bf16 v[120:123], v[162:165], v[196:199], v[120:123]
	v_mfma_f32_16x16x32_bf16 v[108:111], v[154:157], v[204:207], v[108:111]
	v_mfma_f32_16x16x32_bf16 v[104:107], v[162:165], v[204:207], v[104:107]
	v_mfma_f32_16x16x32_bf16 v[92:95], v[154:157], v[212:215], v[92:95]
	v_mfma_f32_16x16x32_bf16 v[88:91], v[162:165], v[212:215], v[88:91]
	v_mfma_f32_16x16x32_bf16 v[76:79], v[154:157], v[220:223], v[76:79]
	v_mfma_f32_16x16x32_bf16 v[72:75], v[162:165], v[220:223], v[72:75]
	s_setprio 0
	s_setprio 1
	v_mfma_f32_16x16x32_bf16 v[116:119], v[166:169], v[192:195], v[116:119]
	v_mfma_f32_16x16x32_bf16 v[112:115], v[184:187], v[192:195], v[112:115]
	v_mfma_f32_16x16x32_bf16 v[100:103], v[166:169], v[200:203], v[100:103]
	v_mfma_f32_16x16x32_bf16 v[96:99], v[184:187], v[200:203], v[96:99]
	v_mfma_f32_16x16x32_bf16 v[84:87], v[166:169], v[208:211], v[84:87]
	v_mfma_f32_16x16x32_bf16 v[80:83], v[184:187], v[208:211], v[80:83]
	v_mfma_f32_16x16x32_bf16 v[68:71], v[166:169], v[216:219], v[68:71]
	v_mfma_f32_16x16x32_bf16 v[64:67], v[184:187], v[216:219], v[64:67]
	v_mfma_f32_16x16x32_bf16 v[116:119], v[180:183], v[196:199], v[116:119]
	v_mfma_f32_16x16x32_bf16 v[112:115], v[188:191], v[196:199], v[112:115]
	v_mfma_f32_16x16x32_bf16 v[100:103], v[180:183], v[204:207], v[100:103]
	v_mfma_f32_16x16x32_bf16 v[96:99], v[188:191], v[204:207], v[96:99]
	v_mfma_f32_16x16x32_bf16 v[84:87], v[180:183], v[212:215], v[84:87]
	v_mfma_f32_16x16x32_bf16 v[80:83], v[188:191], v[212:215], v[80:83]
	v_mfma_f32_16x16x32_bf16 v[68:71], v[180:183], v[220:223], v[68:71]
	v_mfma_f32_16x16x32_bf16 v[64:67], v[188:191], v[220:223], v[64:67]
	s_setprio 0
	s_barrier
; #define PG8_STAGE(bufoff, gbase, voff) do { _Pragma("unroll") for (int _i = 0; _i < 2; ++_i) \
;         __builtin_amdgcn_global_load_lds((const unsigned*)((const char*)(gbase) + (voff)[_i]), (PG8_LAS unsigned*)(lds + (bufoff) + ldsw + _i * 8192), 16, 0, 0); } while (0)
; #define PG8_LDA(dst, b, h) do { _Pragma("unroll") for (int m = 0; m < 4; ++m) _Pragma("unroll") for (int k = 0; k < 2; ++k) dst[m][k] = *(const PG8_LAS bf16x8*)(lds + PG8_SA(b, h) + aoff + m * 2048 + k * 1024); } while (0)
; #define PG8_MMA(ai, bj, At, Bt) do { __builtin_amdgcn_s_setprio(1); _Pragma("unroll") for (int m = 0; m < 4; ++m) _Pragma("unroll") for (int n = 0; n < 2; ++n) _Pragma("unroll") for (int k = 0; k < 2; ++k) \
;         acc[ai][bj][m][n] = __builtin_amdgcn_mfma_f32_16x16x32_bf16(Bt[n][k], At[m][k], acc[ai][bj][m][n], 0, 0, 0); __builtin_amdgcn_s_setprio(0); } while (0)
; #define PG8_WAIT_V(n) asm volatile("s_waitcnt vmcnt(" #n ")" ::: "memory")
; #define PG8_WAIT_L(n) asm volatile("s_waitcnt lgkmcnt(" #n ")" ::: "memory")
; #define PG8_BAR __builtin_amdgcn_s_barrier()
; #define PG8_SCHED __builtin_amdgcn_sched_barrier(0)
; template <class Epi, class Sched, bool ALIGN_EPI = false, bool SP2 = false>
; __device__ __forceinline__ void gemm_phase(PG8_LAS unsigned char* lds, const Gemm g, const Sched& S, const Epi& E) {
;     ...
;         for (int t = 0; t < nt; t += 2) {
;     ...
;             PG8_LDA(At, 1, 1); PG8_STAGE(PG8_SB(1, 0), b3, voffB); PG8_STAGE(PG8_SB(1, 1), b3 + hstep, voffB); PG8_STAGE(PG8_SA(1, 0), a3, voffA);
;             PG8_WAIT_V(8); PG8_WAIT_L(0); PG8_BAR; PG8_MMA(1, 0, At, B0); PG8_MMA(1, 1, At, B1); PG8_BAR; PG8_SCHED;
	s_add_i32 s18, s50, s28
	v_lshl_add_u64 v[146:147], v[146:147], 0, s[4:5]
	s_mov_b32 m0, s18
	ds_read_b128 v[192:195], v153 offset:49152
	ds_read_b128 v[196:199], v153 offset:50176
	ds_read_b128 v[200:203], v153 offset:51200
	ds_read_b128 v[204:207], v153 offset:52224
	ds_read_b128 v[208:211], v153 offset:53248
	ds_read_b128 v[212:215], v153 offset:54272
	ds_read_b128 v[216:219], v153 offset:55296
	ds_read_b128 v[220:223], v153 offset:56320
	global_load_lds_dwordx4 v[146:147], off
	s_add_i32 m0, s18, 0x2000
	s_add_u32 s18, s22, 0x160080
	v_lshl_add_u64 v[146:147], v[170:171], 0, s[4:5]
	s_addc_u32 s19, s23, 0
	s_add_i32 s22, s51, s28
	global_load_lds_dwordx4 v[146:147], off
	s_mov_b32 m0, s22
	s_nop 0
	global_load_lds_dwordx4 v130, s[18:19]
	s_add_i32 m0, s22, 0x2000
	s_nop 0
	global_load_lds_dwordx4 v132, s[18:19]
	v_lshl_add_u64 v[146:147], v[224:225], 0, s[4:5]
	s_mov_b32 m0, s35
	s_nop 0
	global_load_lds_dwordx4 v[146:147], off
	v_lshl_add_u64 v[146:147], v[226:227], 0, s[4:5]
	s_mov_b32 m0, s36
	s_nop 0
	global_load_lds_dwordx4 v[146:147], off
	s_waitcnt vmcnt(8)
	s_waitcnt lgkmcnt(0)
	s_barrier
	s_setprio 1
	s_waitcnt lgkmcnt(0)
	v_mfma_f32_16x16x32_bf16 v[60:63], v[142:145], v[192:195], v[60:63]
	v_mfma_f32_16x16x32_bf16 v[56:59], v[158:161], v[192:195], v[56:59]
	v_mfma_f32_16x16x32_bf16 v[44:47], v[142:145], v[200:203], v[44:47]
	v_mfma_f32_16x16x32_bf16 v[40:43], v[158:161], v[200:203], v[40:43]
	v_mfma_f32_16x16x32_bf16 v[28:31], v[142:145], v[208:211], v[28:31]
	v_mfma_f32_16x16x32_bf16 v[24:27], v[158:161], v[208:211], v[24:27]
	v_mfma_f32_16x16x32_bf16 v[12:15], v[142:145], v[216:219], v[12:15]
	v_mfma_f32_16x16x32_bf16 v[8:11], v[158:161], v[216:219], v[8:11]
	v_mfma_f32_16x16x32_bf16 v[60:63], v[154:157], v[196:199], v[60:63]
	v_mfma_f32_16x16x32_bf16 v[56:59], v[162:165], v[196:199], v[56:59]
	v_mfma_f32_16x16x32_bf16 v[44:47], v[154:157], v[204:207], v[44:47]
	v_mfma_f32_16x16x32_bf16 v[40:43], v[162:165], v[204:207], v[40:43]
	v_mfma_f32_16x16x32_bf16 v[28:31], v[154:157], v[212:215], v[28:31]
	v_mfma_f32_16x16x32_bf16 v[24:27], v[162:165], v[212:215], v[24:27]
	v_mfma_f32_16x16x32_bf16 v[12:15], v[154:157], v[220:223], v[12:15]
	v_mfma_f32_16x16x32_bf16 v[8:11], v[162:165], v[220:223], v[8:11]
	s_setprio 0
	s_setprio 1
	v_mfma_f32_16x16x32_bf16 v[52:55], v[166:169], v[192:195], v[52:55]
	v_mfma_f32_16x16x32_bf16 v[48:51], v[184:187], v[192:195], v[48:51]
	v_mfma_f32_16x16x32_bf16 v[36:39], v[166:169], v[200:203], v[36:39]
	v_mfma_f32_16x16x32_bf16 v[32:35], v[184:187], v[200:203], v[32:35]
	v_mfma_f32_16x16x32_bf16 v[20:23], v[166:169], v[208:211], v[20:23]
	v_mfma_f32_16x16x32_bf16 v[16:19], v[184:187], v[208:211], v[16:19]
	v_mfma_f32_16x16x32_bf16 v[4:7], v[166:169], v[216:219], v[4:7]
	v_mfma_f32_16x16x32_bf16 v[0:3], v[184:187], v[216:219], v[0:3]
	v_mfma_f32_16x16x32_bf16 v[52:55], v[180:183], v[196:199], v[52:55]
	v_mfma_f32_16x16x32_bf16 v[48:51], v[188:191], v[196:199], v[48:51]
	v_mfma_f32_16x16x32_bf16 v[36:39], v[180:183], v[204:207], v[36:39]
	v_mfma_f32_16x16x32_bf16 v[32:35], v[188:191], v[204:207], v[32:35]
	v_mfma_f32_16x16x32_bf16 v[20:23], v[180:183], v[212:215], v[20:23]
	v_mfma_f32_16x16x32_bf16 v[16:19], v[188:191], v[212:215], v[16:19]
	v_mfma_f32_16x16x32_bf16 v[4:7], v[180:183], v[220:223], v[4:7]
	v_mfma_f32_16x16x32_bf16 v[0:3], v[188:191], v[220:223], v[0:3]
	s_setprio 0
	s_barrier
	s_add_i32 s49, s49, 2
	s_add_u32 s47, s47, 0x100
	s_addc_u32 s48, s48, 0
	s_cmpk_gt_u32 s49, 0x55
	s_mov_b64 s[18:19], s[20:21]
	s_cbranch_scc0 .LBB0_1080
	s_nop 0
	v_readfirstlane_b32 s18, v172
	s_nop 3
	s_lshr_b32 s18, s18, 6
	s_cmp_lt_u32 s18, 4
	s_cbranch_scc0 .Lprio_k3
	s_setprio 1

; #define PG8_STAGE(bufoff, gbase, voff) do { _Pragma("unroll") for (int _i = 0; _i < 2; ++_i) \
;         __builtin_amdgcn_global_load_lds((const unsigned*)((const char*)(gbase) + (voff)[_i]), (PG8_LAS unsigned*)(lds + (bufoff) + ldsw + _i * 8192), 16, 0, 0); } while (0)
; #define PG8_WAIT_V(n) asm volatile("s_waitcnt vmcnt(" #n ")" ::: "memory")
; #define PG8_BAR __builtin_amdgcn_s_barrier()
; template <class Epi, class Sched, bool ALIGN_EPI = false, bool SP2 = false>
; __device__ __forceinline__ void gemm_phase(PG8_LAS unsigned char* lds, const Gemm g, const Sched& S, const Epi& E) {
;     ...
;     for (int i = 0; i < 2; ++i) { int R, C; stage_rc(tid * 16 + i * 8192, R, C); const int Rb = Epi::PERM ? ((R & ~31) + perm32(R & 31)) : R;
;         voffA[i] = (unsigned)(R * K + C) * 2u; voffB[i] = (unsigned)(Rb * K + C) * 2u; }
;     const size_t kstep = (size_t)(BK * 2);
;     const size_t hstep = (size_t)HALF * K * 2;
;     const size_t tstep = 2 * hstep;
;     const unsigned ldsw = (unsigned)wid * 1024u;
;     const int aoff = lds_byte(wr * 64 + fr, fq * 8), boff = lds_byte(wc * 32 + fr, fq * 8);
;     ...
;         PG8_STAGE(PG8_SB(1, 0), cB + kstep, voffB); PG8_STAGE(PG8_SA(1, 0), cA + kstep, voffA); PG8_STAGE(PG8_SB(1, 1), cB + hstep + kstep, voffB);
;         PG8_WAIT_V(6); PG8_BAR;
.LBB0_1171:
	v_and_b32_e32 v15, 15, v14
	v_lshrrev_b32_e32 v14, 1, v14
	v_and_b32_e32 v14, 24, v14
	v_lshlrev_b32_e32 v16, 1, v14
	v_lshl_or_b32 v150, s6, 6, v15
	v_lshl_or_b32 v16, v15, 6, v16
	v_lshlrev_b32_e32 v15, 2, v15
	s_sext_i32_i16 s41, s2
	s_lshl_b32 s2, s6, 13
	v_and_b32_e32 v17, 32, v15
	v_bitop3_b32 v18, v16, s2, v17 bitop3:0xde
	s_lshl_b32 s2, s3, 5
	s_and_b32 s7, s2, 0x60
	s_lshl_b32 s2, s7, 7
	v_bitop3_b32 v151, v16, s2, v17 bitop3:0xde
	s_mov_b64 s[2:3], 0x80
	s_add_i32 m0, s17, 0x18000
	v_lshl_add_u64 v[6:7], v[6:7], 0, s[2:3]
	s_waitcnt vmcnt(2)
	s_barrier
	global_load_lds_dwordx4 v[6:7], off
	v_lshl_add_u64 v[4:5], v[4:5], 0, s[2:3]
	s_add_i32 m0, s17, 0x1a000
	s_add_i32 s33, s17, 0x8000
	s_add_i32 s34, s17, 0xa000
	global_load_lds_dwordx4 v[4:5], off
	v_lshl_add_u64 v[0:1], v[0:1], 0, s[2:3]
	s_mov_b32 m0, s33
	s_add_u32 s8, s22, 0x80080
	global_load_lds_dwordx4 v[0:1], off
	v_lshl_add_u64 v[0:1], v[2:3], 0, s[2:3]
	s_mov_b32 m0, s34
	s_addc_u32 s9, s23, 0
	global_load_lds_dwordx4 v[0:1], off
	s_add_i32 m0, s17, 0x1c000
	s_nop 0
	global_load_lds_dwordx4 v132, s[8:9]
	s_add_i32 m0, s17, 0x1e000
	s_cmpk_lt_u32 s4, 0x100
	global_load_lds_dwordx4 v136, s[8:9]
	v_lshlrev_b32_e32 v0, 15, v8
	v_and_b32_e32 v0, 0xffff0000, v0
	v_lshl_add_u32 v0, v9, 12, v0
	v_and_b32_e32 v1, 1, v8
	v_lshl_or_b32 v0, v1, 6, v0
	v_lshl_add_u32 v138, v10, 1, v0
	v_lshlrev_b32_e32 v0, 15, v11
	s_cselect_b64 s[4:5], -1, 0
	s_lshl_b32 s6, s6, 8
	v_and_b32_e32 v0, 0xffff0000, v0
	s_waitcnt vmcnt(6)
	s_add_i32 s6, s6, 0
	v_lshl_add_u32 v0, v12, 12, v0
	v_and_b32_e32 v1, 1, v11
	s_add_i32 s6, s6, 0x20000
	v_lshl_or_b32 v0, v1, 6, v0
	s_add_i32 s35, 0, 0x10000
	s_add_i32 s36, 0, 0x14000
	v_add_u32_e32 v152, s6, v15
	v_or_b32_e32 v153, s7, v14
	v_mov_b32_e32 v139, v133
	v_lshl_add_u32 v140, v13, 1, v0
	v_mov_b32_e32 v141, v133
	v_mov_b64_e32 v[142:143], 0x400
	v_mov_b64_e32 v[144:145], 0x3ff
	v_add_u32_e32 v154, s35, v151
	v_add_u32_e32 v155, s36, v151
	v_add_u32_e32 v156, 0, v18
	s_barrier
	s_branch .LBB0_1174

; #define PG8_STAGE(bufoff, gbase, voff) do { _Pragma("unroll") for (int _i = 0; _i < 2; ++_i) \
;         __builtin_amdgcn_global_load_lds((const unsigned*)((const char*)(gbase) + (voff)[_i]), (PG8_LAS unsigned*)(lds + (bufoff) + ldsw + _i * 8192), 16, 0, 0); } while (0)
; #define PG8_LDA(dst, b, h) do { _Pragma("unroll") for (int m = 0; m < 4; ++m) _Pragma("unroll") for (int k = 0; k < 2; ++k) dst[m][k] = *(const PG8_LAS bf16x8*)(lds + PG8_SA(b, h) + aoff + m * 2048 + k * 1024); } while (0)
; #define PG8_LDB(dst, b, h) do { _Pragma("unroll") for (int n = 0; n < 2; ++n) _Pragma("unroll") for (int k = 0; k < 2; ++k) dst[n][k] = *(const PG8_LAS bf16x8*)(lds + PG8_SB(b, h) + boff + n * 2048 + k * 1024); } while (0)
; template <class Epi, class Sched, bool ALIGN_EPI = false, bool SP2 = false>
; __device__ __forceinline__ void gemm_phase(PG8_LAS unsigned char* lds, const Gemm g, const Sched& S, const Epi& E) {
;     ...
;         for (int t = 0; t < nt; t += 2) {
;             const bool last = (t == nt - 2);
;             const char* a1 = cA + (size_t)(t + 1) * kstep;
;             const char* a2 = last ? nA : cA + (size_t)(t + 2) * kstep; const char* b2 = last ? nB : cB + (size_t)(t + 2) * kstep;
;             const char* a3 = a2 + kstep; const char* b3 = b2 + kstep;
;             if (last && has_next) S.a_ready(nxt);
;             if constexpr (SP2) {
;             PG8_LDB(B0, 0, 0); PG8_LDB(B1, 0, 1); PG8_SCHED; PG8_LDA(At, 0, 0); PG8_STAGE(PG8_SA(1, 1), a1 + hstep, voffA);
;             PG8_WAIT_V(8); PG8_WAIT_L(0); PG8_BAR; PG8_MMA(0, 0, At, B0); PG8_MMA(0, 1, At, B1); PG8_BAR; PG8_SCHED;
;             PG8_LDA(At, 0, 1); PG8_STAGE(PG8_SB(0, 0), b2, voffB); PG8_STAGE(PG8_SB(0, 1), b2 + hstep, voffB); PG8_STAGE(PG8_SA(0, 0), a2, voffA);
;             PG8_WAIT_V(8); PG8_WAIT_L(0); PG8_BAR; PG8_MMA(1, 0, At, B0); PG8_MMA(1, 1, At, B1); PG8_BAR; PG8_SCHED;
;             PG8_LDB(B0, 1, 0); PG8_LDB(B1, 1, 1); PG8_SCHED; PG8_LDA(At, 1, 0); PG8_STAGE(PG8_SA(0, 1), a2 + hstep, voffA);
;             PG8_WAIT_V(8); PG8_WAIT_L(0); PG8_BAR; PG8_MMA(0, 0, At, B0); PG8_MMA(0, 1, At, B1); PG8_BAR; PG8_SCHED;
;             PG8_LDA(At, 1, 1); PG8_STAGE(PG8_SB(1, 0), b3, voffB); PG8_STAGE(PG8_SB(1, 1), b3 + hstep, voffB); PG8_STAGE(PG8_SA(1, 0), a3, voffA);
;             PG8_WAIT_V(8); PG8_WAIT_L(0); PG8_BAR; PG8_MMA(1, 0, At, B0); PG8_MMA(1, 1, At, B1); PG8_BAR; PG8_SCHED;
.LBB0_1181:
	ds_read_b128 v[146:149], v154
	ds_read_b128 v[158:161], v154 offset:1024
	ds_read_b128 v[162:165], v154 offset:2048
	ds_read_b128 v[166:169], v154 offset:3072
	ds_read_b128 v[180:183], v155
	ds_read_b128 v[184:187], v155 offset:1024
	ds_read_b128 v[188:191], v155 offset:2048
	ds_read_b128 v[192:195], v155 offset:3072
	s_add_u32 s22, s20, 0xfff80080
	s_addc_u32 s23, s21, -1
	s_cmp_eq_u32 s48, 28
	s_cselect_b32 s25, s11, s23
	s_cselect_b32 s24, s44, s22
	s_cselect_b32 s23, s7, s47
	s_cselect_b32 s22, s45, s46
	s_add_i32 m0, s17, 0xc000
	ds_read_b128 v[196:199], v156
	ds_read_b128 v[200:203], v156 offset:1024
	ds_read_b128 v[204:207], v156 offset:2048
	ds_read_b128 v[208:211], v156 offset:3072
	ds_read_b128 v[212:215], v156 offset:4096
	ds_read_b128 v[216:219], v156 offset:5120
	ds_read_b128 v[220:223], v156 offset:6144
	ds_read_b128 v[224:227], v156 offset:7168
	global_load_lds_dwordx4 v138, s[20:21]
	s_add_i32 m0, s17, 0xe000
	s_nop 0
	global_load_lds_dwordx4 v140, s[20:21]
	s_waitcnt vmcnt(8)
	s_waitcnt lgkmcnt(0)
	s_barrier
	s_setprio 1
	s_waitcnt lgkmcnt(0)
	v_mfma_f32_16x16x32_bf16 v[124:127], v[146:149], v[196:199], v[124:127]
	v_mfma_f32_16x16x32_bf16 v[120:123], v[162:165], v[196:199], v[120:123]
	v_mfma_f32_16x16x32_bf16 v[112:115], v[146:149], v[204:207], v[112:115]
	v_mfma_f32_16x16x32_bf16 v[104:107], v[162:165], v[204:207], v[104:107]
	v_mfma_f32_16x16x32_bf16 v[96:99], v[146:149], v[212:215], v[96:99]
	v_mfma_f32_16x16x32_bf16 v[88:91], v[162:165], v[212:215], v[88:91]
	v_mfma_f32_16x16x32_bf16 v[80:83], v[146:149], v[220:223], v[80:83]
	v_mfma_f32_16x16x32_bf16 v[72:75], v[162:165], v[220:223], v[72:75]
	v_mfma_f32_16x16x32_bf16 v[124:127], v[158:161], v[200:203], v[124:127]
	v_mfma_f32_16x16x32_bf16 v[120:123], v[166:169], v[200:203], v[120:123]
	v_mfma_f32_16x16x32_bf16 v[112:115], v[158:161], v[208:211], v[112:115]
	v_mfma_f32_16x16x32_bf16 v[104:107], v[166:169], v[208:211], v[104:107]
	v_mfma_f32_16x16x32_bf16 v[96:99], v[158:161], v[216:219], v[96:99]
	v_mfma_f32_16x16x32_bf16 v[88:91], v[166:169], v[216:219], v[88:91]
	v_mfma_f32_16x16x32_bf16 v[80:83], v[158:161], v[224:227], v[80:83]
	v_mfma_f32_16x16x32_bf16 v[72:75], v[166:169], v[224:227], v[72:75]
	s_setprio 0
	s_setprio 1
	v_mfma_f32_16x16x32_bf16 v[116:119], v[180:183], v[196:199], v[116:119]
	v_mfma_f32_16x16x32_bf16 v[108:111], v[188:191], v[196:199], v[108:111]
	v_mfma_f32_16x16x32_bf16 v[100:103], v[180:183], v[204:207], v[100:103]
	v_mfma_f32_16x16x32_bf16 v[92:95], v[188:191], v[204:207], v[92:95]
	v_mfma_f32_16x16x32_bf16 v[84:87], v[180:183], v[212:215], v[84:87]
	v_mfma_f32_16x16x32_bf16 v[76:79], v[188:191], v[212:215], v[76:79]
	v_mfma_f32_16x16x32_bf16 v[68:71], v[180:183], v[220:223], v[68:71]
	v_mfma_f32_16x16x32_bf16 v[64:67], v[188:191], v[220:223], v[64:67]
	v_mfma_f32_16x16x32_bf16 v[116:119], v[184:187], v[200:203], v[116:119]
	v_mfma_f32_16x16x32_bf16 v[108:111], v[192:195], v[200:203], v[108:111]
	v_mfma_f32_16x16x32_bf16 v[100:103], v[184:187], v[208:211], v[100:103]
	v_mfma_f32_16x16x32_bf16 v[92:95], v[192:195], v[208:211], v[92:95]
	v_mfma_f32_16x16x32_bf16 v[84:87], v[184:187], v[216:219], v[84:87]
	v_mfma_f32_16x16x32_bf16 v[76:79], v[192:195], v[216:219], v[76:79]
	v_mfma_f32_16x16x32_bf16 v[68:71], v[184:187], v[224:227], v[68:71]
	v_mfma_f32_16x16x32_bf16 v[64:67], v[192:195], v[224:227], v[64:67]
	s_setprio 0
	s_barrier
	s_add_i32 s49, s35, s28
	v_lshl_add_u64 v[170:171], s[22:23], 0, v[132:133]
	s_mov_b32 m0, s49
	ds_read_b128 v[196:199], v156 offset:16384
	ds_read_b128 v[200:203], v156 offset:17408
	ds_read_b128 v[204:207], v156 offset:18432
	ds_read_b128 v[208:211], v156 offset:19456
	ds_read_b128 v[212:215], v156 offset:20480
	ds_read_b128 v[216:219], v156 offset:21504
	ds_read_b128 v[220:223], v156 offset:22528
	ds_read_b128 v[224:227], v156 offset:23552
	global_load_lds_dwordx4 v[170:171], off
	s_add_i32 m0, s49, 0x2000
	s_add_u32 s50, s22, 0x80000
	v_lshl_add_u64 v[228:229], s[22:23], 0, v[136:137]
	s_addc_u32 s51, s23, 0
	s_add_i32 s49, s36, s28
	global_load_lds_dwordx4 v[228:229], off
	s_mov_b32 m0, s49
	v_lshl_add_u64 v[232:233], s[24:25], 0, v[134:135]
	global_load_lds_dwordx4 v132, s[50:51]
	s_add_i32 m0, s49, 0x2000
	s_nop 0
	global_load_lds_dwordx4 v136, s[50:51]
	v_lshl_add_u64 v[230:231], s[24:25], 0, v[130:131]
	s_mov_b32 m0, s17
	s_nop 0
	global_load_lds_dwordx4 v[230:231], off
	s_mov_b32 m0, s29
	s_nop 0
	global_load_lds_dwordx4 v[232:233], off
	s_waitcnt vmcnt(8)
	s_waitcnt lgkmcnt(0)
	s_barrier
; #define PG8_STAGE(bufoff, gbase, voff) do { _Pragma("unroll") for (int _i = 0; _i < 2; ++_i) \
;         __builtin_amdgcn_global_load_lds((const unsigned*)((const char*)(gbase) + (voff)[_i]), (PG8_LAS unsigned*)(lds + (bufoff) + ldsw + _i * 8192), 16, 0, 0); } while (0)
; #define PG8_LDA(dst, b, h) do { _Pragma("unroll") for (int m = 0; m < 4; ++m) _Pragma("unroll") for (int k = 0; k < 2; ++k) dst[m][k] = *(const PG8_LAS bf16x8*)(lds + PG8_SA(b, h) + aoff + m * 2048 + k * 1024); } while (0)
; #define PG8_LDB(dst, b, h) do { _Pragma("unroll") for (int n = 0; n < 2; ++n) _Pragma("unroll") for (int k = 0; k < 2; ++k) dst[n][k] = *(const PG8_LAS bf16x8*)(lds + PG8_SB(b, h) + boff + n * 2048 + k * 1024); } while (0)
; template <class Epi, class Sched, bool ALIGN_EPI = false, bool SP2 = false>
; __device__ __forceinline__ void gemm_phase(PG8_LAS unsigned char* lds, const Gemm g, const Sched& S, const Epi& E) {
;     ...
;         for (int t = 0; t < nt; t += 2) {
;             const bool last = (t == nt - 2);
;             const char* a1 = cA + (size_t)(t + 1) * kstep;
;             const char* a2 = last ? nA : cA + (size_t)(t + 2) * kstep; const char* b2 = last ? nB : cB + (size_t)(t + 2) * kstep;
;             const char* a3 = a2 + kstep; const char* b3 = b2 + kstep;
;             if (last && has_next) S.a_ready(nxt);
;             if constexpr (SP2) {
;             PG8_LDB(B0, 0, 0); PG8_LDB(B1, 0, 1); PG8_SCHED; PG8_LDA(At, 0, 0); PG8_STAGE(PG8_SA(1, 1), a1 + hstep, voffA);
;             PG8_WAIT_V(8); PG8_WAIT_L(0); PG8_BAR; PG8_MMA(0, 0, At, B0); PG8_MMA(0, 1, At, B1); PG8_BAR; PG8_SCHED;
;             PG8_LDA(At, 0, 1); PG8_STAGE(PG8_SB(0, 0), b2, voffB); PG8_STAGE(PG8_SB(0, 1), b2 + hstep, voffB); PG8_STAGE(PG8_SA(0, 0), a2, voffA);
;             PG8_WAIT_V(8); PG8_WAIT_L(0); PG8_BAR; PG8_MMA(1, 0, At, B0); PG8_MMA(1, 1, At, B1); PG8_BAR; PG8_SCHED;
;             PG8_LDB(B0, 1, 0); PG8_LDB(B1, 1, 1); PG8_SCHED; PG8_LDA(At, 1, 0); PG8_STAGE(PG8_SA(0, 1), a2 + hstep, voffA);
;             PG8_WAIT_V(8); PG8_WAIT_L(0); PG8_BAR; PG8_MMA(0, 0, At, B0); PG8_MMA(0, 1, At, B1); PG8_BAR; PG8_SCHED;
;             PG8_LDA(At, 1, 1); PG8_STAGE(PG8_SB(1, 0), b3, voffB); PG8_STAGE(PG8_SB(1, 1), b3 + hstep, voffB); PG8_STAGE(PG8_SA(1, 0), a3, voffA);
;             PG8_WAIT_V(8); PG8_WAIT_L(0); PG8_BAR; PG8_MMA(1, 0, At, B0); PG8_MMA(1, 1, At, B1); PG8_BAR; PG8_SCHED;
	s_setprio 1
	s_waitcnt lgkmcnt(0)
	v_mfma_f32_16x16x32_bf16 v[60:63], v[146:149], v[196:199], v[60:63]
	v_mfma_f32_16x16x32_bf16 v[56:59], v[162:165], v[196:199], v[56:59]
	v_mfma_f32_16x16x32_bf16 v[52:55], v[146:149], v[204:207], v[52:55]
	v_mfma_f32_16x16x32_bf16 v[44:47], v[162:165], v[204:207], v[44:47]
	v_mfma_f32_16x16x32_bf16 v[36:39], v[146:149], v[212:215], v[36:39]
	v_mfma_f32_16x16x32_bf16 v[28:31], v[162:165], v[212:215], v[28:31]
	v_mfma_f32_16x16x32_bf16 v[20:23], v[146:149], v[220:223], v[20:23]
	v_mfma_f32_16x16x32_bf16 v[12:15], v[162:165], v[220:223], v[12:15]
	v_mfma_f32_16x16x32_bf16 v[60:63], v[158:161], v[200:203], v[60:63]
	v_mfma_f32_16x16x32_bf16 v[56:59], v[166:169], v[200:203], v[56:59]
	v_mfma_f32_16x16x32_bf16 v[52:55], v[158:161], v[208:211], v[52:55]
	v_mfma_f32_16x16x32_bf16 v[44:47], v[166:169], v[208:211], v[44:47]
	v_mfma_f32_16x16x32_bf16 v[36:39], v[158:161], v[216:219], v[36:39]
	v_mfma_f32_16x16x32_bf16 v[28:31], v[166:169], v[216:219], v[28:31]
	v_mfma_f32_16x16x32_bf16 v[20:23], v[158:161], v[224:227], v[20:23]
	v_mfma_f32_16x16x32_bf16 v[12:15], v[166:169], v[224:227], v[12:15]
	s_setprio 0
	s_setprio 1
	v_mfma_f32_16x16x32_bf16 v[48:51], v[180:183], v[196:199], v[48:51]
	v_mfma_f32_16x16x32_bf16 v[40:43], v[188:191], v[196:199], v[40:43]
	v_mfma_f32_16x16x32_bf16 v[32:35], v[180:183], v[204:207], v[32:35]
	v_mfma_f32_16x16x32_bf16 v[24:27], v[188:191], v[204:207], v[24:27]
	v_mfma_f32_16x16x32_bf16 v[16:19], v[180:183], v[212:215], v[16:19]
	v_mfma_f32_16x16x32_bf16 v[8:11], v[188:191], v[212:215], v[8:11]
	v_mfma_f32_16x16x32_bf16 v[4:7], v[180:183], v[220:223], v[4:7]
	v_mfma_f32_16x16x32_bf16 v[0:3], v[188:191], v[220:223], v[0:3]
	v_mfma_f32_16x16x32_bf16 v[48:51], v[184:187], v[200:203], v[48:51]
	v_mfma_f32_16x16x32_bf16 v[40:43], v[192:195], v[200:203], v[40:43]
	v_mfma_f32_16x16x32_bf16 v[32:35], v[184:187], v[208:211], v[32:35]
	v_mfma_f32_16x16x32_bf16 v[24:27], v[192:195], v[208:211], v[24:27]
	v_mfma_f32_16x16x32_bf16 v[16:19], v[184:187], v[216:219], v[16:19]
	v_mfma_f32_16x16x32_bf16 v[8:11], v[192:195], v[216:219], v[8:11]
	v_mfma_f32_16x16x32_bf16 v[4:7], v[184:187], v[224:227], v[4:7]
	v_mfma_f32_16x16x32_bf16 v[0:3], v[192:195], v[224:227], v[0:3]
	s_setprio 0
	s_barrier
	s_add_i32 s49, 0, 0x18000
	v_add_u32_e32 v157, s49, v151
	s_add_i32 s50, 0, 0x1c000
	ds_read_b128 v[146:149], v157
	ds_read_b128 v[158:161], v157 offset:1024
	ds_read_b128 v[162:165], v157 offset:2048
	ds_read_b128 v[166:169], v157 offset:3072
	v_add_u32_e32 v157, s50, v151
	ds_read_b128 v[180:183], v157
	ds_read_b128 v[184:187], v157 offset:1024
	ds_read_b128 v[188:191], v157 offset:2048
	ds_read_b128 v[192:195], v157 offset:3072
	s_add_u32 s24, s24, 0x80000
	s_addc_u32 s25, s25, 0
	s_mov_b32 m0, s30
	ds_read_b128 v[196:199], v156 offset:32768
	ds_read_b128 v[200:203], v156 offset:33792
	ds_read_b128 v[204:207], v156 offset:34816
	ds_read_b128 v[208:211], v156 offset:35840
	ds_read_b128 v[212:215], v156 offset:36864
	ds_read_b128 v[216:219], v156 offset:37888
	ds_read_b128 v[220:223], v156 offset:38912
	ds_read_b128 v[224:227], v156 offset:39936
	global_load_lds_dwordx4 v130, s[24:25]
	s_mov_b32 m0, s31
	s_nop 0
	global_load_lds_dwordx4 v134, s[24:25]
	s_waitcnt vmcnt(8)
	s_waitcnt lgkmcnt(0)
	s_barrier
	s_setprio 1
	s_waitcnt lgkmcnt(0)
	v_mfma_f32_16x16x32_bf16 v[124:127], v[146:149], v[196:199], v[124:127]
	v_mfma_f32_16x16x32_bf16 v[120:123], v[162:165], v[196:199], v[120:123]
	v_mfma_f32_16x16x32_bf16 v[112:115], v[146:149], v[204:207], v[112:115]
	v_mfma_f32_16x16x32_bf16 v[104:107], v[162:165], v[204:207], v[104:107]
	v_mfma_f32_16x16x32_bf16 v[96:99], v[146:149], v[212:215], v[96:99]
	v_mfma_f32_16x16x32_bf16 v[88:91], v[162:165], v[212:215], v[88:91]
	v_mfma_f32_16x16x32_bf16 v[80:83], v[146:149], v[220:223], v[80:83]
	v_mfma_f32_16x16x32_bf16 v[72:75], v[162:165], v[220:223], v[72:75]
	v_mfma_f32_16x16x32_bf16 v[124:127], v[158:161], v[200:203], v[124:127]
	v_mfma_f32_16x16x32_bf16 v[120:123], v[166:169], v[200:203], v[120:123]
	v_mfma_f32_16x16x32_bf16 v[112:115], v[158:161], v[208:211], v[112:115]
	v_mfma_f32_16x16x32_bf16 v[104:107], v[166:169], v[208:211], v[104:107]
	v_mfma_f32_16x16x32_bf16 v[96:99], v[158:161], v[216:219], v[96:99]
	v_mfma_f32_16x16x32_bf16 v[88:91], v[166:169], v[216:219], v[88:91]
	v_mfma_f32_16x16x32_bf16 v[80:83], v[158:161], v[224:227], v[80:83]
	v_mfma_f32_16x16x32_bf16 v[72:75], v[166:169], v[224:227], v[72:75]
	s_setprio 0
	s_setprio 1
	v_mfma_f32_16x16x32_bf16 v[116:119], v[180:183], v[196:199], v[116:119]
	v_mfma_f32_16x16x32_bf16 v[108:111], v[188:191], v[196:199], v[108:111]
	v_mfma_f32_16x16x32_bf16 v[100:103], v[180:183], v[204:207], v[100:103]
	v_mfma_f32_16x16x32_bf16 v[92:95], v[188:191], v[204:207], v[92:95]
	v_mfma_f32_16x16x32_bf16 v[84:87], v[180:183], v[212:215], v[84:87]
	v_mfma_f32_16x16x32_bf16 v[76:79], v[188:191], v[212:215], v[76:79]
	v_mfma_f32_16x16x32_bf16 v[68:71], v[180:183], v[220:223], v[68:71]
	v_mfma_f32_16x16x32_bf16 v[64:67], v[188:191], v[220:223], v[64:67]
	v_mfma_f32_16x16x32_bf16 v[116:119], v[184:187], v[200:203], v[116:119]
	v_mfma_f32_16x16x32_bf16 v[108:111], v[192:195], v[200:203], v[108:111]
	v_mfma_f32_16x16x32_bf16 v[100:103], v[184:187], v[208:211], v[100:103]
	v_mfma_f32_16x16x32_bf16 v[92:95], v[192:195], v[208:211], v[92:95]
	v_mfma_f32_16x16x32_bf16 v[84:87], v[184:187], v[216:219], v[84:87]
	v_mfma_f32_16x16x32_bf16 v[76:79], v[192:195], v[216:219], v[76:79]
	v_mfma_f32_16x16x32_bf16 v[68:71], v[184:187], v[224:227], v[68:71]
	v_mfma_f32_16x16x32_bf16 v[64:67], v[192:195], v[224:227], v[64:67]
	s_setprio 0
	s_barrier
; #define PG8_STAGE(bufoff, gbase, voff) do { _Pragma("unroll") for (int _i = 0; _i < 2; ++_i) \
;         __builtin_amdgcn_global_load_lds((const unsigned*)((const char*)(gbase) + (voff)[_i]), (PG8_LAS unsigned*)(lds + (bufoff) + ldsw + _i * 8192), 16, 0, 0); } while (0)
; #define PG8_LDA(dst, b, h) do { _Pragma("unroll") for (int m = 0; m < 4; ++m) _Pragma("unroll") for (int k = 0; k < 2; ++k) dst[m][k] = *(const PG8_LAS bf16x8*)(lds + PG8_SA(b, h) + aoff + m * 2048 + k * 1024); } while (0)
; #define PG8_LDB(dst, b, h) do { _Pragma("unroll") for (int n = 0; n < 2; ++n) _Pragma("unroll") for (int k = 0; k < 2; ++k) dst[n][k] = *(const PG8_LAS bf16x8*)(lds + PG8_SB(b, h) + boff + n * 2048 + k * 1024); } while (0)
; template <class Epi, class Sched, bool ALIGN_EPI = false, bool SP2 = false>
; __device__ __forceinline__ void gemm_phase(PG8_LAS unsigned char* lds, const Gemm g, const Sched& S, const Epi& E) {
;     ...
;         for (int t = 0; t < nt; t += 2) {
;             const bool last = (t == nt - 2);
;             const char* a1 = cA + (size_t)(t + 1) * kstep;
;             const char* a2 = last ? nA : cA + (size_t)(t + 2) * kstep; const char* b2 = last ? nB : cB + (size_t)(t + 2) * kstep;
;             const char* a3 = a2 + kstep; const char* b3 = b2 + kstep;
;             if (last && has_next) S.a_ready(nxt);
;             if constexpr (SP2) {
;             PG8_LDB(B0, 0, 0); PG8_LDB(B1, 0, 1); PG8_SCHED; PG8_LDA(At, 0, 0); PG8_STAGE(PG8_SA(1, 1), a1 + hstep, voffA);
;             PG8_WAIT_V(8); PG8_WAIT_L(0); PG8_BAR; PG8_MMA(0, 0, At, B0); PG8_MMA(0, 1, At, B1); PG8_BAR; PG8_SCHED;
;             PG8_LDA(At, 0, 1); PG8_STAGE(PG8_SB(0, 0), b2, voffB); PG8_STAGE(PG8_SB(0, 1), b2 + hstep, voffB); PG8_STAGE(PG8_SA(0, 0), a2, voffA);
;             PG8_WAIT_V(8); PG8_WAIT_L(0); PG8_BAR; PG8_MMA(1, 0, At, B0); PG8_MMA(1, 1, At, B1); PG8_BAR; PG8_SCHED;
;             PG8_LDB(B0, 1, 0); PG8_LDB(B1, 1, 1); PG8_SCHED; PG8_LDA(At, 1, 0); PG8_STAGE(PG8_SA(0, 1), a2 + hstep, voffA);
;             PG8_WAIT_V(8); PG8_WAIT_L(0); PG8_BAR; PG8_MMA(0, 0, At, B0); PG8_MMA(0, 1, At, B1); PG8_BAR; PG8_SCHED;
;             PG8_LDA(At, 1, 1); PG8_STAGE(PG8_SB(1, 0), b3, voffB); PG8_STAGE(PG8_SB(1, 1), b3 + hstep, voffB); PG8_STAGE(PG8_SA(1, 0), a3, voffA);
;             PG8_WAIT_V(8); PG8_WAIT_L(0); PG8_BAR; PG8_MMA(1, 0, At, B0); PG8_MMA(1, 1, At, B1); PG8_BAR; PG8_SCHED;
	s_add_i32 s24, s49, s28
	v_lshl_add_u64 v[170:171], v[170:171], 0, s[2:3]
	s_mov_b32 m0, s24
	ds_read_b128 v[196:199], v156 offset:49152
	ds_read_b128 v[200:203], v156 offset:50176
	ds_read_b128 v[204:207], v156 offset:51200
	ds_read_b128 v[208:211], v156 offset:52224
	ds_read_b128 v[212:215], v156 offset:53248
	ds_read_b128 v[216:219], v156 offset:54272
	ds_read_b128 v[220:223], v156 offset:55296
	ds_read_b128 v[224:227], v156 offset:56320
	global_load_lds_dwordx4 v[170:171], off
	s_add_i32 m0, s24, 0x2000
	s_add_u32 s22, s22, 0x80080
	v_lshl_add_u64 v[170:171], v[228:229], 0, s[2:3]
	s_addc_u32 s23, s23, 0
	s_add_i32 s24, s50, s28
	global_load_lds_dwordx4 v[170:171], off
	s_mov_b32 m0, s24
	s_nop 0
	global_load_lds_dwordx4 v132, s[22:23]
	s_add_i32 m0, s24, 0x2000
	s_nop 0
	global_load_lds_dwordx4 v136, s[22:23]
	v_lshl_add_u64 v[170:171], v[230:231], 0, s[2:3]
	s_mov_b32 m0, s33
	s_nop 0
	global_load_lds_dwordx4 v[170:171], off
	v_lshl_add_u64 v[170:171], v[232:233], 0, s[2:3]
	s_mov_b32 m0, s34
	s_nop 0
	global_load_lds_dwordx4 v[170:171], off
	s_waitcnt vmcnt(8)
	s_waitcnt lgkmcnt(0)
	s_barrier
	s_setprio 1
	s_waitcnt lgkmcnt(0)
	v_mfma_f32_16x16x32_bf16 v[60:63], v[146:149], v[196:199], v[60:63]
	v_mfma_f32_16x16x32_bf16 v[56:59], v[162:165], v[196:199], v[56:59]
	v_mfma_f32_16x16x32_bf16 v[52:55], v[146:149], v[204:207], v[52:55]
	v_mfma_f32_16x16x32_bf16 v[44:47], v[162:165], v[204:207], v[44:47]
	v_mfma_f32_16x16x32_bf16 v[36:39], v[146:149], v[212:215], v[36:39]
	v_mfma_f32_16x16x32_bf16 v[28:31], v[162:165], v[212:215], v[28:31]
	v_mfma_f32_16x16x32_bf16 v[20:23], v[146:149], v[220:223], v[20:23]
	v_mfma_f32_16x16x32_bf16 v[12:15], v[162:165], v[220:223], v[12:15]
	v_mfma_f32_16x16x32_bf16 v[60:63], v[158:161], v[200:203], v[60:63]
	v_mfma_f32_16x16x32_bf16 v[56:59], v[166:169], v[200:203], v[56:59]
	v_mfma_f32_16x16x32_bf16 v[52:55], v[158:161], v[208:211], v[52:55]
	v_mfma_f32_16x16x32_bf16 v[44:47], v[166:169], v[208:211], v[44:47]
	v_mfma_f32_16x16x32_bf16 v[36:39], v[158:161], v[216:219], v[36:39]
	v_mfma_f32_16x16x32_bf16 v[28:31], v[166:169], v[216:219], v[28:31]
	v_mfma_f32_16x16x32_bf16 v[20:23], v[158:161], v[224:227], v[20:23]
	v_mfma_f32_16x16x32_bf16 v[12:15], v[166:169], v[224:227], v[12:15]
	s_setprio 0
	s_setprio 1
	v_mfma_f32_16x16x32_bf16 v[48:51], v[180:183], v[196:199], v[48:51]
	v_mfma_f32_16x16x32_bf16 v[40:43], v[188:191], v[196:199], v[40:43]
	v_mfma_f32_16x16x32_bf16 v[32:35], v[180:183], v[204:207], v[32:35]
	v_mfma_f32_16x16x32_bf16 v[24:27], v[188:191], v[204:207], v[24:27]
	v_mfma_f32_16x16x32_bf16 v[16:19], v[180:183], v[212:215], v[16:19]
	v_mfma_f32_16x16x32_bf16 v[8:11], v[188:191], v[212:215], v[8:11]
	v_mfma_f32_16x16x32_bf16 v[4:7], v[180:183], v[220:223], v[4:7]
	v_mfma_f32_16x16x32_bf16 v[0:3], v[188:191], v[220:223], v[0:3]
	v_mfma_f32_16x16x32_bf16 v[48:51], v[184:187], v[200:203], v[48:51]
	v_mfma_f32_16x16x32_bf16 v[40:43], v[192:195], v[200:203], v[40:43]
	v_mfma_f32_16x16x32_bf16 v[32:35], v[184:187], v[208:211], v[32:35]
	v_mfma_f32_16x16x32_bf16 v[24:27], v[192:195], v[208:211], v[24:27]
	v_mfma_f32_16x16x32_bf16 v[16:19], v[184:187], v[216:219], v[16:19]
	v_mfma_f32_16x16x32_bf16 v[8:11], v[192:195], v[216:219], v[8:11]
	v_mfma_f32_16x16x32_bf16 v[4:7], v[184:187], v[224:227], v[4:7]
	v_mfma_f32_16x16x32_bf16 v[0:3], v[192:195], v[224:227], v[0:3]
	s_setprio 0
	s_barrier
	s_add_i32 s48, s48, 2
	s_add_u32 s20, s20, 0x100
	s_addc_u32 s21, s21, 0
	s_add_u32 s46, s46, 0x100
	s_addc_u32 s47, s47, 0
	s_cmp_gt_u32 s48, 29
	s_cbranch_scc0 .LBB0_1181
	s_nop 0
	v_readfirstlane_b32 s7, v172
	s_nop 3
	s_lshr_b32 s7, s7, 6
	s_cmp_lt_u32 s7, 4
	s_cbranch_scc0 .Lprio_k4
	s_setprio 1

; #define PG8_STAGE(bufoff, gbase, voff) do { _Pragma("unroll") for (int _i = 0; _i < 2; ++_i) \
;         __builtin_amdgcn_global_load_lds((const unsigned*)((const char*)(gbase) + (voff)[_i]), (PG8_LAS unsigned*)(lds + (bufoff) + ldsw + _i * 8192), 16, 0, 0); } while (0)
; #define PG8_WAIT_V(n) asm volatile("s_waitcnt vmcnt(" #n ")" ::: "memory")
; #define PG8_BAR __builtin_amdgcn_s_barrier()
; template <class Epi, class Sched, bool ALIGN_EPI = false, bool SP2 = false>
; __device__ __forceinline__ void gemm_phase(PG8_LAS unsigned char* lds, const Gemm g, const Sched& S, const Epi& E) {
;     ...
;     if constexpr (SP2) {
;         PG8_STAGE(PG8_SB(0, 0), cB, voffB); PG8_STAGE(PG8_SB(0, 1), cB + hstep, voffB); PG8_STAGE(PG8_SA(0, 0), cA, voffA); PG8_STAGE(PG8_SA(0, 1), cA + hstep, voffA);
;         if (wr == 1) PG8_BAR;
;         PG8_WAIT_V(2); PG8_BAR;
;         PG8_STAGE(PG8_SB(1, 0), cB + kstep, voffB); PG8_STAGE(PG8_SA(1, 0), cA + kstep, voffA); PG8_STAGE(PG8_SB(1, 1), cB + hstep + kstep, voffB);
;         PG8_WAIT_V(6); PG8_BAR;
;     } else {
;         PG8_STAGE(PG8_SB(0, 0), cB, voffB); PG8_STAGE(PG8_SA(0, 0), cA, voffA); PG8_STAGE(PG8_SB(0, 1), cB + hstep, voffB); PG8_STAGE(PG8_SA(0, 1), cA + hstep, voffA);
;         if (wr == 1) PG8_BAR;
;         PG8_WAIT_V(4); PG8_BAR;
;         PG8_STAGE(PG8_SB(1, 0), cB + kstep, voffB); PG8_STAGE(PG8_SA(1, 0), cA + kstep, voffA); PG8_STAGE(PG8_SB(1, 1), cB + hstep + kstep, voffB);
;         PG8_WAIT_V(6); PG8_BAR;
;     }
;     for (;;) {
;         const bool has_next = S.next(ui + 1, nxt);
;         const char* nA = has_next ? (const char*)g.A + (size_t)nxt.pm * tstep : cA; const char* nB = has_next ? (const char*)g.Bt + (size_t)nxt.pn * tstep : cB;
.LBB0_1447:
	v_bfe_u32 v17, v9, 4, 2
	v_and_b32_e32 v18, 15, v9
	v_lshlrev_b32_e32 v19, 4, v17
	v_lshlrev_b32_e32 v9, 2, v9
	s_and_b32 s38, s4, 3
	v_lshl_or_b32 v148, s5, 6, v18
	v_lshl_or_b32 v18, v18, 6, v19
	s_lshl_b32 s4, s5, 13
	v_and_b32_e32 v9, 32, v9
	v_bitop3_b32 v19, v18, s4, v9 bitop3:0xde
	s_lshl_b32 s4, s38, 12
	v_bitop3_b32 v149, v18, s4, v9 bitop3:0xde
	s_mov_b64 s[4:5], 0x80
	s_add_i32 m0, s34, 0x18000
	v_lshl_add_u64 v[6:7], v[6:7], 0, s[4:5]
	s_waitcnt vmcnt(2)
	s_barrier
	global_load_lds_dwordx4 v[6:7], off
	v_lshl_add_u64 v[4:5], v[4:5], 0, s[4:5]
	s_add_i32 m0, s34, 0x1a000
	s_add_i32 s39, s34, 0x8000
	s_add_i32 s40, s34, 0xa000
	global_load_lds_dwordx4 v[4:5], off
	v_lshl_add_u64 v[0:1], v[0:1], 0, s[4:5]
	s_mov_b32 m0, s39
	s_add_u32 s8, s24, 0x80080
	global_load_lds_dwordx4 v[0:1], off
	v_lshl_add_u64 v[0:1], v[2:3], 0, s[4:5]
	s_mov_b32 m0, s40
	s_addc_u32 s9, s25, 0
	global_load_lds_dwordx4 v[0:1], off
	s_add_i32 m0, s34, 0x1c000
	s_nop 0
	global_load_lds_dwordx4 v130, s[8:9]
	s_add_i32 m0, s34, 0x1e000
	s_mov_b64 s[10:11], 0x80080
	global_load_lds_dwordx4 v132, s[8:9]
	v_lshlrev_b32_e32 v0, 2, v17
	v_lshl_or_b32 v150, s38, 5, v0
	v_lshlrev_b32_e32 v0, 14, v8
	v_and_b32_e32 v0, 0x7fff8000, v0
	v_lshl_add_u32 v0, v10, 11, v0
	v_or_b32_e32 v0, v0, v11
	v_add_lshl_u32 v0, v0, v12, 1
	v_mov_b32_e32 v1, v131
	v_lshl_add_u64 v[134:135], v[0:1], 0, s[10:11]
	v_lshlrev_b32_e32 v0, 14, v13
	v_and_b32_e32 v0, 0x7fff8000, v0
	v_lshl_add_u32 v0, v14, 11, v0
	s_waitcnt vmcnt(6)
	s_cmpk_lt_u32 s6, 0x100
	v_or_b32_e32 v0, v0, v15
	s_cselect_b64 s[6:7], -1, 0
	v_add_lshl_u32 v0, v0, v16, 1
	s_add_i32 s41, 0, 0x10000
	s_add_i32 s42, 0, 0x14000
	v_cmp_eq_u32_e64 s[8:9], 0, v17
	v_lshl_add_u64 v[136:137], v[0:1], 0, s[10:11]
	v_mov_b64_e32 v[138:139], 0x100
	v_mov_b64_e32 v[140:141], 0xff
	v_add_u32_e32 v151, s41, v149
	v_add_u32_e32 v152, s42, v149
	v_add_u32_e32 v153, 0, v19
	s_mov_b32 s43, 0
	s_barrier
	s_branch .LBB0_1450

; #define PG8_STAGE(bufoff, gbase, voff) do { _Pragma("unroll") for (int _i = 0; _i < 2; ++_i) \
;         __builtin_amdgcn_global_load_lds((const unsigned*)((const char*)(gbase) + (voff)[_i]), (PG8_LAS unsigned*)(lds + (bufoff) + ldsw + _i * 8192), 16, 0, 0); } while (0)
; #define PG8_LDA(dst, b, h) do { _Pragma("unroll") for (int m = 0; m < 4; ++m) _Pragma("unroll") for (int k = 0; k < 2; ++k) dst[m][k] = *(const PG8_LAS bf16x8*)(lds + PG8_SA(b, h) + aoff + m * 2048 + k * 1024); } while (0)
; #define PG8_LDB(dst, b, h) do { _Pragma("unroll") for (int n = 0; n < 2; ++n) _Pragma("unroll") for (int k = 0; k < 2; ++k) dst[n][k] = *(const PG8_LAS bf16x8*)(lds + PG8_SB(b, h) + boff + n * 2048 + k * 1024); } while (0)
; template <class Epi, class Sched, bool ALIGN_EPI = false, bool SP2 = false>
; __device__ __forceinline__ void gemm_phase(PG8_LAS unsigned char* lds, const Gemm g, const Sched& S, const Epi& E) {
;     ...
;         for (int t = 0; t < nt; t += 2) {
;             const bool last = (t == nt - 2);
;             const char* a1 = cA + (size_t)(t + 1) * kstep;
;             const char* a2 = last ? nA : cA + (size_t)(t + 2) * kstep; const char* b2 = last ? nB : cB + (size_t)(t + 2) * kstep;
;             const char* a3 = a2 + kstep; const char* b3 = b2 + kstep;
;             if (last && has_next) S.a_ready(nxt);
;             if constexpr (SP2) {
;             PG8_LDB(B0, 0, 0); PG8_LDB(B1, 0, 1); PG8_SCHED; PG8_LDA(At, 0, 0); PG8_STAGE(PG8_SA(1, 1), a1 + hstep, voffA);
;             PG8_WAIT_V(8); PG8_WAIT_L(0); PG8_BAR; PG8_MMA(0, 0, At, B0); PG8_MMA(0, 1, At, B1); PG8_BAR; PG8_SCHED;
;             PG8_LDA(At, 0, 1); PG8_STAGE(PG8_SB(0, 0), b2, voffB); PG8_STAGE(PG8_SB(0, 1), b2 + hstep, voffB); PG8_STAGE(PG8_SA(0, 0), a2, voffA);
;             PG8_WAIT_V(8); PG8_WAIT_L(0); PG8_BAR; PG8_MMA(1, 0, At, B0); PG8_MMA(1, 1, At, B1); PG8_BAR; PG8_SCHED;
;             PG8_LDB(B0, 1, 0); PG8_LDB(B1, 1, 1); PG8_SCHED; PG8_LDA(At, 1, 0); PG8_STAGE(PG8_SA(0, 1), a2 + hstep, voffA);
;             PG8_WAIT_V(8); PG8_WAIT_L(0); PG8_BAR; PG8_MMA(0, 0, At, B0); PG8_MMA(0, 1, At, B1); PG8_BAR; PG8_SCHED;
;             PG8_LDA(At, 1, 1); PG8_STAGE(PG8_SB(1, 0), b3, voffB); PG8_STAGE(PG8_SB(1, 1), b3 + hstep, voffB); PG8_STAGE(PG8_SA(1, 0), a3, voffA);
;             PG8_WAIT_V(8); PG8_WAIT_L(0); PG8_BAR; PG8_MMA(1, 0, At, B0); PG8_MMA(1, 1, At, B1); PG8_BAR; PG8_SCHED;
.LBB0_1457:
	ds_read_b128 v[142:145], v151
	ds_read_b128 v[154:157], v151 offset:1024
	ds_read_b128 v[158:161], v151 offset:2048
	ds_read_b128 v[162:165], v151 offset:3072
	ds_read_b128 v[166:169], v152
	ds_read_b128 v[178:181], v152 offset:1024
	ds_read_b128 v[182:185], v152 offset:2048
	ds_read_b128 v[186:189], v152 offset:3072
	s_add_u32 s24, s22, 0x100
	s_addc_u32 s25, s23, 0
	s_cmp_eq_u32 s47, 28
	s_cselect_b32 s29, s15, s25
	s_cselect_b32 s28, s21, s24
	s_cselect_b32 s27, s13, s46
	s_cselect_b32 s26, s44, s45
	s_add_i32 m0, s34, 0xc000
	ds_read_b128 v[190:193], v153
	ds_read_b128 v[194:197], v153 offset:1024
	ds_read_b128 v[198:201], v153 offset:2048
	ds_read_b128 v[202:205], v153 offset:3072
	ds_read_b128 v[206:209], v153 offset:4096
	ds_read_b128 v[210:213], v153 offset:5120
	ds_read_b128 v[214:217], v153 offset:6144
	ds_read_b128 v[218:221], v153 offset:7168
	global_load_lds_dwordx4 v134, s[22:23]
	s_add_i32 m0, s34, 0xe000
	s_nop 0
	global_load_lds_dwordx4 v136, s[22:23]
	s_waitcnt vmcnt(8)
	s_waitcnt lgkmcnt(0)
	s_barrier
	s_setprio 1
	s_waitcnt lgkmcnt(0)
	v_mfma_f32_16x16x32_bf16 v[124:127], v[142:145], v[190:193], v[124:127]
	v_mfma_f32_16x16x32_bf16 v[120:123], v[158:161], v[190:193], v[120:123]
	v_mfma_f32_16x16x32_bf16 v[108:111], v[142:145], v[198:201], v[108:111]
	v_mfma_f32_16x16x32_bf16 v[104:107], v[158:161], v[198:201], v[104:107]
	v_mfma_f32_16x16x32_bf16 v[92:95], v[142:145], v[206:209], v[92:95]
	v_mfma_f32_16x16x32_bf16 v[88:91], v[158:161], v[206:209], v[88:91]
	v_mfma_f32_16x16x32_bf16 v[76:79], v[142:145], v[214:217], v[76:79]
	v_mfma_f32_16x16x32_bf16 v[72:75], v[158:161], v[214:217], v[72:75]
	v_mfma_f32_16x16x32_bf16 v[124:127], v[154:157], v[194:197], v[124:127]
	v_mfma_f32_16x16x32_bf16 v[120:123], v[162:165], v[194:197], v[120:123]
	v_mfma_f32_16x16x32_bf16 v[108:111], v[154:157], v[202:205], v[108:111]
	v_mfma_f32_16x16x32_bf16 v[104:107], v[162:165], v[202:205], v[104:107]
	v_mfma_f32_16x16x32_bf16 v[92:95], v[154:157], v[210:213], v[92:95]
	v_mfma_f32_16x16x32_bf16 v[88:91], v[162:165], v[210:213], v[88:91]
	v_mfma_f32_16x16x32_bf16 v[76:79], v[154:157], v[218:221], v[76:79]
	v_mfma_f32_16x16x32_bf16 v[72:75], v[162:165], v[218:221], v[72:75]
	s_setprio 0
	s_setprio 1
	v_mfma_f32_16x16x32_bf16 v[116:119], v[166:169], v[190:193], v[116:119]
	v_mfma_f32_16x16x32_bf16 v[112:115], v[182:185], v[190:193], v[112:115]
	v_mfma_f32_16x16x32_bf16 v[100:103], v[166:169], v[198:201], v[100:103]
	v_mfma_f32_16x16x32_bf16 v[96:99], v[182:185], v[198:201], v[96:99]
	v_mfma_f32_16x16x32_bf16 v[84:87], v[166:169], v[206:209], v[84:87]
	v_mfma_f32_16x16x32_bf16 v[80:83], v[182:185], v[206:209], v[80:83]
	v_mfma_f32_16x16x32_bf16 v[68:71], v[166:169], v[214:217], v[68:71]
	v_mfma_f32_16x16x32_bf16 v[64:67], v[182:185], v[214:217], v[64:67]
	v_mfma_f32_16x16x32_bf16 v[116:119], v[178:181], v[194:197], v[116:119]
	v_mfma_f32_16x16x32_bf16 v[112:115], v[186:189], v[194:197], v[112:115]
	v_mfma_f32_16x16x32_bf16 v[100:103], v[178:181], v[202:205], v[100:103]
	v_mfma_f32_16x16x32_bf16 v[96:99], v[186:189], v[202:205], v[96:99]
	v_mfma_f32_16x16x32_bf16 v[84:87], v[178:181], v[210:213], v[84:87]
	v_mfma_f32_16x16x32_bf16 v[80:83], v[186:189], v[210:213], v[80:83]
	v_mfma_f32_16x16x32_bf16 v[68:71], v[178:181], v[218:221], v[68:71]
	v_mfma_f32_16x16x32_bf16 v[64:67], v[186:189], v[218:221], v[64:67]
	s_setprio 0
	s_barrier
	s_add_i32 s22, s41, s33
	v_lshl_add_u64 v[146:147], s[26:27], 0, v[130:131]
	s_mov_b32 m0, s22
	ds_read_b128 v[190:193], v153 offset:16384
	ds_read_b128 v[194:197], v153 offset:17408
	ds_read_b128 v[198:201], v153 offset:18432
	ds_read_b128 v[202:205], v153 offset:19456
	ds_read_b128 v[206:209], v153 offset:20480
	ds_read_b128 v[210:213], v153 offset:21504
	ds_read_b128 v[214:217], v153 offset:22528
	ds_read_b128 v[218:221], v153 offset:23552
	global_load_lds_dwordx4 v[146:147], off
	s_add_i32 m0, s22, 0x2000
	s_add_u32 s22, s26, 0x80000
	v_lshl_add_u64 v[170:171], s[26:27], 0, v[132:133]
	s_addc_u32 s23, s27, 0
	s_add_i32 s48, s42, s33
	global_load_lds_dwordx4 v[170:171], off
	s_mov_b32 m0, s48
	v_lshl_add_u64 v[224:225], s[28:29], 0, v[132:133]
	global_load_lds_dwordx4 v130, s[22:23]
	s_add_i32 m0, s48, 0x2000
	s_nop 0
	global_load_lds_dwordx4 v132, s[22:23]
	v_lshl_add_u64 v[222:223], s[28:29], 0, v[130:131]
	s_mov_b32 m0, s34
	s_nop 0
	global_load_lds_dwordx4 v[222:223], off
	s_mov_b32 m0, s35
	s_nop 0
	global_load_lds_dwordx4 v[224:225], off
	s_waitcnt vmcnt(8)
	s_waitcnt lgkmcnt(0)
	s_barrier
; #define PG8_STAGE(bufoff, gbase, voff) do { _Pragma("unroll") for (int _i = 0; _i < 2; ++_i) \
;         __builtin_amdgcn_global_load_lds((const unsigned*)((const char*)(gbase) + (voff)[_i]), (PG8_LAS unsigned*)(lds + (bufoff) + ldsw + _i * 8192), 16, 0, 0); } while (0)
; #define PG8_LDA(dst, b, h) do { _Pragma("unroll") for (int m = 0; m < 4; ++m) _Pragma("unroll") for (int k = 0; k < 2; ++k) dst[m][k] = *(const PG8_LAS bf16x8*)(lds + PG8_SA(b, h) + aoff + m * 2048 + k * 1024); } while (0)
; #define PG8_LDB(dst, b, h) do { _Pragma("unroll") for (int n = 0; n < 2; ++n) _Pragma("unroll") for (int k = 0; k < 2; ++k) dst[n][k] = *(const PG8_LAS bf16x8*)(lds + PG8_SB(b, h) + boff + n * 2048 + k * 1024); } while (0)
; template <class Epi, class Sched, bool ALIGN_EPI = false, bool SP2 = false>
; __device__ __forceinline__ void gemm_phase(PG8_LAS unsigned char* lds, const Gemm g, const Sched& S, const Epi& E) {
;     ...
;         for (int t = 0; t < nt; t += 2) {
;             const bool last = (t == nt - 2);
;             const char* a1 = cA + (size_t)(t + 1) * kstep;
;             const char* a2 = last ? nA : cA + (size_t)(t + 2) * kstep; const char* b2 = last ? nB : cB + (size_t)(t + 2) * kstep;
;             const char* a3 = a2 + kstep; const char* b3 = b2 + kstep;
;             if (last && has_next) S.a_ready(nxt);
;             if constexpr (SP2) {
;             PG8_LDB(B0, 0, 0); PG8_LDB(B1, 0, 1); PG8_SCHED; PG8_LDA(At, 0, 0); PG8_STAGE(PG8_SA(1, 1), a1 + hstep, voffA);
;             PG8_WAIT_V(8); PG8_WAIT_L(0); PG8_BAR; PG8_MMA(0, 0, At, B0); PG8_MMA(0, 1, At, B1); PG8_BAR; PG8_SCHED;
;             PG8_LDA(At, 0, 1); PG8_STAGE(PG8_SB(0, 0), b2, voffB); PG8_STAGE(PG8_SB(0, 1), b2 + hstep, voffB); PG8_STAGE(PG8_SA(0, 0), a2, voffA);
;             PG8_WAIT_V(8); PG8_WAIT_L(0); PG8_BAR; PG8_MMA(1, 0, At, B0); PG8_MMA(1, 1, At, B1); PG8_BAR; PG8_SCHED;
;             PG8_LDB(B0, 1, 0); PG8_LDB(B1, 1, 1); PG8_SCHED; PG8_LDA(At, 1, 0); PG8_STAGE(PG8_SA(0, 1), a2 + hstep, voffA);
;             PG8_WAIT_V(8); PG8_WAIT_L(0); PG8_BAR; PG8_MMA(0, 0, At, B0); PG8_MMA(0, 1, At, B1); PG8_BAR; PG8_SCHED;
;             PG8_LDA(At, 1, 1); PG8_STAGE(PG8_SB(1, 0), b3, voffB); PG8_STAGE(PG8_SB(1, 1), b3 + hstep, voffB); PG8_STAGE(PG8_SA(1, 0), a3, voffA);
;             PG8_WAIT_V(8); PG8_WAIT_L(0); PG8_BAR; PG8_MMA(1, 0, At, B0); PG8_MMA(1, 1, At, B1); PG8_BAR; PG8_SCHED;
	s_setprio 1
	s_waitcnt lgkmcnt(0)
	v_mfma_f32_16x16x32_bf16 v[60:63], v[142:145], v[190:193], v[60:63]
	v_mfma_f32_16x16x32_bf16 v[56:59], v[158:161], v[190:193], v[56:59]
	v_mfma_f32_16x16x32_bf16 v[44:47], v[142:145], v[198:201], v[44:47]
	v_mfma_f32_16x16x32_bf16 v[40:43], v[158:161], v[198:201], v[40:43]
	v_mfma_f32_16x16x32_bf16 v[28:31], v[142:145], v[206:209], v[28:31]
	v_mfma_f32_16x16x32_bf16 v[24:27], v[158:161], v[206:209], v[24:27]
	v_mfma_f32_16x16x32_bf16 v[12:15], v[142:145], v[214:217], v[12:15]
	v_mfma_f32_16x16x32_bf16 v[8:11], v[158:161], v[214:217], v[8:11]
	v_mfma_f32_16x16x32_bf16 v[60:63], v[154:157], v[194:197], v[60:63]
	v_mfma_f32_16x16x32_bf16 v[56:59], v[162:165], v[194:197], v[56:59]
	v_mfma_f32_16x16x32_bf16 v[44:47], v[154:157], v[202:205], v[44:47]
	v_mfma_f32_16x16x32_bf16 v[40:43], v[162:165], v[202:205], v[40:43]
	v_mfma_f32_16x16x32_bf16 v[28:31], v[154:157], v[210:213], v[28:31]
	v_mfma_f32_16x16x32_bf16 v[24:27], v[162:165], v[210:213], v[24:27]
	v_mfma_f32_16x16x32_bf16 v[12:15], v[154:157], v[218:221], v[12:15]
	v_mfma_f32_16x16x32_bf16 v[8:11], v[162:165], v[218:221], v[8:11]
	s_setprio 0
	s_setprio 1
	v_mfma_f32_16x16x32_bf16 v[52:55], v[166:169], v[190:193], v[52:55]
	v_mfma_f32_16x16x32_bf16 v[48:51], v[182:185], v[190:193], v[48:51]
	v_mfma_f32_16x16x32_bf16 v[36:39], v[166:169], v[198:201], v[36:39]
	v_mfma_f32_16x16x32_bf16 v[32:35], v[182:185], v[198:201], v[32:35]
	v_mfma_f32_16x16x32_bf16 v[20:23], v[166:169], v[206:209], v[20:23]
	v_mfma_f32_16x16x32_bf16 v[16:19], v[182:185], v[206:209], v[16:19]
	v_mfma_f32_16x16x32_bf16 v[4:7], v[166:169], v[214:217], v[4:7]
	v_mfma_f32_16x16x32_bf16 v[0:3], v[182:185], v[214:217], v[0:3]
	v_mfma_f32_16x16x32_bf16 v[52:55], v[178:181], v[194:197], v[52:55]
	v_mfma_f32_16x16x32_bf16 v[48:51], v[186:189], v[194:197], v[48:51]
	v_mfma_f32_16x16x32_bf16 v[36:39], v[178:181], v[202:205], v[36:39]
	v_mfma_f32_16x16x32_bf16 v[32:35], v[186:189], v[202:205], v[32:35]
	v_mfma_f32_16x16x32_bf16 v[20:23], v[178:181], v[210:213], v[20:23]
	v_mfma_f32_16x16x32_bf16 v[16:19], v[186:189], v[210:213], v[16:19]
	v_mfma_f32_16x16x32_bf16 v[4:7], v[178:181], v[218:221], v[4:7]
	v_mfma_f32_16x16x32_bf16 v[0:3], v[186:189], v[218:221], v[0:3]
	s_setprio 0
	s_barrier
	s_add_i32 s48, 0, 0x18000
	s_add_i32 s49, 0, 0x1c000
	v_add_u32_e32 v162, s48, v149
	v_add_u32_e32 v186, s49, v149
	ds_read_b128 v[142:145], v162
	ds_read_b128 v[154:157], v162 offset:1024
	ds_read_b128 v[158:161], v162 offset:2048
	ds_read_b128 v[162:165], v162 offset:3072
	ds_read_b128 v[166:169], v186
	ds_read_b128 v[178:181], v186 offset:1024
	ds_read_b128 v[182:185], v186 offset:2048
	ds_read_b128 v[186:189], v186 offset:3072
	s_add_u32 s22, s28, 0x80000
	s_addc_u32 s23, s29, 0
	s_mov_b32 m0, s36
	ds_read_b128 v[190:193], v153 offset:32768
	ds_read_b128 v[194:197], v153 offset:33792
	ds_read_b128 v[198:201], v153 offset:34816
	ds_read_b128 v[202:205], v153 offset:35840
	ds_read_b128 v[206:209], v153 offset:36864
	ds_read_b128 v[210:213], v153 offset:37888
	ds_read_b128 v[214:217], v153 offset:38912
	ds_read_b128 v[218:221], v153 offset:39936
	global_load_lds_dwordx4 v130, s[22:23]
	s_mov_b32 m0, s37
	s_nop 0
	global_load_lds_dwordx4 v132, s[22:23]
	s_waitcnt vmcnt(8)
	s_waitcnt lgkmcnt(0)
	s_barrier
	s_setprio 1
	s_waitcnt lgkmcnt(0)
	v_mfma_f32_16x16x32_bf16 v[124:127], v[142:145], v[190:193], v[124:127]
	v_mfma_f32_16x16x32_bf16 v[120:123], v[158:161], v[190:193], v[120:123]
	v_mfma_f32_16x16x32_bf16 v[108:111], v[142:145], v[198:201], v[108:111]
	v_mfma_f32_16x16x32_bf16 v[104:107], v[158:161], v[198:201], v[104:107]
	v_mfma_f32_16x16x32_bf16 v[92:95], v[142:145], v[206:209], v[92:95]
	v_mfma_f32_16x16x32_bf16 v[88:91], v[158:161], v[206:209], v[88:91]
	v_mfma_f32_16x16x32_bf16 v[76:79], v[142:145], v[214:217], v[76:79]
	v_mfma_f32_16x16x32_bf16 v[72:75], v[158:161], v[214:217], v[72:75]
	v_mfma_f32_16x16x32_bf16 v[124:127], v[154:157], v[194:197], v[124:127]
	v_mfma_f32_16x16x32_bf16 v[120:123], v[162:165], v[194:197], v[120:123]
	v_mfma_f32_16x16x32_bf16 v[108:111], v[154:157], v[202:205], v[108:111]
	v_mfma_f32_16x16x32_bf16 v[104:107], v[162:165], v[202:205], v[104:107]
	v_mfma_f32_16x16x32_bf16 v[92:95], v[154:157], v[210:213], v[92:95]
	v_mfma_f32_16x16x32_bf16 v[88:91], v[162:165], v[210:213], v[88:91]
	v_mfma_f32_16x16x32_bf16 v[76:79], v[154:157], v[218:221], v[76:79]
	v_mfma_f32_16x16x32_bf16 v[72:75], v[162:165], v[218:221], v[72:75]
	s_setprio 0
	s_setprio 1
	v_mfma_f32_16x16x32_bf16 v[116:119], v[166:169], v[190:193], v[116:119]
	v_mfma_f32_16x16x32_bf16 v[112:115], v[182:185], v[190:193], v[112:115]
	v_mfma_f32_16x16x32_bf16 v[100:103], v[166:169], v[198:201], v[100:103]
	v_mfma_f32_16x16x32_bf16 v[96:99], v[182:185], v[198:201], v[96:99]
	v_mfma_f32_16x16x32_bf16 v[84:87], v[166:169], v[206:209], v[84:87]
	v_mfma_f32_16x16x32_bf16 v[80:83], v[182:185], v[206:209], v[80:83]
	v_mfma_f32_16x16x32_bf16 v[68:71], v[166:169], v[214:217], v[68:71]
	v_mfma_f32_16x16x32_bf16 v[64:67], v[182:185], v[214:217], v[64:67]
	v_mfma_f32_16x16x32_bf16 v[116:119], v[178:181], v[194:197], v[116:119]
	v_mfma_f32_16x16x32_bf16 v[112:115], v[186:189], v[194:197], v[112:115]
	v_mfma_f32_16x16x32_bf16 v[100:103], v[178:181], v[202:205], v[100:103]
	v_mfma_f32_16x16x32_bf16 v[96:99], v[186:189], v[202:205], v[96:99]
	v_mfma_f32_16x16x32_bf16 v[84:87], v[178:181], v[210:213], v[84:87]
	v_mfma_f32_16x16x32_bf16 v[80:83], v[186:189], v[210:213], v[80:83]
	v_mfma_f32_16x16x32_bf16 v[68:71], v[178:181], v[218:221], v[68:71]
	v_mfma_f32_16x16x32_bf16 v[64:67], v[186:189], v[218:221], v[64:67]
	s_setprio 0
	s_barrier
; #define PG8_STAGE(bufoff, gbase, voff) do { _Pragma("unroll") for (int _i = 0; _i < 2; ++_i) \
;         __builtin_amdgcn_global_load_lds((const unsigned*)((const char*)(gbase) + (voff)[_i]), (PG8_LAS unsigned*)(lds + (bufoff) + ldsw + _i * 8192), 16, 0, 0); } while (0)
; #define PG8_LDA(dst, b, h) do { _Pragma("unroll") for (int m = 0; m < 4; ++m) _Pragma("unroll") for (int k = 0; k < 2; ++k) dst[m][k] = *(const PG8_LAS bf16x8*)(lds + PG8_SA(b, h) + aoff + m * 2048 + k * 1024); } while (0)
; #define PG8_LDB(dst, b, h) do { _Pragma("unroll") for (int n = 0; n < 2; ++n) _Pragma("unroll") for (int k = 0; k < 2; ++k) dst[n][k] = *(const PG8_LAS bf16x8*)(lds + PG8_SB(b, h) + boff + n * 2048 + k * 1024); } while (0)
; template <class Epi, class Sched, bool ALIGN_EPI = false, bool SP2 = false>
; __device__ __forceinline__ void gemm_phase(PG8_LAS unsigned char* lds, const Gemm g, const Sched& S, const Epi& E) {
;     ...
;         for (int t = 0; t < nt; t += 2) {
;             const bool last = (t == nt - 2);
;             const char* a1 = cA + (size_t)(t + 1) * kstep;
;             const char* a2 = last ? nA : cA + (size_t)(t + 2) * kstep; const char* b2 = last ? nB : cB + (size_t)(t + 2) * kstep;
;             const char* a3 = a2 + kstep; const char* b3 = b2 + kstep;
;             if (last && has_next) S.a_ready(nxt);
;             if constexpr (SP2) {
;             PG8_LDB(B0, 0, 0); PG8_LDB(B1, 0, 1); PG8_SCHED; PG8_LDA(At, 0, 0); PG8_STAGE(PG8_SA(1, 1), a1 + hstep, voffA);
;             PG8_WAIT_V(8); PG8_WAIT_L(0); PG8_BAR; PG8_MMA(0, 0, At, B0); PG8_MMA(0, 1, At, B1); PG8_BAR; PG8_SCHED;
;             PG8_LDA(At, 0, 1); PG8_STAGE(PG8_SB(0, 0), b2, voffB); PG8_STAGE(PG8_SB(0, 1), b2 + hstep, voffB); PG8_STAGE(PG8_SA(0, 0), a2, voffA);
;             PG8_WAIT_V(8); PG8_WAIT_L(0); PG8_BAR; PG8_MMA(1, 0, At, B0); PG8_MMA(1, 1, At, B1); PG8_BAR; PG8_SCHED;
;             PG8_LDB(B0, 1, 0); PG8_LDB(B1, 1, 1); PG8_SCHED; PG8_LDA(At, 1, 0); PG8_STAGE(PG8_SA(0, 1), a2 + hstep, voffA);
;             PG8_WAIT_V(8); PG8_WAIT_L(0); PG8_BAR; PG8_MMA(0, 0, At, B0); PG8_MMA(0, 1, At, B1); PG8_BAR; PG8_SCHED;
;             PG8_LDA(At, 1, 1); PG8_STAGE(PG8_SB(1, 0), b3, voffB); PG8_STAGE(PG8_SB(1, 1), b3 + hstep, voffB); PG8_STAGE(PG8_SA(1, 0), a3, voffA);
;             PG8_WAIT_V(8); PG8_WAIT_L(0); PG8_BAR; PG8_MMA(1, 0, At, B0); PG8_MMA(1, 1, At, B1); PG8_BAR; PG8_SCHED;
	s_add_i32 s22, s48, s33
	v_lshl_add_u64 v[146:147], v[146:147], 0, s[4:5]
	s_mov_b32 m0, s22
	ds_read_b128 v[190:193], v153 offset:49152
	ds_read_b128 v[194:197], v153 offset:50176
	ds_read_b128 v[198:201], v153 offset:51200
	ds_read_b128 v[202:205], v153 offset:52224
	ds_read_b128 v[206:209], v153 offset:53248
	ds_read_b128 v[210:213], v153 offset:54272
	ds_read_b128 v[214:217], v153 offset:55296
	ds_read_b128 v[218:221], v153 offset:56320
	global_load_lds_dwordx4 v[146:147], off
	s_add_i32 m0, s22, 0x2000
	s_add_u32 s22, s26, 0x80080
	v_lshl_add_u64 v[146:147], v[170:171], 0, s[4:5]
	s_addc_u32 s23, s27, 0
	s_add_i32 s26, s49, s33
	global_load_lds_dwordx4 v[146:147], off
	s_mov_b32 m0, s26
	s_nop 0
	global_load_lds_dwordx4 v130, s[22:23]
	s_add_i32 m0, s26, 0x2000
	s_nop 0
	global_load_lds_dwordx4 v132, s[22:23]
	v_lshl_add_u64 v[146:147], v[222:223], 0, s[4:5]
	s_mov_b32 m0, s39
	s_nop 0
	global_load_lds_dwordx4 v[146:147], off
	v_lshl_add_u64 v[146:147], v[224:225], 0, s[4:5]
	s_mov_b32 m0, s40
	s_nop 0
	global_load_lds_dwordx4 v[146:147], off
	s_waitcnt vmcnt(8)
	s_waitcnt lgkmcnt(0)
	s_barrier
	s_setprio 1
	s_waitcnt lgkmcnt(0)
	v_mfma_f32_16x16x32_bf16 v[60:63], v[142:145], v[190:193], v[60:63]
	v_mfma_f32_16x16x32_bf16 v[56:59], v[158:161], v[190:193], v[56:59]
	v_mfma_f32_16x16x32_bf16 v[44:47], v[142:145], v[198:201], v[44:47]
	v_mfma_f32_16x16x32_bf16 v[40:43], v[158:161], v[198:201], v[40:43]
	v_mfma_f32_16x16x32_bf16 v[28:31], v[142:145], v[206:209], v[28:31]
	v_mfma_f32_16x16x32_bf16 v[24:27], v[158:161], v[206:209], v[24:27]
	v_mfma_f32_16x16x32_bf16 v[12:15], v[142:145], v[214:217], v[12:15]
	v_mfma_f32_16x16x32_bf16 v[8:11], v[158:161], v[214:217], v[8:11]
	v_mfma_f32_16x16x32_bf16 v[60:63], v[154:157], v[194:197], v[60:63]
	v_mfma_f32_16x16x32_bf16 v[56:59], v[162:165], v[194:197], v[56:59]
	v_mfma_f32_16x16x32_bf16 v[44:47], v[154:157], v[202:205], v[44:47]
	v_mfma_f32_16x16x32_bf16 v[40:43], v[162:165], v[202:205], v[40:43]
	v_mfma_f32_16x16x32_bf16 v[28:31], v[154:157], v[210:213], v[28:31]
	v_mfma_f32_16x16x32_bf16 v[24:27], v[162:165], v[210:213], v[24:27]
	v_mfma_f32_16x16x32_bf16 v[12:15], v[154:157], v[218:221], v[12:15]
	v_mfma_f32_16x16x32_bf16 v[8:11], v[162:165], v[218:221], v[8:11]
	s_setprio 0
	s_setprio 1
	v_mfma_f32_16x16x32_bf16 v[52:55], v[166:169], v[190:193], v[52:55]
	v_mfma_f32_16x16x32_bf16 v[48:51], v[182:185], v[190:193], v[48:51]
	v_mfma_f32_16x16x32_bf16 v[36:39], v[166:169], v[198:201], v[36:39]
	v_mfma_f32_16x16x32_bf16 v[32:35], v[182:185], v[198:201], v[32:35]
	v_mfma_f32_16x16x32_bf16 v[20:23], v[166:169], v[206:209], v[20:23]
	v_mfma_f32_16x16x32_bf16 v[16:19], v[182:185], v[206:209], v[16:19]
	v_mfma_f32_16x16x32_bf16 v[4:7], v[166:169], v[214:217], v[4:7]
	v_mfma_f32_16x16x32_bf16 v[0:3], v[182:185], v[214:217], v[0:3]
	v_mfma_f32_16x16x32_bf16 v[52:55], v[178:181], v[194:197], v[52:55]
	v_mfma_f32_16x16x32_bf16 v[48:51], v[186:189], v[194:197], v[48:51]
	v_mfma_f32_16x16x32_bf16 v[36:39], v[178:181], v[202:205], v[36:39]
	v_mfma_f32_16x16x32_bf16 v[32:35], v[186:189], v[202:205], v[32:35]
	v_mfma_f32_16x16x32_bf16 v[20:23], v[178:181], v[210:213], v[20:23]
	v_mfma_f32_16x16x32_bf16 v[16:19], v[186:189], v[210:213], v[16:19]
	v_mfma_f32_16x16x32_bf16 v[4:7], v[178:181], v[218:221], v[4:7]
	v_mfma_f32_16x16x32_bf16 v[0:3], v[186:189], v[218:221], v[0:3]
	s_setprio 0
	s_barrier
	s_add_i32 s47, s47, 2
	s_add_u32 s45, s45, 0x100
	s_addc_u32 s46, s46, 0
	s_cmp_gt_u32 s47, 29
	s_mov_b64 s[22:23], s[24:25]
	s_cbranch_scc0 .LBB0_1457
	s_nop 0
	v_readfirstlane_b32 s21, v172
	s_nop 3
	s_lshr_b32 s21, s21, 6
	s_cmp_lt_u32 s21, 4
	s_cbranch_scc0 .Lprio_k5
	s_setprio 1

; #define PG8_STAGE(bufoff, gbase, voff) do { _Pragma("unroll") for (int _i = 0; _i < 2; ++_i) \
;         __builtin_amdgcn_global_load_lds((const unsigned*)((const char*)(gbase) + (voff)[_i]), (PG8_LAS unsigned*)(lds + (bufoff) + ldsw + _i * 8192), 16, 0, 0); } while (0)
; #define PG8_WAIT_V(n) asm volatile("s_waitcnt vmcnt(" #n ")" ::: "memory")
; #define PG8_BAR __builtin_amdgcn_s_barrier()
; template <class Epi, class Sched, bool ALIGN_EPI = false, bool SP2 = false>
; __device__ __forceinline__ void gemm_phase(PG8_LAS unsigned char* lds, const Gemm g, const Sched& S, const Epi& E) {
;     ...
;     if constexpr (SP2) {
;         PG8_STAGE(PG8_SB(0, 0), cB, voffB); PG8_STAGE(PG8_SB(0, 1), cB + hstep, voffB); PG8_STAGE(PG8_SA(0, 0), cA, voffA); PG8_STAGE(PG8_SA(0, 1), cA + hstep, voffA);
;         if (wr == 1) PG8_BAR;
;         PG8_WAIT_V(2); PG8_BAR;
;         PG8_STAGE(PG8_SB(1, 0), cB + kstep, voffB); PG8_STAGE(PG8_SA(1, 0), cA + kstep, voffA); PG8_STAGE(PG8_SB(1, 1), cB + hstep + kstep, voffB);
;         PG8_WAIT_V(6); PG8_BAR;
;     } else {
;         PG8_STAGE(PG8_SB(0, 0), cB, voffB); PG8_STAGE(PG8_SA(0, 0), cA, voffA); PG8_STAGE(PG8_SB(0, 1), cB + hstep, voffB); PG8_STAGE(PG8_SA(0, 1), cA + hstep, voffA);
;         if (wr == 1) PG8_BAR;
;         PG8_WAIT_V(4); PG8_BAR;
;         PG8_STAGE(PG8_SB(1, 0), cB + kstep, voffB); PG8_STAGE(PG8_SA(1, 0), cA + kstep, voffA); PG8_STAGE(PG8_SB(1, 1), cB + hstep + kstep, voffB);
;         PG8_WAIT_V(6); PG8_BAR;
;     }
;     for (;;) {
;         const bool has_next = S.next(ui + 1, nxt);
;         const char* nA = has_next ? (const char*)g.A + (size_t)nxt.pm * tstep : cA; const char* nB = has_next ? (const char*)g.Bt + (size_t)nxt.pn * tstep : cB;
.LBB0_1706:
	s_lshl_b32 s2, s2, 5
	s_and_b32 s10, s2, 0x60
	s_mov_b64 s[2:3], 0x80
	s_add_i32 m0, s17, 0x18000
	v_lshl_add_u64 v[6:7], v[6:7], 0, s[2:3]
	s_lshl_b32 s9, s8, 13
	s_lshl_b32 s11, s10, 7
	s_waitcnt vmcnt(2)
	s_barrier
	global_load_lds_dwordx4 v[6:7], off
	v_lshl_add_u64 v[4:5], v[4:5], 0, s[2:3]
	s_add_i32 m0, s17, 0x1a000
	s_add_i32 s31, s17, 0x8000
	s_add_i32 s33, s17, 0xa000
	global_load_lds_dwordx4 v[4:5], off
	v_lshl_add_u64 v[0:1], v[0:1], 0, s[2:3]
	s_mov_b32 m0, s31
	s_add_u32 s6, s20, 0x80080
	global_load_lds_dwordx4 v[0:1], off
	v_lshl_add_u64 v[0:1], v[2:3], 0, s[2:3]
	s_mov_b32 m0, s33
	s_addc_u32 s7, s21, 0
	global_load_lds_dwordx4 v[0:1], off
	s_add_i32 m0, s17, 0x1c000
	s_nop 0
	global_load_lds_dwordx4 v132, s[6:7]
	s_add_i32 m0, s17, 0x1e000
	s_cmpk_lt_u32 s5, 0x100
	global_load_lds_dwordx4 v128, s[6:7]
	v_lshrrev_b32_e32 v1, 1, v9
	s_sext_i32_i16 s39, s4
	v_and_b32_e32 v1, 24, v1
	s_cselect_b64 s[6:7], -1, 0
	s_lshl_b32 s4, s8, 8
	v_and_b32_e32 v0, 15, v9
	v_lshlrev_b32_e32 v2, 1, v1
	s_add_i32 s4, s4, 0
	v_lshl_or_b32 v152, s8, 6, v0
	v_lshl_or_b32 v2, v0, 6, v2
	v_lshlrev_b32_e32 v0, 2, v0
	s_add_i32 s4, s4, 0x20000
	v_and_b32_e32 v3, 32, v0
	v_add_u32_e32 v154, s4, v0
	v_lshlrev_b32_e32 v0, 15, v13
	v_and_b32_e32 v0, 0xffff0000, v0
	v_or_b32_e32 v155, s10, v1
	v_lshl_add_u32 v0, v12, 12, v0
	v_and_b32_e32 v1, 1, v13
	v_lshl_or_b32 v0, v1, 6, v0
	v_lshl_add_u32 v136, v14, 1, v0
	v_lshlrev_b32_e32 v0, 15, v8
	v_and_b32_e32 v0, 0xffff0000, v0
	s_waitcnt vmcnt(6)
	v_lshl_add_u32 v0, v10, 12, v0
	v_and_b32_e32 v1, 1, v8
	v_bitop3_b32 v4, v2, s9, v3 bitop3:0xde
	v_bitop3_b32 v153, v2, s11, v3 bitop3:0xde
	v_lshl_or_b32 v0, v1, 6, v0
	s_add_i32 s34, 0, 0x10000
	s_add_i32 s35, 0, 0x14000
	v_mov_b32_e32 v137, v133
	v_lshl_add_u32 v138, v11, 1, v0
	v_mov_b32_e32 v139, v133
	v_mov_b64_e32 v[140:141], 0x580
	v_mov_b64_e32 v[142:143], 0x57f
	v_add_u32_e32 v156, s34, v153
	v_add_u32_e32 v157, s35, v153
	v_add_u32_e32 v158, 0, v4
	s_movk_i32 s36, 0x2c00
	s_barrier
	s_waitcnt vmcnt(0)
	s_branch .LBB0_1709

; #define PG8_STAGE(bufoff, gbase, voff) do { _Pragma("unroll") for (int _i = 0; _i < 2; ++_i) \
;         __builtin_amdgcn_global_load_lds((const unsigned*)((const char*)(gbase) + (voff)[_i]), (PG8_LAS unsigned*)(lds + (bufoff) + ldsw + _i * 8192), 16, 0, 0); } while (0)
; #define PG8_LDA(dst, b, h) do { _Pragma("unroll") for (int m = 0; m < 4; ++m) _Pragma("unroll") for (int k = 0; k < 2; ++k) dst[m][k] = *(const PG8_LAS bf16x8*)(lds + PG8_SA(b, h) + aoff + m * 2048 + k * 1024); } while (0)
; #define PG8_LDB(dst, b, h) do { _Pragma("unroll") for (int n = 0; n < 2; ++n) _Pragma("unroll") for (int k = 0; k < 2; ++k) dst[n][k] = *(const PG8_LAS bf16x8*)(lds + PG8_SB(b, h) + boff + n * 2048 + k * 1024); } while (0)
; template <class Epi, class Sched, bool ALIGN_EPI = false, bool SP2 = false>
; __device__ __forceinline__ void gemm_phase(PG8_LAS unsigned char* lds, const Gemm g, const Sched& S, const Epi& E) {
;     ...
;         for (int t = 0; t < nt; t += 2) {
;             const bool last = (t == nt - 2);
;             const char* a1 = cA + (size_t)(t + 1) * kstep;
;             const char* a2 = last ? nA : cA + (size_t)(t + 2) * kstep; const char* b2 = last ? nB : cB + (size_t)(t + 2) * kstep;
;             const char* a3 = a2 + kstep; const char* b3 = b2 + kstep;
;             if (last && has_next) S.a_ready(nxt);
;             if constexpr (SP2) {
;             PG8_LDB(B0, 0, 0); PG8_LDB(B1, 0, 1); PG8_SCHED; PG8_LDA(At, 0, 0); PG8_STAGE(PG8_SA(1, 1), a1 + hstep, voffA);
;             PG8_WAIT_V(8); PG8_WAIT_L(0); PG8_BAR; PG8_MMA(0, 0, At, B0); PG8_MMA(0, 1, At, B1); PG8_BAR; PG8_SCHED;
;             PG8_LDA(At, 0, 1); PG8_STAGE(PG8_SB(0, 0), b2, voffB); PG8_STAGE(PG8_SB(0, 1), b2 + hstep, voffB); PG8_STAGE(PG8_SA(0, 0), a2, voffA);
;             PG8_WAIT_V(8); PG8_WAIT_L(0); PG8_BAR; PG8_MMA(1, 0, At, B0); PG8_MMA(1, 1, At, B1); PG8_BAR; PG8_SCHED;
;             PG8_LDB(B0, 1, 0); PG8_LDB(B1, 1, 1); PG8_SCHED; PG8_LDA(At, 1, 0); PG8_STAGE(PG8_SA(0, 1), a2 + hstep, voffA);
;             PG8_WAIT_V(8); PG8_WAIT_L(0); PG8_BAR; PG8_MMA(0, 0, At, B0); PG8_MMA(0, 1, At, B1); PG8_BAR; PG8_SCHED;
;             PG8_LDA(At, 1, 1); PG8_STAGE(PG8_SB(1, 0), b3, voffB); PG8_STAGE(PG8_SB(1, 1), b3 + hstep, voffB); PG8_STAGE(PG8_SA(1, 0), a3, voffA);
;             PG8_WAIT_V(8); PG8_WAIT_L(0); PG8_BAR; PG8_MMA(1, 0, At, B0); PG8_MMA(1, 1, At, B1); PG8_BAR; PG8_SCHED;
.LBB0_1712:
	ds_read_b128 v[144:147], v156
	ds_read_b128 v[148:151], v156 offset:1024
	ds_read_b128 v[160:163], v156 offset:2048
	ds_read_b128 v[164:167], v156 offset:3072
	ds_read_b128 v[168:171], v157
	ds_read_b128 v[174:177], v157 offset:1024
	ds_read_b128 v[178:181], v157 offset:2048
	ds_read_b128 v[182:185], v157 offset:3072
	s_add_u32 s20, s18, 0xfff80080
	s_addc_u32 s21, s19, -1
	s_cmp_eq_u32 s44, 28
	s_cselect_b32 s23, s11, s21
	s_cselect_b32 s22, s40, s20
	s_cselect_b32 s21, s9, s43
	s_cselect_b32 s20, s41, s42
	s_add_i32 m0, s17, 0xc000
	ds_read_b128 v[186:189], v158
	ds_read_b128 v[190:193], v158 offset:1024
	ds_read_b128 v[194:197], v158 offset:2048
	ds_read_b128 v[198:201], v158 offset:3072
	ds_read_b128 v[202:205], v158 offset:4096
	ds_read_b128 v[206:209], v158 offset:5120
	ds_read_b128 v[210:213], v158 offset:6144
	ds_read_b128 v[214:217], v158 offset:7168
	global_load_lds_dwordx4 v136, s[18:19]
	s_add_i32 m0, s17, 0xe000
	s_nop 0
	global_load_lds_dwordx4 v138, s[18:19]
	s_waitcnt vmcnt(8)
	s_waitcnt lgkmcnt(0)
	s_barrier
	s_setprio 1
	s_waitcnt lgkmcnt(0)
	v_mfma_f32_16x16x32_bf16 v[124:127], v[144:147], v[186:189], v[124:127]
	v_mfma_f32_16x16x32_bf16 v[120:123], v[160:163], v[186:189], v[120:123]
	v_mfma_f32_16x16x32_bf16 v[108:111], v[144:147], v[194:197], v[108:111]
	v_mfma_f32_16x16x32_bf16 v[104:107], v[160:163], v[194:197], v[104:107]
	v_mfma_f32_16x16x32_bf16 v[92:95], v[144:147], v[202:205], v[92:95]
	v_mfma_f32_16x16x32_bf16 v[88:91], v[160:163], v[202:205], v[88:91]
	v_mfma_f32_16x16x32_bf16 v[76:79], v[144:147], v[210:213], v[76:79]
	v_mfma_f32_16x16x32_bf16 v[72:75], v[160:163], v[210:213], v[72:75]
	v_mfma_f32_16x16x32_bf16 v[124:127], v[148:151], v[190:193], v[124:127]
	v_mfma_f32_16x16x32_bf16 v[120:123], v[164:167], v[190:193], v[120:123]
	v_mfma_f32_16x16x32_bf16 v[108:111], v[148:151], v[198:201], v[108:111]
	v_mfma_f32_16x16x32_bf16 v[104:107], v[164:167], v[198:201], v[104:107]
	v_mfma_f32_16x16x32_bf16 v[92:95], v[148:151], v[206:209], v[92:95]
	v_mfma_f32_16x16x32_bf16 v[88:91], v[164:167], v[206:209], v[88:91]
	v_mfma_f32_16x16x32_bf16 v[76:79], v[148:151], v[214:217], v[76:79]
	v_mfma_f32_16x16x32_bf16 v[72:75], v[164:167], v[214:217], v[72:75]
	s_setprio 0
	s_setprio 1
	v_mfma_f32_16x16x32_bf16 v[116:119], v[168:171], v[186:189], v[116:119]
	v_mfma_f32_16x16x32_bf16 v[112:115], v[178:181], v[186:189], v[112:115]
	v_mfma_f32_16x16x32_bf16 v[100:103], v[168:171], v[194:197], v[100:103]
	v_mfma_f32_16x16x32_bf16 v[96:99], v[178:181], v[194:197], v[96:99]
	v_mfma_f32_16x16x32_bf16 v[84:87], v[168:171], v[202:205], v[84:87]
	v_mfma_f32_16x16x32_bf16 v[80:83], v[178:181], v[202:205], v[80:83]
	v_mfma_f32_16x16x32_bf16 v[68:71], v[168:171], v[210:213], v[68:71]
	v_mfma_f32_16x16x32_bf16 v[64:67], v[178:181], v[210:213], v[64:67]
	v_mfma_f32_16x16x32_bf16 v[116:119], v[174:177], v[190:193], v[116:119]
	v_mfma_f32_16x16x32_bf16 v[112:115], v[182:185], v[190:193], v[112:115]
	v_mfma_f32_16x16x32_bf16 v[100:103], v[174:177], v[198:201], v[100:103]
	v_mfma_f32_16x16x32_bf16 v[96:99], v[182:185], v[198:201], v[96:99]
	v_mfma_f32_16x16x32_bf16 v[84:87], v[174:177], v[206:209], v[84:87]
	v_mfma_f32_16x16x32_bf16 v[80:83], v[182:185], v[206:209], v[80:83]
	v_mfma_f32_16x16x32_bf16 v[68:71], v[174:177], v[214:217], v[68:71]
	v_mfma_f32_16x16x32_bf16 v[64:67], v[182:185], v[214:217], v[64:67]
	s_setprio 0
	s_barrier
	s_add_i32 s45, s34, s26
	v_lshl_add_u64 v[218:219], s[20:21], 0, v[132:133]
	s_mov_b32 m0, s45
	ds_read_b128 v[186:189], v158 offset:16384
	ds_read_b128 v[190:193], v158 offset:17408
	ds_read_b128 v[194:197], v158 offset:18432
	ds_read_b128 v[198:201], v158 offset:19456
	ds_read_b128 v[202:205], v158 offset:20480
	ds_read_b128 v[206:209], v158 offset:21504
	ds_read_b128 v[210:213], v158 offset:22528
	ds_read_b128 v[214:217], v158 offset:23552
	global_load_lds_dwordx4 v[218:219], off
	s_add_i32 m0, s45, 0x2000
	s_add_u32 s46, s20, 0x80000
	v_lshl_add_u64 v[220:221], s[20:21], 0, v[128:129]
	s_addc_u32 s47, s21, 0
	s_add_i32 s45, s35, s26
	global_load_lds_dwordx4 v[220:221], off
	s_mov_b32 m0, s45
	v_lshl_add_u64 v[224:225], s[22:23], 0, v[130:131]
	global_load_lds_dwordx4 v132, s[46:47]
	s_add_i32 m0, s45, 0x2000
	s_nop 0
	global_load_lds_dwordx4 v128, s[46:47]
	v_lshl_add_u64 v[222:223], s[22:23], 0, v[134:135]
	s_mov_b32 m0, s17
	s_nop 0
	global_load_lds_dwordx4 v[222:223], off
	s_mov_b32 m0, s28
	s_nop 0
	global_load_lds_dwordx4 v[224:225], off
	s_waitcnt vmcnt(8)
	s_waitcnt lgkmcnt(0)
	s_barrier
; #define PG8_STAGE(bufoff, gbase, voff) do { _Pragma("unroll") for (int _i = 0; _i < 2; ++_i) \
;         __builtin_amdgcn_global_load_lds((const unsigned*)((const char*)(gbase) + (voff)[_i]), (PG8_LAS unsigned*)(lds + (bufoff) + ldsw + _i * 8192), 16, 0, 0); } while (0)
; #define PG8_LDA(dst, b, h) do { _Pragma("unroll") for (int m = 0; m < 4; ++m) _Pragma("unroll") for (int k = 0; k < 2; ++k) dst[m][k] = *(const PG8_LAS bf16x8*)(lds + PG8_SA(b, h) + aoff + m * 2048 + k * 1024); } while (0)
; #define PG8_LDB(dst, b, h) do { _Pragma("unroll") for (int n = 0; n < 2; ++n) _Pragma("unroll") for (int k = 0; k < 2; ++k) dst[n][k] = *(const PG8_LAS bf16x8*)(lds + PG8_SB(b, h) + boff + n * 2048 + k * 1024); } while (0)
; template <class Epi, class Sched, bool ALIGN_EPI = false, bool SP2 = false>
; __device__ __forceinline__ void gemm_phase(PG8_LAS unsigned char* lds, const Gemm g, const Sched& S, const Epi& E) {
;     ...
;         for (int t = 0; t < nt; t += 2) {
;             const bool last = (t == nt - 2);
;             const char* a1 = cA + (size_t)(t + 1) * kstep;
;             const char* a2 = last ? nA : cA + (size_t)(t + 2) * kstep; const char* b2 = last ? nB : cB + (size_t)(t + 2) * kstep;
;             const char* a3 = a2 + kstep; const char* b3 = b2 + kstep;
;             if (last && has_next) S.a_ready(nxt);
;             if constexpr (SP2) {
;             PG8_LDB(B0, 0, 0); PG8_LDB(B1, 0, 1); PG8_SCHED; PG8_LDA(At, 0, 0); PG8_STAGE(PG8_SA(1, 1), a1 + hstep, voffA);
;             PG8_WAIT_V(8); PG8_WAIT_L(0); PG8_BAR; PG8_MMA(0, 0, At, B0); PG8_MMA(0, 1, At, B1); PG8_BAR; PG8_SCHED;
;             PG8_LDA(At, 0, 1); PG8_STAGE(PG8_SB(0, 0), b2, voffB); PG8_STAGE(PG8_SB(0, 1), b2 + hstep, voffB); PG8_STAGE(PG8_SA(0, 0), a2, voffA);
;             PG8_WAIT_V(8); PG8_WAIT_L(0); PG8_BAR; PG8_MMA(1, 0, At, B0); PG8_MMA(1, 1, At, B1); PG8_BAR; PG8_SCHED;
;             PG8_LDB(B0, 1, 0); PG8_LDB(B1, 1, 1); PG8_SCHED; PG8_LDA(At, 1, 0); PG8_STAGE(PG8_SA(0, 1), a2 + hstep, voffA);
;             PG8_WAIT_V(8); PG8_WAIT_L(0); PG8_BAR; PG8_MMA(0, 0, At, B0); PG8_MMA(0, 1, At, B1); PG8_BAR; PG8_SCHED;
;             PG8_LDA(At, 1, 1); PG8_STAGE(PG8_SB(1, 0), b3, voffB); PG8_STAGE(PG8_SB(1, 1), b3 + hstep, voffB); PG8_STAGE(PG8_SA(1, 0), a3, voffA);
;             PG8_WAIT_V(8); PG8_WAIT_L(0); PG8_BAR; PG8_MMA(1, 0, At, B0); PG8_MMA(1, 1, At, B1); PG8_BAR; PG8_SCHED;
	s_setprio 1
	s_waitcnt lgkmcnt(0)
	v_mfma_f32_16x16x32_bf16 v[60:63], v[144:147], v[186:189], v[60:63]
	v_mfma_f32_16x16x32_bf16 v[56:59], v[160:163], v[186:189], v[56:59]
	v_mfma_f32_16x16x32_bf16 v[44:47], v[144:147], v[194:197], v[44:47]
	v_mfma_f32_16x16x32_bf16 v[40:43], v[160:163], v[194:197], v[40:43]
	v_mfma_f32_16x16x32_bf16 v[28:31], v[144:147], v[202:205], v[28:31]
	v_mfma_f32_16x16x32_bf16 v[24:27], v[160:163], v[202:205], v[24:27]
	v_mfma_f32_16x16x32_bf16 v[12:15], v[144:147], v[210:213], v[12:15]
	v_mfma_f32_16x16x32_bf16 v[8:11], v[160:163], v[210:213], v[8:11]
	v_mfma_f32_16x16x32_bf16 v[60:63], v[148:151], v[190:193], v[60:63]
	v_mfma_f32_16x16x32_bf16 v[56:59], v[164:167], v[190:193], v[56:59]
	v_mfma_f32_16x16x32_bf16 v[44:47], v[148:151], v[198:201], v[44:47]
	v_mfma_f32_16x16x32_bf16 v[40:43], v[164:167], v[198:201], v[40:43]
	v_mfma_f32_16x16x32_bf16 v[28:31], v[148:151], v[206:209], v[28:31]
	v_mfma_f32_16x16x32_bf16 v[24:27], v[164:167], v[206:209], v[24:27]
	v_mfma_f32_16x16x32_bf16 v[12:15], v[148:151], v[214:217], v[12:15]
	v_mfma_f32_16x16x32_bf16 v[8:11], v[164:167], v[214:217], v[8:11]
	s_setprio 0
	s_setprio 1
	v_mfma_f32_16x16x32_bf16 v[52:55], v[168:171], v[186:189], v[52:55]
	v_mfma_f32_16x16x32_bf16 v[48:51], v[178:181], v[186:189], v[48:51]
	v_mfma_f32_16x16x32_bf16 v[36:39], v[168:171], v[194:197], v[36:39]
	v_mfma_f32_16x16x32_bf16 v[32:35], v[178:181], v[194:197], v[32:35]
	v_mfma_f32_16x16x32_bf16 v[20:23], v[168:171], v[202:205], v[20:23]
	v_mfma_f32_16x16x32_bf16 v[16:19], v[178:181], v[202:205], v[16:19]
	v_mfma_f32_16x16x32_bf16 v[4:7], v[168:171], v[210:213], v[4:7]
	v_mfma_f32_16x16x32_bf16 v[0:3], v[178:181], v[210:213], v[0:3]
	v_mfma_f32_16x16x32_bf16 v[52:55], v[174:177], v[190:193], v[52:55]
	v_mfma_f32_16x16x32_bf16 v[48:51], v[182:185], v[190:193], v[48:51]
	v_mfma_f32_16x16x32_bf16 v[36:39], v[174:177], v[198:201], v[36:39]
	v_mfma_f32_16x16x32_bf16 v[32:35], v[182:185], v[198:201], v[32:35]
	v_mfma_f32_16x16x32_bf16 v[20:23], v[174:177], v[206:209], v[20:23]
	v_mfma_f32_16x16x32_bf16 v[16:19], v[182:185], v[206:209], v[16:19]
	v_mfma_f32_16x16x32_bf16 v[4:7], v[174:177], v[214:217], v[4:7]
	v_mfma_f32_16x16x32_bf16 v[0:3], v[182:185], v[214:217], v[0:3]
	s_setprio 0
	s_barrier
	s_add_i32 s45, 0, 0x18000
	v_add_u32_e32 v159, s45, v153
	s_add_i32 s46, 0, 0x1c000
	ds_read_b128 v[144:147], v159
	ds_read_b128 v[148:151], v159 offset:1024
	ds_read_b128 v[160:163], v159 offset:2048
	ds_read_b128 v[164:167], v159 offset:3072
	v_add_u32_e32 v159, s46, v153
	ds_read_b128 v[168:171], v159
	ds_read_b128 v[174:177], v159 offset:1024
	ds_read_b128 v[178:181], v159 offset:2048
	ds_read_b128 v[182:185], v159 offset:3072
	s_add_u32 s22, s22, 0x80000
	s_addc_u32 s23, s23, 0
	s_mov_b32 m0, s29
	ds_read_b128 v[186:189], v158 offset:32768
	ds_read_b128 v[190:193], v158 offset:33792
	ds_read_b128 v[194:197], v158 offset:34816
	ds_read_b128 v[198:201], v158 offset:35840
	ds_read_b128 v[202:205], v158 offset:36864
	ds_read_b128 v[206:209], v158 offset:37888
	ds_read_b128 v[210:213], v158 offset:38912
	ds_read_b128 v[214:217], v158 offset:39936
	global_load_lds_dwordx4 v134, s[22:23]
	s_mov_b32 m0, s30
	s_nop 0
	global_load_lds_dwordx4 v130, s[22:23]
	s_waitcnt vmcnt(8)
	s_waitcnt lgkmcnt(0)
	s_barrier
	s_setprio 1
	s_waitcnt lgkmcnt(0)
	v_mfma_f32_16x16x32_bf16 v[124:127], v[144:147], v[186:189], v[124:127]
	v_mfma_f32_16x16x32_bf16 v[120:123], v[160:163], v[186:189], v[120:123]
	v_mfma_f32_16x16x32_bf16 v[108:111], v[144:147], v[194:197], v[108:111]
	v_mfma_f32_16x16x32_bf16 v[104:107], v[160:163], v[194:197], v[104:107]
	v_mfma_f32_16x16x32_bf16 v[92:95], v[144:147], v[202:205], v[92:95]
	v_mfma_f32_16x16x32_bf16 v[88:91], v[160:163], v[202:205], v[88:91]
	v_mfma_f32_16x16x32_bf16 v[76:79], v[144:147], v[210:213], v[76:79]
	v_mfma_f32_16x16x32_bf16 v[72:75], v[160:163], v[210:213], v[72:75]
	v_mfma_f32_16x16x32_bf16 v[124:127], v[148:151], v[190:193], v[124:127]
	v_mfma_f32_16x16x32_bf16 v[120:123], v[164:167], v[190:193], v[120:123]
	v_mfma_f32_16x16x32_bf16 v[108:111], v[148:151], v[198:201], v[108:111]
	v_mfma_f32_16x16x32_bf16 v[104:107], v[164:167], v[198:201], v[104:107]
	v_mfma_f32_16x16x32_bf16 v[92:95], v[148:151], v[206:209], v[92:95]
	v_mfma_f32_16x16x32_bf16 v[88:91], v[164:167], v[206:209], v[88:91]
	v_mfma_f32_16x16x32_bf16 v[76:79], v[148:151], v[214:217], v[76:79]
	v_mfma_f32_16x16x32_bf16 v[72:75], v[164:167], v[214:217], v[72:75]
	s_setprio 0
	s_setprio 1
	v_mfma_f32_16x16x32_bf16 v[116:119], v[168:171], v[186:189], v[116:119]
	v_mfma_f32_16x16x32_bf16 v[112:115], v[178:181], v[186:189], v[112:115]
	v_mfma_f32_16x16x32_bf16 v[100:103], v[168:171], v[194:197], v[100:103]
	v_mfma_f32_16x16x32_bf16 v[96:99], v[178:181], v[194:197], v[96:99]
	v_mfma_f32_16x16x32_bf16 v[84:87], v[168:171], v[202:205], v[84:87]
	v_mfma_f32_16x16x32_bf16 v[80:83], v[178:181], v[202:205], v[80:83]
	v_mfma_f32_16x16x32_bf16 v[68:71], v[168:171], v[210:213], v[68:71]
	v_mfma_f32_16x16x32_bf16 v[64:67], v[178:181], v[210:213], v[64:67]
	v_mfma_f32_16x16x32_bf16 v[116:119], v[174:177], v[190:193], v[116:119]
	v_mfma_f32_16x16x32_bf16 v[112:115], v[182:185], v[190:193], v[112:115]
	v_mfma_f32_16x16x32_bf16 v[100:103], v[174:177], v[198:201], v[100:103]
	v_mfma_f32_16x16x32_bf16 v[96:99], v[182:185], v[198:201], v[96:99]
	v_mfma_f32_16x16x32_bf16 v[84:87], v[174:177], v[206:209], v[84:87]
	v_mfma_f32_16x16x32_bf16 v[80:83], v[182:185], v[206:209], v[80:83]
	v_mfma_f32_16x16x32_bf16 v[68:71], v[174:177], v[214:217], v[68:71]
	v_mfma_f32_16x16x32_bf16 v[64:67], v[182:185], v[214:217], v[64:67]
	s_setprio 0
	s_barrier
; #define PG8_STAGE(bufoff, gbase, voff) do { _Pragma("unroll") for (int _i = 0; _i < 2; ++_i) \
;         __builtin_amdgcn_global_load_lds((const unsigned*)((const char*)(gbase) + (voff)[_i]), (PG8_LAS unsigned*)(lds + (bufoff) + ldsw + _i * 8192), 16, 0, 0); } while (0)
; #define PG8_LDA(dst, b, h) do { _Pragma("unroll") for (int m = 0; m < 4; ++m) _Pragma("unroll") for (int k = 0; k < 2; ++k) dst[m][k] = *(const PG8_LAS bf16x8*)(lds + PG8_SA(b, h) + aoff + m * 2048 + k * 1024); } while (0)
; #define PG8_LDB(dst, b, h) do { _Pragma("unroll") for (int n = 0; n < 2; ++n) _Pragma("unroll") for (int k = 0; k < 2; ++k) dst[n][k] = *(const PG8_LAS bf16x8*)(lds + PG8_SB(b, h) + boff + n * 2048 + k * 1024); } while (0)
; template <class Epi, class Sched, bool ALIGN_EPI = false, bool SP2 = false>
; __device__ __forceinline__ void gemm_phase(PG8_LAS unsigned char* lds, const Gemm g, const Sched& S, const Epi& E) {
;     ...
;         for (int t = 0; t < nt; t += 2) {
;             const bool last = (t == nt - 2);
;             const char* a1 = cA + (size_t)(t + 1) * kstep;
;             const char* a2 = last ? nA : cA + (size_t)(t + 2) * kstep; const char* b2 = last ? nB : cB + (size_t)(t + 2) * kstep;
;             const char* a3 = a2 + kstep; const char* b3 = b2 + kstep;
;             if (last && has_next) S.a_ready(nxt);
;             if constexpr (SP2) {
;             PG8_LDB(B0, 0, 0); PG8_LDB(B1, 0, 1); PG8_SCHED; PG8_LDA(At, 0, 0); PG8_STAGE(PG8_SA(1, 1), a1 + hstep, voffA);
;             PG8_WAIT_V(8); PG8_WAIT_L(0); PG8_BAR; PG8_MMA(0, 0, At, B0); PG8_MMA(0, 1, At, B1); PG8_BAR; PG8_SCHED;
;             PG8_LDA(At, 0, 1); PG8_STAGE(PG8_SB(0, 0), b2, voffB); PG8_STAGE(PG8_SB(0, 1), b2 + hstep, voffB); PG8_STAGE(PG8_SA(0, 0), a2, voffA);
;             PG8_WAIT_V(8); PG8_WAIT_L(0); PG8_BAR; PG8_MMA(1, 0, At, B0); PG8_MMA(1, 1, At, B1); PG8_BAR; PG8_SCHED;
;             PG8_LDB(B0, 1, 0); PG8_LDB(B1, 1, 1); PG8_SCHED; PG8_LDA(At, 1, 0); PG8_STAGE(PG8_SA(0, 1), a2 + hstep, voffA);
;             PG8_WAIT_V(8); PG8_WAIT_L(0); PG8_BAR; PG8_MMA(0, 0, At, B0); PG8_MMA(0, 1, At, B1); PG8_BAR; PG8_SCHED;
;             PG8_LDA(At, 1, 1); PG8_STAGE(PG8_SB(1, 0), b3, voffB); PG8_STAGE(PG8_SB(1, 1), b3 + hstep, voffB); PG8_STAGE(PG8_SA(1, 0), a3, voffA);
;             PG8_WAIT_V(8); PG8_WAIT_L(0); PG8_BAR; PG8_MMA(1, 0, At, B0); PG8_MMA(1, 1, At, B1); PG8_BAR; PG8_SCHED;
	s_add_i32 s22, s45, s26
	v_lshl_add_u64 v[218:219], v[218:219], 0, s[2:3]
	s_mov_b32 m0, s22
	ds_read_b128 v[186:189], v158 offset:49152
	ds_read_b128 v[190:193], v158 offset:50176
	ds_read_b128 v[194:197], v158 offset:51200
	ds_read_b128 v[198:201], v158 offset:52224
	ds_read_b128 v[202:205], v158 offset:53248
	ds_read_b128 v[206:209], v158 offset:54272
	ds_read_b128 v[210:213], v158 offset:55296
	ds_read_b128 v[214:217], v158 offset:56320
	global_load_lds_dwordx4 v[218:219], off
	s_add_i32 m0, s22, 0x2000
	s_add_u32 s20, s20, 0x80080
	v_lshl_add_u64 v[218:219], v[220:221], 0, s[2:3]
	s_addc_u32 s21, s21, 0
	s_add_i32 s22, s46, s26
	global_load_lds_dwordx4 v[218:219], off
	s_mov_b32 m0, s22
	s_nop 0
	global_load_lds_dwordx4 v132, s[20:21]
	s_add_i32 m0, s22, 0x2000
	s_nop 0
	global_load_lds_dwordx4 v128, s[20:21]
	v_lshl_add_u64 v[218:219], v[222:223], 0, s[2:3]
	s_mov_b32 m0, s31
	s_nop 0
	global_load_lds_dwordx4 v[218:219], off
	v_lshl_add_u64 v[218:219], v[224:225], 0, s[2:3]
	s_mov_b32 m0, s33
	s_nop 0
	global_load_lds_dwordx4 v[218:219], off
	s_waitcnt vmcnt(8)
	s_waitcnt lgkmcnt(0)
	s_barrier
	s_setprio 1
	s_waitcnt lgkmcnt(0)
	v_mfma_f32_16x16x32_bf16 v[60:63], v[144:147], v[186:189], v[60:63]
	v_mfma_f32_16x16x32_bf16 v[56:59], v[160:163], v[186:189], v[56:59]
	v_mfma_f32_16x16x32_bf16 v[44:47], v[144:147], v[194:197], v[44:47]
	v_mfma_f32_16x16x32_bf16 v[40:43], v[160:163], v[194:197], v[40:43]
	v_mfma_f32_16x16x32_bf16 v[28:31], v[144:147], v[202:205], v[28:31]
	v_mfma_f32_16x16x32_bf16 v[24:27], v[160:163], v[202:205], v[24:27]
	v_mfma_f32_16x16x32_bf16 v[12:15], v[144:147], v[210:213], v[12:15]
	v_mfma_f32_16x16x32_bf16 v[8:11], v[160:163], v[210:213], v[8:11]
	v_mfma_f32_16x16x32_bf16 v[60:63], v[148:151], v[190:193], v[60:63]
	v_mfma_f32_16x16x32_bf16 v[56:59], v[164:167], v[190:193], v[56:59]
	v_mfma_f32_16x16x32_bf16 v[44:47], v[148:151], v[198:201], v[44:47]
	v_mfma_f32_16x16x32_bf16 v[40:43], v[164:167], v[198:201], v[40:43]
	v_mfma_f32_16x16x32_bf16 v[28:31], v[148:151], v[206:209], v[28:31]
	v_mfma_f32_16x16x32_bf16 v[24:27], v[164:167], v[206:209], v[24:27]
	v_mfma_f32_16x16x32_bf16 v[12:15], v[148:151], v[214:217], v[12:15]
	v_mfma_f32_16x16x32_bf16 v[8:11], v[164:167], v[214:217], v[8:11]
	s_setprio 0
	s_setprio 1
	v_mfma_f32_16x16x32_bf16 v[52:55], v[168:171], v[186:189], v[52:55]
	v_mfma_f32_16x16x32_bf16 v[48:51], v[178:181], v[186:189], v[48:51]
	v_mfma_f32_16x16x32_bf16 v[36:39], v[168:171], v[194:197], v[36:39]
	v_mfma_f32_16x16x32_bf16 v[32:35], v[178:181], v[194:197], v[32:35]
	v_mfma_f32_16x16x32_bf16 v[20:23], v[168:171], v[202:205], v[20:23]
	v_mfma_f32_16x16x32_bf16 v[16:19], v[178:181], v[202:205], v[16:19]
	v_mfma_f32_16x16x32_bf16 v[4:7], v[168:171], v[210:213], v[4:7]
	v_mfma_f32_16x16x32_bf16 v[0:3], v[178:181], v[210:213], v[0:3]
	v_mfma_f32_16x16x32_bf16 v[52:55], v[174:177], v[190:193], v[52:55]
	v_mfma_f32_16x16x32_bf16 v[48:51], v[182:185], v[190:193], v[48:51]
	v_mfma_f32_16x16x32_bf16 v[36:39], v[174:177], v[198:201], v[36:39]
	v_mfma_f32_16x16x32_bf16 v[32:35], v[182:185], v[198:201], v[32:35]
	v_mfma_f32_16x16x32_bf16 v[20:23], v[174:177], v[206:209], v[20:23]
	v_mfma_f32_16x16x32_bf16 v[16:19], v[182:185], v[206:209], v[16:19]
	v_mfma_f32_16x16x32_bf16 v[4:7], v[174:177], v[214:217], v[4:7]
	v_mfma_f32_16x16x32_bf16 v[0:3], v[182:185], v[214:217], v[0:3]
	s_setprio 0
	s_barrier
	s_add_i32 s44, s44, 2
	s_add_u32 s18, s18, 0x100
	s_addc_u32 s19, s19, 0
	s_add_u32 s42, s42, 0x100
	s_addc_u32 s43, s43, 0
	s_cmp_gt_u32 s44, 29
	s_cbranch_scc0 .LBB0_1712
	s_nop 0
	v_readfirstlane_b32 s9, v172
	s_nop 3
	s_lshr_b32 s9, s9, 6
	s_cmp_lt_u32 s9, 4
	s_cbranch_scc0 .Lprio_k6
	s_setprio 1

; #define PG8_STAGE(bufoff, gbase, voff) do { _Pragma("unroll") for (int _i = 0; _i < 2; ++_i) \
;         __builtin_amdgcn_global_load_lds((const unsigned*)((const char*)(gbase) + (voff)[_i]), (PG8_LAS unsigned*)(lds + (bufoff) + ldsw + _i * 8192), 16, 0, 0); } while (0)
; #define PG8_WAIT_V(n) asm volatile("s_waitcnt vmcnt(" #n ")" ::: "memory")
; #define PG8_BAR __builtin_amdgcn_s_barrier()
; template <class Epi, class Sched, bool ALIGN_EPI = false, bool SP2 = false>
; __device__ __forceinline__ void gemm_phase(PG8_LAS unsigned char* lds, const Gemm g, const Sched& S, const Epi& E) {
;     ...
;     if constexpr (SP2) {
;         PG8_STAGE(PG8_SB(0, 0), cB, voffB); PG8_STAGE(PG8_SB(0, 1), cB + hstep, voffB); PG8_STAGE(PG8_SA(0, 0), cA, voffA); PG8_STAGE(PG8_SA(0, 1), cA + hstep, voffA);
;         if (wr == 1) PG8_BAR;
;         PG8_WAIT_V(2); PG8_BAR;
;         PG8_STAGE(PG8_SB(1, 0), cB + kstep, voffB); PG8_STAGE(PG8_SA(1, 0), cA + kstep, voffA); PG8_STAGE(PG8_SB(1, 1), cB + hstep + kstep, voffB);
;         PG8_WAIT_V(6); PG8_BAR;
;     } else {
;         PG8_STAGE(PG8_SB(0, 0), cB, voffB); PG8_STAGE(PG8_SA(0, 0), cA, voffA); PG8_STAGE(PG8_SB(0, 1), cB + hstep, voffB); PG8_STAGE(PG8_SA(0, 1), cA + hstep, voffA);
;         if (wr == 1) PG8_BAR;
;         PG8_WAIT_V(4); PG8_BAR;
;         PG8_STAGE(PG8_SB(1, 0), cB + kstep, voffB); PG8_STAGE(PG8_SA(1, 0), cA + kstep, voffA); PG8_STAGE(PG8_SB(1, 1), cB + hstep + kstep, voffB);
;         PG8_WAIT_V(6); PG8_BAR;
;     }
;     for (;;) {
;         const bool has_next = S.next(ui + 1, nxt);
;         const char* nA = has_next ? (const char*)g.A + (size_t)nxt.pm * tstep : cA; const char* nB = has_next ? (const char*)g.Bt + (size_t)nxt.pn * tstep : cB;
.LBB0_1942:
	s_lshl_b32 s6, s6, 5
	s_and_b32 s14, s6, 0x60
	s_mov_b64 s[6:7], 0x80
	s_add_i32 m0, s31, 0x18000
	v_lshl_add_u64 v[6:7], v[6:7], 0, s[6:7]
	s_lshl_b32 s11, s0, 13
	s_lshl_b32 s12, s14, 7
	s_waitcnt vmcnt(2)
	s_barrier
	global_load_lds_dwordx4 v[6:7], off
	v_lshl_add_u64 v[4:5], v[4:5], 0, s[6:7]
	s_add_i32 m0, s31, 0x1a000
	s_add_i32 s37, s31, 0x8000
	s_add_i32 s38, s31, 0xa000
	global_load_lds_dwordx4 v[4:5], off
	v_lshl_add_u64 v[0:1], v[0:1], 0, s[6:7]
	s_mov_b32 m0, s37
	s_add_u32 s8, s22, 0x160080
	global_load_lds_dwordx4 v[0:1], off
	v_lshl_add_u64 v[0:1], v[2:3], 0, s[6:7]
	s_mov_b32 m0, s38
	s_addc_u32 s9, s23, 0
	global_load_lds_dwordx4 v[0:1], off
	s_add_i32 m0, s31, 0x1c000
	s_nop 0
	global_load_lds_dwordx4 v128, s[8:9]
	s_add_i32 m0, s31, 0x1e000
	s_sext_i32_i8 s44, s5
	global_load_lds_dwordx4 v130, s[8:9]
	v_bfe_u32 v1, v172, 4, 2
	v_and_b32_e32 v0, 15, v172
	v_lshlrev_b32_e32 v2, 4, v1
	v_lshl_or_b32 v146, s0, 6, v0
	v_lshl_or_b32 v0, v0, 6, v2
	v_lshlrev_b32_e32 v2, 2, v172
	v_and_b32_e32 v2, 32, v2
	v_bitop3_b32 v3, v0, s11, v2 bitop3:0xde
	v_bitop3_b32 v147, v0, s12, v2 bitop3:0xde
	v_lshl_or_b32 v148, v1, 2, s14
	v_lshrrev_b32_e32 v1, 1, v8
	v_mul_lo_u32 v0, v9, s1
	s_cmpk_lt_u32 s4, 0x100
	v_mad_u64_u32 v[0:1], s[4:5], v1, s10, v[0:1]
	v_or_b32_e32 v0, v0, v10
	s_mov_b64 s[12:13], 0x160080
	v_add_lshl_u32 v0, v0, v11, 1
	v_mov_b32_e32 v1, v129
	v_lshl_add_u64 v[132:133], v[0:1], 0, s[12:13]
	v_lshrrev_b32_e32 v1, 1, v12
	v_mul_lo_u32 v0, v13, s1
	v_mad_u64_u32 v[0:1], s[0:1], v1, s10, v[0:1]
	s_waitcnt vmcnt(6)
	v_or_b32_e32 v0, v0, v14
	s_cselect_b64 s[8:9], -1, 0
	v_add_lshl_u32 v0, v0, v15, 1
	v_mov_b32_e32 v1, v129
	s_add_i32 s39, 0, 0x10000
	s_add_i32 s40, 0, 0x14000
	v_lshl_add_u64 v[134:135], v[0:1], 0, s[12:13]
	v_mov_b64_e32 v[136:137], 0x100
	v_mov_b64_e32 v[138:139], 0xff
	v_add_u32_e32 v149, s39, v147
	v_add_u32_e32 v150, s40, v147
	v_add_u32_e32 v151, 0, v3
	s_mov_b64 s[10:11], 0x40000
	s_mov_b64 s[12:13], 0x48000
	s_mov_b64 s[14:15], 0x50000
	s_mov_b64 s[16:17], 0x58000
	s_barrier
	s_branch .LBB0_1945

; #define PG8_STAGE(bufoff, gbase, voff) do { _Pragma("unroll") for (int _i = 0; _i < 2; ++_i) \
;         __builtin_amdgcn_global_load_lds((const unsigned*)((const char*)(gbase) + (voff)[_i]), (PG8_LAS unsigned*)(lds + (bufoff) + ldsw + _i * 8192), 16, 0, 0); } while (0)
; #define PG8_LDA(dst, b, h) do { _Pragma("unroll") for (int m = 0; m < 4; ++m) _Pragma("unroll") for (int k = 0; k < 2; ++k) dst[m][k] = *(const PG8_LAS bf16x8*)(lds + PG8_SA(b, h) + aoff + m * 2048 + k * 1024); } while (0)
; #define PG8_LDB(dst, b, h) do { _Pragma("unroll") for (int n = 0; n < 2; ++n) _Pragma("unroll") for (int k = 0; k < 2; ++k) dst[n][k] = *(const PG8_LAS bf16x8*)(lds + PG8_SB(b, h) + boff + n * 2048 + k * 1024); } while (0)
; template <class Epi, class Sched, bool ALIGN_EPI = false, bool SP2 = false>
; __device__ __forceinline__ void gemm_phase(PG8_LAS unsigned char* lds, const Gemm g, const Sched& S, const Epi& E) {
;     ...
;         for (int t = 0; t < nt; t += 2) {
;             const bool last = (t == nt - 2);
;             const char* a1 = cA + (size_t)(t + 1) * kstep;
;             const char* a2 = last ? nA : cA + (size_t)(t + 2) * kstep; const char* b2 = last ? nB : cB + (size_t)(t + 2) * kstep;
;             const char* a3 = a2 + kstep; const char* b3 = b2 + kstep;
;             if (last && has_next) S.a_ready(nxt);
;             if constexpr (SP2) {
;             PG8_LDB(B0, 0, 0); PG8_LDB(B1, 0, 1); PG8_SCHED; PG8_LDA(At, 0, 0); PG8_STAGE(PG8_SA(1, 1), a1 + hstep, voffA);
;             PG8_WAIT_V(8); PG8_WAIT_L(0); PG8_BAR; PG8_MMA(0, 0, At, B0); PG8_MMA(0, 1, At, B1); PG8_BAR; PG8_SCHED;
;             PG8_LDA(At, 0, 1); PG8_STAGE(PG8_SB(0, 0), b2, voffB); PG8_STAGE(PG8_SB(0, 1), b2 + hstep, voffB); PG8_STAGE(PG8_SA(0, 0), a2, voffA);
;             PG8_WAIT_V(8); PG8_WAIT_L(0); PG8_BAR; PG8_MMA(1, 0, At, B0); PG8_MMA(1, 1, At, B1); PG8_BAR; PG8_SCHED;
;             PG8_LDB(B0, 1, 0); PG8_LDB(B1, 1, 1); PG8_SCHED; PG8_LDA(At, 1, 0); PG8_STAGE(PG8_SA(0, 1), a2 + hstep, voffA);
;             PG8_WAIT_V(8); PG8_WAIT_L(0); PG8_BAR; PG8_MMA(0, 0, At, B0); PG8_MMA(0, 1, At, B1); PG8_BAR; PG8_SCHED;
;             PG8_LDA(At, 1, 1); PG8_STAGE(PG8_SB(1, 0), b3, voffB); PG8_STAGE(PG8_SB(1, 1), b3 + hstep, voffB); PG8_STAGE(PG8_SA(1, 0), a3, voffA);
;             PG8_WAIT_V(8); PG8_WAIT_L(0); PG8_BAR; PG8_MMA(1, 0, At, B0); PG8_MMA(1, 1, At, B1); PG8_BAR; PG8_SCHED;
.LBB0_1956:
	ds_read_b128 v[140:143], v149
	ds_read_b128 v[152:155], v149 offset:1024
	ds_read_b128 v[156:159], v149 offset:2048
	ds_read_b128 v[160:163], v149 offset:3072
	ds_read_b128 v[164:167], v150
	ds_read_b128 v[168:171], v150 offset:1024
	ds_read_b128 v[172:175], v150 offset:2048
	ds_read_b128 v[176:179], v150 offset:3072
	s_add_u32 s22, s20, 0x100
	s_addc_u32 s23, s21, 0
	s_cmpk_eq_i32 s47, 0x54
	s_cselect_b32 s27, s5, s23
	s_cselect_b32 s26, s4, s22
	s_cselect_b32 s25, s19, s46
	s_cselect_b32 s24, s18, s45
	s_add_i32 m0, s31, 0xc000
	ds_read_b128 v[180:183], v151
	ds_read_b128 v[184:187], v151 offset:1024
	ds_read_b128 v[188:191], v151 offset:2048
	ds_read_b128 v[192:195], v151 offset:3072
	ds_read_b128 v[196:199], v151 offset:4096
	ds_read_b128 v[200:203], v151 offset:5120
	ds_read_b128 v[204:207], v151 offset:6144
	ds_read_b128 v[208:211], v151 offset:7168
	global_load_lds_dwordx4 v132, s[20:21]
	s_add_i32 m0, s31, 0xe000
	s_nop 0
	global_load_lds_dwordx4 v134, s[20:21]
	s_waitcnt vmcnt(8)
	s_waitcnt lgkmcnt(0)
	s_barrier
	s_setprio 1
	s_waitcnt lgkmcnt(0)
	v_mfma_f32_16x16x32_bf16 v[124:127], v[140:143], v[180:183], v[124:127]
	v_mfma_f32_16x16x32_bf16 v[120:123], v[156:159], v[180:183], v[120:123]
	v_mfma_f32_16x16x32_bf16 v[108:111], v[140:143], v[188:191], v[108:111]
	v_mfma_f32_16x16x32_bf16 v[104:107], v[156:159], v[188:191], v[104:107]
	v_mfma_f32_16x16x32_bf16 v[92:95], v[140:143], v[196:199], v[92:95]
	v_mfma_f32_16x16x32_bf16 v[88:91], v[156:159], v[196:199], v[88:91]
	v_mfma_f32_16x16x32_bf16 v[76:79], v[140:143], v[204:207], v[76:79]
	v_mfma_f32_16x16x32_bf16 v[72:75], v[156:159], v[204:207], v[72:75]
	v_mfma_f32_16x16x32_bf16 v[124:127], v[152:155], v[184:187], v[124:127]
	v_mfma_f32_16x16x32_bf16 v[120:123], v[160:163], v[184:187], v[120:123]
	v_mfma_f32_16x16x32_bf16 v[108:111], v[152:155], v[192:195], v[108:111]
	v_mfma_f32_16x16x32_bf16 v[104:107], v[160:163], v[192:195], v[104:107]
	v_mfma_f32_16x16x32_bf16 v[92:95], v[152:155], v[200:203], v[92:95]
	v_mfma_f32_16x16x32_bf16 v[88:91], v[160:163], v[200:203], v[88:91]
	v_mfma_f32_16x16x32_bf16 v[76:79], v[152:155], v[208:211], v[76:79]
	v_mfma_f32_16x16x32_bf16 v[72:75], v[160:163], v[208:211], v[72:75]
	s_setprio 0
	s_setprio 1
	v_mfma_f32_16x16x32_bf16 v[116:119], v[164:167], v[180:183], v[116:119]
	v_mfma_f32_16x16x32_bf16 v[112:115], v[172:175], v[180:183], v[112:115]
	v_mfma_f32_16x16x32_bf16 v[100:103], v[164:167], v[188:191], v[100:103]
	v_mfma_f32_16x16x32_bf16 v[96:99], v[172:175], v[188:191], v[96:99]
	v_mfma_f32_16x16x32_bf16 v[84:87], v[164:167], v[196:199], v[84:87]
	v_mfma_f32_16x16x32_bf16 v[80:83], v[172:175], v[196:199], v[80:83]
	v_mfma_f32_16x16x32_bf16 v[68:71], v[164:167], v[204:207], v[68:71]
	v_mfma_f32_16x16x32_bf16 v[64:67], v[172:175], v[204:207], v[64:67]
	v_mfma_f32_16x16x32_bf16 v[116:119], v[168:171], v[184:187], v[116:119]
	v_mfma_f32_16x16x32_bf16 v[112:115], v[176:179], v[184:187], v[112:115]
	v_mfma_f32_16x16x32_bf16 v[100:103], v[168:171], v[192:195], v[100:103]
	v_mfma_f32_16x16x32_bf16 v[96:99], v[176:179], v[192:195], v[96:99]
	v_mfma_f32_16x16x32_bf16 v[84:87], v[168:171], v[200:203], v[84:87]
	v_mfma_f32_16x16x32_bf16 v[80:83], v[176:179], v[200:203], v[80:83]
	v_mfma_f32_16x16x32_bf16 v[68:71], v[168:171], v[208:211], v[68:71]
	v_mfma_f32_16x16x32_bf16 v[64:67], v[176:179], v[208:211], v[64:67]
	s_setprio 0
	s_barrier
	s_add_i32 s20, s39, s30
	v_lshl_add_u64 v[144:145], s[24:25], 0, v[128:129]
	s_mov_b32 m0, s20
	ds_read_b128 v[180:183], v151 offset:16384
	ds_read_b128 v[184:187], v151 offset:17408
	ds_read_b128 v[188:191], v151 offset:18432
	ds_read_b128 v[192:195], v151 offset:19456
	ds_read_b128 v[196:199], v151 offset:20480
	ds_read_b128 v[200:203], v151 offset:21504
	ds_read_b128 v[204:207], v151 offset:22528
	ds_read_b128 v[208:211], v151 offset:23552
	global_load_lds_dwordx4 v[144:145], off
	s_add_i32 m0, s20, 0x2000
	s_add_u32 s20, s24, 0x160000
	v_lshl_add_u64 v[212:213], s[24:25], 0, v[130:131]
	s_addc_u32 s21, s25, 0
	s_add_i32 s48, s40, s30
	global_load_lds_dwordx4 v[212:213], off
	s_mov_b32 m0, s48
	v_lshl_add_u64 v[216:217], s[26:27], 0, v[130:131]
	global_load_lds_dwordx4 v128, s[20:21]
	s_add_i32 m0, s48, 0x2000
	s_nop 0
	global_load_lds_dwordx4 v130, s[20:21]
	v_lshl_add_u64 v[214:215], s[26:27], 0, v[128:129]
	s_mov_b32 m0, s31
	s_nop 0
	global_load_lds_dwordx4 v[214:215], off
	s_mov_b32 m0, s33
	s_nop 0
	global_load_lds_dwordx4 v[216:217], off
	s_waitcnt vmcnt(8)
	s_waitcnt lgkmcnt(0)
	s_barrier
; #define PG8_STAGE(bufoff, gbase, voff) do { _Pragma("unroll") for (int _i = 0; _i < 2; ++_i) \
;         __builtin_amdgcn_global_load_lds((const unsigned*)((const char*)(gbase) + (voff)[_i]), (PG8_LAS unsigned*)(lds + (bufoff) + ldsw + _i * 8192), 16, 0, 0); } while (0)
; #define PG8_LDA(dst, b, h) do { _Pragma("unroll") for (int m = 0; m < 4; ++m) _Pragma("unroll") for (int k = 0; k < 2; ++k) dst[m][k] = *(const PG8_LAS bf16x8*)(lds + PG8_SA(b, h) + aoff + m * 2048 + k * 1024); } while (0)
; #define PG8_LDB(dst, b, h) do { _Pragma("unroll") for (int n = 0; n < 2; ++n) _Pragma("unroll") for (int k = 0; k < 2; ++k) dst[n][k] = *(const PG8_LAS bf16x8*)(lds + PG8_SB(b, h) + boff + n * 2048 + k * 1024); } while (0)
; template <class Epi, class Sched, bool ALIGN_EPI = false, bool SP2 = false>
; __device__ __forceinline__ void gemm_phase(PG8_LAS unsigned char* lds, const Gemm g, const Sched& S, const Epi& E) {
;     ...
;         for (int t = 0; t < nt; t += 2) {
;             const bool last = (t == nt - 2);
;             const char* a1 = cA + (size_t)(t + 1) * kstep;
;             const char* a2 = last ? nA : cA + (size_t)(t + 2) * kstep; const char* b2 = last ? nB : cB + (size_t)(t + 2) * kstep;
;             const char* a3 = a2 + kstep; const char* b3 = b2 + kstep;
;             if (last && has_next) S.a_ready(nxt);
;             if constexpr (SP2) {
;             PG8_LDB(B0, 0, 0); PG8_LDB(B1, 0, 1); PG8_SCHED; PG8_LDA(At, 0, 0); PG8_STAGE(PG8_SA(1, 1), a1 + hstep, voffA);
;             PG8_WAIT_V(8); PG8_WAIT_L(0); PG8_BAR; PG8_MMA(0, 0, At, B0); PG8_MMA(0, 1, At, B1); PG8_BAR; PG8_SCHED;
;             PG8_LDA(At, 0, 1); PG8_STAGE(PG8_SB(0, 0), b2, voffB); PG8_STAGE(PG8_SB(0, 1), b2 + hstep, voffB); PG8_STAGE(PG8_SA(0, 0), a2, voffA);
;             PG8_WAIT_V(8); PG8_WAIT_L(0); PG8_BAR; PG8_MMA(1, 0, At, B0); PG8_MMA(1, 1, At, B1); PG8_BAR; PG8_SCHED;
;             PG8_LDB(B0, 1, 0); PG8_LDB(B1, 1, 1); PG8_SCHED; PG8_LDA(At, 1, 0); PG8_STAGE(PG8_SA(0, 1), a2 + hstep, voffA);
;             PG8_WAIT_V(8); PG8_WAIT_L(0); PG8_BAR; PG8_MMA(0, 0, At, B0); PG8_MMA(0, 1, At, B1); PG8_BAR; PG8_SCHED;
;             PG8_LDA(At, 1, 1); PG8_STAGE(PG8_SB(1, 0), b3, voffB); PG8_STAGE(PG8_SB(1, 1), b3 + hstep, voffB); PG8_STAGE(PG8_SA(1, 0), a3, voffA);
;             PG8_WAIT_V(8); PG8_WAIT_L(0); PG8_BAR; PG8_MMA(1, 0, At, B0); PG8_MMA(1, 1, At, B1); PG8_BAR; PG8_SCHED;
	s_setprio 1
	s_waitcnt lgkmcnt(0)
	v_mfma_f32_16x16x32_bf16 v[60:63], v[140:143], v[180:183], v[60:63]
	v_mfma_f32_16x16x32_bf16 v[56:59], v[156:159], v[180:183], v[56:59]
	v_mfma_f32_16x16x32_bf16 v[44:47], v[140:143], v[188:191], v[44:47]
	v_mfma_f32_16x16x32_bf16 v[40:43], v[156:159], v[188:191], v[40:43]
	v_mfma_f32_16x16x32_bf16 v[28:31], v[140:143], v[196:199], v[28:31]
	v_mfma_f32_16x16x32_bf16 v[24:27], v[156:159], v[196:199], v[24:27]
	v_mfma_f32_16x16x32_bf16 v[12:15], v[140:143], v[204:207], v[12:15]
	v_mfma_f32_16x16x32_bf16 v[8:11], v[156:159], v[204:207], v[8:11]
	v_mfma_f32_16x16x32_bf16 v[60:63], v[152:155], v[184:187], v[60:63]
	v_mfma_f32_16x16x32_bf16 v[56:59], v[160:163], v[184:187], v[56:59]
	v_mfma_f32_16x16x32_bf16 v[44:47], v[152:155], v[192:195], v[44:47]
	v_mfma_f32_16x16x32_bf16 v[40:43], v[160:163], v[192:195], v[40:43]
	v_mfma_f32_16x16x32_bf16 v[28:31], v[152:155], v[200:203], v[28:31]
	v_mfma_f32_16x16x32_bf16 v[24:27], v[160:163], v[200:203], v[24:27]
	v_mfma_f32_16x16x32_bf16 v[12:15], v[152:155], v[208:211], v[12:15]
	v_mfma_f32_16x16x32_bf16 v[8:11], v[160:163], v[208:211], v[8:11]
	s_setprio 0
	s_setprio 1
	v_mfma_f32_16x16x32_bf16 v[52:55], v[164:167], v[180:183], v[52:55]
	v_mfma_f32_16x16x32_bf16 v[48:51], v[172:175], v[180:183], v[48:51]
	v_mfma_f32_16x16x32_bf16 v[36:39], v[164:167], v[188:191], v[36:39]
	v_mfma_f32_16x16x32_bf16 v[32:35], v[172:175], v[188:191], v[32:35]
	v_mfma_f32_16x16x32_bf16 v[20:23], v[164:167], v[196:199], v[20:23]
	v_mfma_f32_16x16x32_bf16 v[16:19], v[172:175], v[196:199], v[16:19]
	v_mfma_f32_16x16x32_bf16 v[4:7], v[164:167], v[204:207], v[4:7]
	v_mfma_f32_16x16x32_bf16 v[0:3], v[172:175], v[204:207], v[0:3]
	v_mfma_f32_16x16x32_bf16 v[52:55], v[168:171], v[184:187], v[52:55]
	v_mfma_f32_16x16x32_bf16 v[48:51], v[176:179], v[184:187], v[48:51]
	v_mfma_f32_16x16x32_bf16 v[36:39], v[168:171], v[192:195], v[36:39]
	v_mfma_f32_16x16x32_bf16 v[32:35], v[176:179], v[192:195], v[32:35]
	v_mfma_f32_16x16x32_bf16 v[20:23], v[168:171], v[200:203], v[20:23]
	v_mfma_f32_16x16x32_bf16 v[16:19], v[176:179], v[200:203], v[16:19]
	v_mfma_f32_16x16x32_bf16 v[4:7], v[168:171], v[208:211], v[4:7]
	v_mfma_f32_16x16x32_bf16 v[0:3], v[176:179], v[208:211], v[0:3]
	s_setprio 0
	s_barrier
	s_add_i32 s48, 0, 0x18000
	s_add_i32 s49, 0, 0x1c000
	v_add_u32_e32 v160, s48, v147
	v_add_u32_e32 v176, s49, v147
	ds_read_b128 v[140:143], v160
	ds_read_b128 v[152:155], v160 offset:1024
	ds_read_b128 v[156:159], v160 offset:2048
	ds_read_b128 v[160:163], v160 offset:3072
	ds_read_b128 v[164:167], v176
	ds_read_b128 v[168:171], v176 offset:1024
	ds_read_b128 v[172:175], v176 offset:2048
	ds_read_b128 v[176:179], v176 offset:3072
	s_add_u32 s20, s26, 0x160000
	s_addc_u32 s21, s27, 0
	s_mov_b32 m0, s34
	ds_read_b128 v[180:183], v151 offset:32768
	ds_read_b128 v[184:187], v151 offset:33792
	ds_read_b128 v[188:191], v151 offset:34816
	ds_read_b128 v[192:195], v151 offset:35840
	ds_read_b128 v[196:199], v151 offset:36864
	ds_read_b128 v[200:203], v151 offset:37888
	ds_read_b128 v[204:207], v151 offset:38912
	ds_read_b128 v[208:211], v151 offset:39936
	global_load_lds_dwordx4 v128, s[20:21]
	s_mov_b32 m0, s35
	s_nop 0
	global_load_lds_dwordx4 v130, s[20:21]
	s_waitcnt vmcnt(8)
	s_waitcnt lgkmcnt(0)
	s_barrier
	s_setprio 1
	s_waitcnt lgkmcnt(0)
	v_mfma_f32_16x16x32_bf16 v[124:127], v[140:143], v[180:183], v[124:127]
	v_mfma_f32_16x16x32_bf16 v[120:123], v[156:159], v[180:183], v[120:123]
	v_mfma_f32_16x16x32_bf16 v[108:111], v[140:143], v[188:191], v[108:111]
	v_mfma_f32_16x16x32_bf16 v[104:107], v[156:159], v[188:191], v[104:107]
	v_mfma_f32_16x16x32_bf16 v[92:95], v[140:143], v[196:199], v[92:95]
	v_mfma_f32_16x16x32_bf16 v[88:91], v[156:159], v[196:199], v[88:91]
	v_mfma_f32_16x16x32_bf16 v[76:79], v[140:143], v[204:207], v[76:79]
	v_mfma_f32_16x16x32_bf16 v[72:75], v[156:159], v[204:207], v[72:75]
	v_mfma_f32_16x16x32_bf16 v[124:127], v[152:155], v[184:187], v[124:127]
	v_mfma_f32_16x16x32_bf16 v[120:123], v[160:163], v[184:187], v[120:123]
	v_mfma_f32_16x16x32_bf16 v[108:111], v[152:155], v[192:195], v[108:111]
	v_mfma_f32_16x16x32_bf16 v[104:107], v[160:163], v[192:195], v[104:107]
	v_mfma_f32_16x16x32_bf16 v[92:95], v[152:155], v[200:203], v[92:95]
	v_mfma_f32_16x16x32_bf16 v[88:91], v[160:163], v[200:203], v[88:91]
	v_mfma_f32_16x16x32_bf16 v[76:79], v[152:155], v[208:211], v[76:79]
	v_mfma_f32_16x16x32_bf16 v[72:75], v[160:163], v[208:211], v[72:75]
	s_setprio 0
	s_setprio 1
	v_mfma_f32_16x16x32_bf16 v[116:119], v[164:167], v[180:183], v[116:119]
	v_mfma_f32_16x16x32_bf16 v[112:115], v[172:175], v[180:183], v[112:115]
	v_mfma_f32_16x16x32_bf16 v[100:103], v[164:167], v[188:191], v[100:103]
	v_mfma_f32_16x16x32_bf16 v[96:99], v[172:175], v[188:191], v[96:99]
	v_mfma_f32_16x16x32_bf16 v[84:87], v[164:167], v[196:199], v[84:87]
	v_mfma_f32_16x16x32_bf16 v[80:83], v[172:175], v[196:199], v[80:83]
	v_mfma_f32_16x16x32_bf16 v[68:71], v[164:167], v[204:207], v[68:71]
	v_mfma_f32_16x16x32_bf16 v[64:67], v[172:175], v[204:207], v[64:67]
	v_mfma_f32_16x16x32_bf16 v[116:119], v[168:171], v[184:187], v[116:119]
	v_mfma_f32_16x16x32_bf16 v[112:115], v[176:179], v[184:187], v[112:115]
	v_mfma_f32_16x16x32_bf16 v[100:103], v[168:171], v[192:195], v[100:103]
	v_mfma_f32_16x16x32_bf16 v[96:99], v[176:179], v[192:195], v[96:99]
	v_mfma_f32_16x16x32_bf16 v[84:87], v[168:171], v[200:203], v[84:87]
	v_mfma_f32_16x16x32_bf16 v[80:83], v[176:179], v[200:203], v[80:83]
	v_mfma_f32_16x16x32_bf16 v[68:71], v[168:171], v[208:211], v[68:71]
	v_mfma_f32_16x16x32_bf16 v[64:67], v[176:179], v[208:211], v[64:67]
	s_setprio 0
	s_barrier
; #define PG8_STAGE(bufoff, gbase, voff) do { _Pragma("unroll") for (int _i = 0; _i < 2; ++_i) \
;         __builtin_amdgcn_global_load_lds((const unsigned*)((const char*)(gbase) + (voff)[_i]), (PG8_LAS unsigned*)(lds + (bufoff) + ldsw + _i * 8192), 16, 0, 0); } while (0)
; #define PG8_LDA(dst, b, h) do { _Pragma("unroll") for (int m = 0; m < 4; ++m) _Pragma("unroll") for (int k = 0; k < 2; ++k) dst[m][k] = *(const PG8_LAS bf16x8*)(lds + PG8_SA(b, h) + aoff + m * 2048 + k * 1024); } while (0)
; #define PG8_LDB(dst, b, h) do { _Pragma("unroll") for (int n = 0; n < 2; ++n) _Pragma("unroll") for (int k = 0; k < 2; ++k) dst[n][k] = *(const PG8_LAS bf16x8*)(lds + PG8_SB(b, h) + boff + n * 2048 + k * 1024); } while (0)
; template <class Epi, class Sched, bool ALIGN_EPI = false, bool SP2 = false>
; __device__ __forceinline__ void gemm_phase(PG8_LAS unsigned char* lds, const Gemm g, const Sched& S, const Epi& E) {
;     ...
;         for (int t = 0; t < nt; t += 2) {
;             const bool last = (t == nt - 2);
;             const char* a1 = cA + (size_t)(t + 1) * kstep;
;             const char* a2 = last ? nA : cA + (size_t)(t + 2) * kstep; const char* b2 = last ? nB : cB + (size_t)(t + 2) * kstep;
;             const char* a3 = a2 + kstep; const char* b3 = b2 + kstep;
;             if (last && has_next) S.a_ready(nxt);
;             if constexpr (SP2) {
;             PG8_LDB(B0, 0, 0); PG8_LDB(B1, 0, 1); PG8_SCHED; PG8_LDA(At, 0, 0); PG8_STAGE(PG8_SA(1, 1), a1 + hstep, voffA);
;             PG8_WAIT_V(8); PG8_WAIT_L(0); PG8_BAR; PG8_MMA(0, 0, At, B0); PG8_MMA(0, 1, At, B1); PG8_BAR; PG8_SCHED;
;             PG8_LDA(At, 0, 1); PG8_STAGE(PG8_SB(0, 0), b2, voffB); PG8_STAGE(PG8_SB(0, 1), b2 + hstep, voffB); PG8_STAGE(PG8_SA(0, 0), a2, voffA);
;             PG8_WAIT_V(8); PG8_WAIT_L(0); PG8_BAR; PG8_MMA(1, 0, At, B0); PG8_MMA(1, 1, At, B1); PG8_BAR; PG8_SCHED;
;             PG8_LDB(B0, 1, 0); PG8_LDB(B1, 1, 1); PG8_SCHED; PG8_LDA(At, 1, 0); PG8_STAGE(PG8_SA(0, 1), a2 + hstep, voffA);
;             PG8_WAIT_V(8); PG8_WAIT_L(0); PG8_BAR; PG8_MMA(0, 0, At, B0); PG8_MMA(0, 1, At, B1); PG8_BAR; PG8_SCHED;
;             PG8_LDA(At, 1, 1); PG8_STAGE(PG8_SB(1, 0), b3, voffB); PG8_STAGE(PG8_SB(1, 1), b3 + hstep, voffB); PG8_STAGE(PG8_SA(1, 0), a3, voffA);
;             PG8_WAIT_V(8); PG8_WAIT_L(0); PG8_BAR; PG8_MMA(1, 0, At, B0); PG8_MMA(1, 1, At, B1); PG8_BAR; PG8_SCHED;
	s_add_i32 s20, s48, s30
	v_lshl_add_u64 v[144:145], v[144:145], 0, s[6:7]
	s_mov_b32 m0, s20
	ds_read_b128 v[180:183], v151 offset:49152
	ds_read_b128 v[184:187], v151 offset:50176
	ds_read_b128 v[188:191], v151 offset:51200
	ds_read_b128 v[192:195], v151 offset:52224
	ds_read_b128 v[196:199], v151 offset:53248
	ds_read_b128 v[200:203], v151 offset:54272
	ds_read_b128 v[204:207], v151 offset:55296
	ds_read_b128 v[208:211], v151 offset:56320
	global_load_lds_dwordx4 v[144:145], off
	s_add_i32 m0, s20, 0x2000
	s_add_u32 s20, s24, 0x160080
	v_lshl_add_u64 v[144:145], v[212:213], 0, s[6:7]
	s_addc_u32 s21, s25, 0
	s_add_i32 s24, s49, s30
	global_load_lds_dwordx4 v[144:145], off
	s_mov_b32 m0, s24
	s_nop 0
	global_load_lds_dwordx4 v128, s[20:21]
	s_add_i32 m0, s24, 0x2000
	s_nop 0
	global_load_lds_dwordx4 v130, s[20:21]
	v_lshl_add_u64 v[144:145], v[214:215], 0, s[6:7]
	s_mov_b32 m0, s37
	s_nop 0
	global_load_lds_dwordx4 v[144:145], off
	v_lshl_add_u64 v[144:145], v[216:217], 0, s[6:7]
	s_mov_b32 m0, s38
	s_nop 0
	global_load_lds_dwordx4 v[144:145], off
	s_waitcnt vmcnt(8)
	s_waitcnt lgkmcnt(0)
	s_barrier
	s_setprio 1
	s_waitcnt lgkmcnt(0)
	v_mfma_f32_16x16x32_bf16 v[60:63], v[140:143], v[180:183], v[60:63]
	v_mfma_f32_16x16x32_bf16 v[56:59], v[156:159], v[180:183], v[56:59]
	v_mfma_f32_16x16x32_bf16 v[44:47], v[140:143], v[188:191], v[44:47]
	v_mfma_f32_16x16x32_bf16 v[40:43], v[156:159], v[188:191], v[40:43]
	v_mfma_f32_16x16x32_bf16 v[28:31], v[140:143], v[196:199], v[28:31]
	v_mfma_f32_16x16x32_bf16 v[24:27], v[156:159], v[196:199], v[24:27]
	v_mfma_f32_16x16x32_bf16 v[12:15], v[140:143], v[204:207], v[12:15]
	v_mfma_f32_16x16x32_bf16 v[8:11], v[156:159], v[204:207], v[8:11]
	v_mfma_f32_16x16x32_bf16 v[60:63], v[152:155], v[184:187], v[60:63]
	v_mfma_f32_16x16x32_bf16 v[56:59], v[160:163], v[184:187], v[56:59]
	v_mfma_f32_16x16x32_bf16 v[44:47], v[152:155], v[192:195], v[44:47]
	v_mfma_f32_16x16x32_bf16 v[40:43], v[160:163], v[192:195], v[40:43]
	v_mfma_f32_16x16x32_bf16 v[28:31], v[152:155], v[200:203], v[28:31]
	v_mfma_f32_16x16x32_bf16 v[24:27], v[160:163], v[200:203], v[24:27]
	v_mfma_f32_16x16x32_bf16 v[12:15], v[152:155], v[208:211], v[12:15]
	v_mfma_f32_16x16x32_bf16 v[8:11], v[160:163], v[208:211], v[8:11]
	s_setprio 0
	s_setprio 1
	v_mfma_f32_16x16x32_bf16 v[52:55], v[164:167], v[180:183], v[52:55]
	v_mfma_f32_16x16x32_bf16 v[48:51], v[172:175], v[180:183], v[48:51]
	v_mfma_f32_16x16x32_bf16 v[36:39], v[164:167], v[188:191], v[36:39]
	v_mfma_f32_16x16x32_bf16 v[32:35], v[172:175], v[188:191], v[32:35]
	v_mfma_f32_16x16x32_bf16 v[20:23], v[164:167], v[196:199], v[20:23]
	v_mfma_f32_16x16x32_bf16 v[16:19], v[172:175], v[196:199], v[16:19]
	v_mfma_f32_16x16x32_bf16 v[4:7], v[164:167], v[204:207], v[4:7]
	v_mfma_f32_16x16x32_bf16 v[0:3], v[172:175], v[204:207], v[0:3]
	v_mfma_f32_16x16x32_bf16 v[52:55], v[168:171], v[184:187], v[52:55]
	v_mfma_f32_16x16x32_bf16 v[48:51], v[176:179], v[184:187], v[48:51]
	v_mfma_f32_16x16x32_bf16 v[36:39], v[168:171], v[192:195], v[36:39]
	v_mfma_f32_16x16x32_bf16 v[32:35], v[176:179], v[192:195], v[32:35]
	v_mfma_f32_16x16x32_bf16 v[20:23], v[168:171], v[200:203], v[20:23]
	v_mfma_f32_16x16x32_bf16 v[16:19], v[176:179], v[200:203], v[16:19]
	v_mfma_f32_16x16x32_bf16 v[4:7], v[168:171], v[208:211], v[4:7]
	v_mfma_f32_16x16x32_bf16 v[0:3], v[176:179], v[208:211], v[0:3]
	s_setprio 0
	s_barrier
	s_add_i32 s47, s47, 2
	s_add_u32 s45, s45, 0x100
	s_addc_u32 s46, s46, 0
	s_cmpk_gt_u32 s47, 0x55
	s_mov_b64 s[20:21], s[22:23]
	s_cbranch_scc0 .LBB0_1956
	s_nop 0
	v_readfirstlane_b32 s20, v172
	s_nop 3
	s_lshr_b32 s20, s20, 6
	s_cmp_lt_u32 s20, 4
	s_cbranch_scc0 .Lprio_k7
	s_setprio 1
